# mixer D GLU Z loads issued early (under LayerNorm code) instead of one round trip per iteration
# speedup vs baseline: 1.0599x; 1.0007x over previous
; __device__ __forceinline__ unsigned cvt_pk_bf16(float lo, float hi) { unsigned r; asm volatile("v_cvt_pk_bf16_f32 %0, %1, %2" : "=v"(r) : "v"(lo), "v"(hi)); return r; }
; __device__ __forceinline__ void mixer_bd(const bf16_t* __restrict__ Z, bf16_t* __restrict__ Y, const float* __restrict__ lng, const float* __restrict__ lnb, const float* __restrict__ wsp, const float* __restrict__ bsp, ...
;     ...
;     for (int un = bid; un < 256; un += G) {
;         const int chunk = un >> 1, hf = un & 1; const size_t row0 = (size_t)chunk * 128;
;         const int t = wave * 16 + fr; const size_t row = row0 + t;
;         bf16x8 wf[2][4]; u32x2 uu[2][4]; float bias[2];
; #pragma unroll
;         for (int hh = 0; hh < 2; ++hh) {
;             const int h = hf * 2 + hh; const float* W = wsp + (size_t)h * 128 * 128 + (size_t)t * 128;
;             f32x4 wa[4], wb[4];
; #pragma unroll
;             for (int ks = 0; ks < 4; ++ks) { wa[ks] = *(const f32x4*)(W + ks * 32 + fq * 8); wb[ks] = *(const f32x4*)(W + ks * 32 + fq * 8 + 4); }
; #pragma unroll
;             for (int nt = 0; nt < 4; ++nt) uu[hh][nt] = *(const u32x2*)(Z + row * NZ + 3 * 256 + h * 64 + nt * 16 + fq * 4);
;             bias[hh] = bsp[h * 128 + t];
; #pragma unroll
;             for (int ks = 0; ks < 4; ++ks) {
;                 const int s0 = ks * 32 + fq * 8;
; #pragma unroll
;                 for (int j = 0; j < 4; ++j) { if (s0 + j > t) wa[ks][j] = 0.f; if (s0 + 4 + j > t) wb[ks][j] = 0.f; }
;                 u32x4 wp; wp.x = cvt_pk_bf16(wa[ks][0], wa[ks][1]); wp.y = cvt_pk_bf16(wa[ks][2], wa[ks][3]); wp.z = cvt_pk_bf16(wb[ks][0], wb[ks][1]); wp.w = cvt_pk_bf16(wb[ks][2], wb[ks][3]);
;                 wf[hh][ks] = __builtin_bit_cast(bf16x8, wp);
;             }
;         }
.LBB0_248:
	s_and_b32 s70, s86, 1
	s_lshl_b32 s82, s70, 17
	v_lshl_add_u64 v[26:27], v[52:53], 0, s[82:83]
	global_load_dwordx4 v[10:13], v[26:27], off
	global_load_dwordx4 v[14:17], v[26:27], off offset:16
	global_load_dwordx4 v[18:21], v[26:27], off offset:128
	global_load_dwordx4 v[32:35], v[26:27], off offset:144
	global_load_dwordx4 v[36:39], v[26:27], off offset:256
	global_load_dwordx4 v[40:43], v[26:27], off offset:272
	global_load_dwordx4 v[22:25], v[26:27], off offset:384
	s_nop 0
	global_load_dwordx4 v[26:29], v[26:27], off offset:400
	s_ashr_i32 s72, s86, 1
	s_ashr_i32 s73, s72, 31
	s_lshl_b64 vcc, s[72:73], 7
	s_waitcnt vmcnt(43)
	v_lshl_add_u64 v[76:77], vcc, 0, v[50:51]
	s_waitcnt vmcnt(42)
	v_mad_u64_u32 v[30:31], vcc, v76, s33, v[58:59]
	v_mad_i32_i24 v31, v77, s33, v31
	s_lshl_b32 s82, s70, 8
	v_lshl_add_u64 v[44:45], v[30:31], 0, s[82:83]
	global_load_dwordx2 v[74:75], v[44:45], off offset:1536
	global_load_dwordx2 v[72:73], v[44:45], off offset:1568
	global_load_dwordx2 v[70:71], v[44:45], off offset:1600
	global_load_dwordx2 v[68:69], v[44:45], off offset:1632
	v_add_u32_e32 v44, s82, v50
	v_ashrrev_i32_e32 v45, 31, v44
	v_lshl_add_u64 v[44:45], v[44:45], 2, s[74:75]
	global_load_dword v138, v[44:45], off
	v_mov_b32_e32 v44, s83
	s_lshl_b32 s71, s70, 1
	s_or_b32 s71, s71, 1
	s_lshl_b32 s82, s71, 16
	s_lshl_b32 s77, s70, 7
	v_readlane_b32 vcc_lo, v255, 41
	v_readlane_b32 vcc_hi, v255, 42
	s_waitcnt vmcnt(12)
	v_cndmask_b32_e64 v45, v10, 0, s[4:5]
	s_waitcnt vmcnt(11)
	v_cndmask_b32_e64 v14, v14, v44, s[6:7]
	v_cndmask_b32_e64 v17, v17, v17, s[6:7]
	v_cndmask_b32_e64 v16, v16, v16, s[6:7]
	v_cndmask_b32_e64 v15, v15, v15, s[6:7]
	v_cndmask_b32_e64 v10, v45, v10, s[8:9]
	v_cndmask_b32_e64 v11, 0, v11, s[8:9]
	v_cndmask_b32_e64 v12, v12, 0, s[12:13]
	v_cndmask_b32_e64 v15, v15, 0, s[10:11]
	v_cndmask_b32_e64 v16, v16, 0, s[14:15]
	v_cndmask_b32_e64 v13, v13, 0, s[16:17]
	v_cndmask_b32_e64 v17, v17, 0, s[18:19]
	v_cvt_pk_bf16_f32 v10, v10, v11
	v_cvt_pk_bf16_f32 v11, v12, v13
	v_cvt_pk_bf16_f32 v12, v14, v15
	v_mov_b32_e32 v14, s83
	v_cvt_pk_bf16_f32 v13, v16, v17
	s_waitcnt vmcnt(10)
	v_cndmask_b32_e64 v15, v18, 0, s[20:21]
	s_waitcnt vmcnt(9)
	v_cndmask_b32_e64 v16, v32, v14, s[22:23]
	v_cndmask_b32_e64 v14, v35, v35, s[22:23]
	v_cndmask_b32_e64 v17, v34, v34, s[22:23]
	v_cndmask_b32_e64 v18, v33, v33, s[22:23]
	v_cndmask_b32_e64 v18, v18, 0, s[26:27]
	v_cndmask_b32_e64 v17, v17, 0, s[30:31]
	v_cndmask_b32_e64 v32, v14, 0, s[36:37]
	v_cndmask_b32_e64 v19, v19, 0, s[24:25]
	v_cndmask_b32_e64 v20, v20, 0, s[28:29]
	v_cndmask_b32_e64 v21, v21, 0, s[34:35]
	v_cvt_pk_bf16_f32 v14, v15, v19
	v_cvt_pk_bf16_f32 v15, v20, v21
	v_cvt_pk_bf16_f32 v16, v16, v18
	v_cvt_pk_bf16_f32 v17, v17, v32
	v_mov_b32_e32 v18, s83
	s_waitcnt vmcnt(7)
	v_cndmask_b32_e64 v32, v41, v41, s[40:41]
	v_cndmask_b32_e64 v19, v36, 0, s[38:39]
	v_cndmask_b32_e64 v20, v40, v18, s[40:41]
	v_cndmask_b32_e64 v18, v43, v43, s[40:41]
	v_cndmask_b32_e64 v32, v32, 0, s[44:45]
	v_cndmask_b32_e64 v21, v42, v42, s[40:41]
	v_cndmask_b32_e64 v33, v37, 0, s[42:43]
	v_cndmask_b32_e64 v34, v38, 0, s[46:47]
	v_cndmask_b32_e64 v35, v39, 0, s[50:51]
	v_cndmask_b32_e64 v36, v18, 0, s[52:53]
	v_cvt_pk_bf16_f32 v18, v19, v33
	v_cvt_pk_bf16_f32 v19, v34, v35
	v_cvt_pk_bf16_f32 v20, v20, v32
	s_waitcnt vmcnt(6)
	v_cndmask_b32_e64 v32, v22, 0, s[54:55]
	v_mov_b32_e32 v22, s83
	v_cndmask_b32_e64 v21, v21, 0, s[48:49]
	s_waitcnt vmcnt(5)
	v_cndmask_b32_e64 v22, v26, v22, s[56:57]
	v_cndmask_b32_e64 v26, v29, v29, s[56:57]
	v_cndmask_b32_e64 v28, v28, v28, s[56:57]
	v_cndmask_b32_e64 v27, v27, v27, s[56:57]
	v_cvt_pk_bf16_f32 v21, v21, v36
	v_cndmask_b32_e64 v23, v23, 0, s[58:59]
	v_cndmask_b32_e64 v29, v27, 0, s[60:61]
	v_cndmask_b32_e64 v24, v24, 0, s[62:63]
	v_cndmask_b32_e64 v33, v28, 0, s[64:65]
	v_cndmask_b32_e64 v25, v25, 0, s[66:67]
	v_cndmask_b32_e64 v34, v26, 0, s[68:69]
	v_lshl_add_u64 v[36:37], v[52:53], 0, s[82:83]
	v_cvt_pk_bf16_f32 v26, v32, v23
	v_cvt_pk_bf16_f32 v27, v24, v25
	v_cvt_pk_bf16_f32 v28, v22, v29
	v_cvt_pk_bf16_f32 v29, v33, v34
	global_load_dwordx4 v[22:25], v[36:37], off
	global_load_dwordx4 v[32:35], v[36:37], off offset:16
	global_load_dwordx4 v[46:49], v[36:37], off offset:128
	global_load_dwordx4 v[140:143], v[36:37], off offset:144
	global_load_dwordx4 v[144:147], v[36:37], off offset:256
	global_load_dwordx4 v[148:151], v[36:37], off offset:272
	global_load_dwordx4 v[38:41], v[36:37], off offset:384
	global_load_dwordx4 v[42:45], v[36:37], off offset:400
	s_lshl_b32 s82, s71, 7
	v_lshl_add_u64 v[30:31], v[30:31], 0, s[82:83]
	global_load_dwordx2 v[84:85], v[30:31], off offset:1536
	global_load_dwordx2 v[82:83], v[30:31], off offset:1568
	global_load_dwordx2 v[80:81], v[30:31], off offset:1600
	global_load_dwordx2 v[78:79], v[30:31], off offset:1632
	v_add_u32_e32 v30, s82, v50
	v_ashrrev_i32_e32 v31, 31, v30
	v_lshl_add_u64 v[30:31], v[30:31], 2, s[74:75]
	global_load_dword v139, v[30:31], off
	v_mov_b32_e32 v30, s83
	s_cmp_eq_u32 s70, 0
	s_cselect_b64 s[70:71], -1, 0
	s_waitcnt vmcnt(12)
	v_cndmask_b32_e64 v31, v22, 0, s[4:5]
	s_waitcnt vmcnt(11)
	v_cndmask_b32_e64 v30, v32, v30, s[6:7]
	v_cndmask_b32_e64 v32, v35, v35, s[6:7]
	v_cndmask_b32_e64 v34, v34, v34, s[6:7]
	v_cndmask_b32_e64 v33, v33, v33, s[6:7]
	v_cndmask_b32_e64 v22, v31, v22, s[8:9]
	v_cndmask_b32_e64 v23, 0, v23, s[8:9]
	v_cndmask_b32_e64 v24, v24, 0, s[12:13]
	v_cndmask_b32_e64 v31, v33, 0, s[10:11]
	v_cndmask_b32_e64 v33, v34, 0, s[14:15]
	v_cndmask_b32_e64 v25, v25, 0, s[16:17]
	v_cndmask_b32_e64 v32, v32, 0, s[18:19]
	v_cvt_pk_bf16_f32 v22, v22, v23
	v_cvt_pk_bf16_f32 v23, v24, v25
	v_cvt_pk_bf16_f32 v24, v30, v31
	v_mov_b32_e32 v30, s83
	v_cvt_pk_bf16_f32 v25, v33, v32
	s_waitcnt vmcnt(9)
; __device__ __forceinline__ unsigned cvt_pk_bf16(float lo, float hi) { unsigned r; asm volatile("v_cvt_pk_bf16_f32 %0, %1, %2" : "=v"(r) : "v"(lo), "v"(hi)); return r; }
; __device__ __forceinline__ float bf2f(unsigned short h) { return __uint_as_float((unsigned)h << 16); }
; __device__ __forceinline__ void mixer_bd(const bf16_t* __restrict__ Z, bf16_t* __restrict__ Y, const float* __restrict__ lng, const float* __restrict__ lnb, const float* __restrict__ wsp, const float* __restrict__ bsp, ...
;     ...
;             for (int ks = 0; ks < 4; ++ks) {
;                 const int s0 = ks * 32 + fq * 8;
; #pragma unroll
;                 for (int j = 0; j < 4; ++j) { if (s0 + j > t) wa[ks][j] = 0.f; if (s0 + 4 + j > t) wb[ks][j] = 0.f; }
;                 u32x4 wp; wp.x = cvt_pk_bf16(wa[ks][0], wa[ks][1]); wp.y = cvt_pk_bf16(wa[ks][2], wa[ks][3]); wp.z = cvt_pk_bf16(wb[ks][0], wb[ks][1]); wp.w = cvt_pk_bf16(wb[ks][2], wb[ks][3]);
;                 wf[hh][ks] = __builtin_bit_cast(bf16x8, wp);
;             }
;         }
; #pragma unroll 8
;         for (int k = 0; k < 16; ++k) {
;             const int s = wave * 16 + k; const bf16_t* zr = Z + (row0 + s) * NZ + 4 * 256;
;             const float v0 = bf2f(zr[lane]), v1 = bf2f(zr[lane + 64]), v2 = bf2f(zr[lane + 128]), v3 = bf2f(zr[lane + 192]);
	v_cndmask_b32_e64 v32, v140, v30, s[22:23]
	v_cndmask_b32_e64 v30, v143, v143, s[22:23]
	v_cndmask_b32_e64 v33, v142, v142, s[22:23]
	v_cndmask_b32_e64 v34, v141, v141, s[22:23]
	v_cndmask_b32_e64 v31, v46, 0, s[20:21]
	v_cndmask_b32_e64 v34, v34, 0, s[26:27]
	v_cndmask_b32_e64 v33, v33, 0, s[30:31]
	v_cndmask_b32_e64 v46, v30, 0, s[36:37]
	v_cndmask_b32_e64 v35, v47, 0, s[24:25]
	v_cndmask_b32_e64 v36, v48, 0, s[28:29]
	v_cndmask_b32_e64 v37, v49, 0, s[34:35]
	v_cvt_pk_bf16_f32 v30, v31, v35
	v_cvt_pk_bf16_f32 v31, v36, v37
	v_cvt_pk_bf16_f32 v32, v32, v34
	v_cvt_pk_bf16_f32 v33, v33, v46
	v_mov_b32_e32 v34, s83
	s_waitcnt vmcnt(7)
	v_cndmask_b32_e64 v46, v149, v149, s[40:41]
	v_cndmask_b32_e64 v35, v144, 0, s[38:39]
	v_cndmask_b32_e64 v36, v148, v34, s[40:41]
	v_cndmask_b32_e64 v34, v151, v151, s[40:41]
	v_cndmask_b32_e64 v46, v46, 0, s[44:45]
	v_cndmask_b32_e64 v37, v150, v150, s[40:41]
	v_cndmask_b32_e64 v47, v145, 0, s[42:43]
	v_cndmask_b32_e64 v48, v146, 0, s[46:47]
	v_cndmask_b32_e64 v49, v147, 0, s[50:51]
	v_cndmask_b32_e64 v63, v34, 0, s[52:53]
	v_cvt_pk_bf16_f32 v34, v35, v47
	v_cvt_pk_bf16_f32 v35, v48, v49
	v_cvt_pk_bf16_f32 v36, v36, v46
	s_waitcnt vmcnt(6)
	v_cndmask_b32_e64 v46, v38, 0, s[54:55]
	v_mov_b32_e32 v38, s83
	v_cndmask_b32_e64 v37, v37, 0, s[48:49]
	s_waitcnt vmcnt(5)
	v_cndmask_b32_e64 v42, v42, v38, s[56:57]
	v_cndmask_b32_e64 v38, v45, v45, s[56:57]
	v_cndmask_b32_e64 v43, v43, v43, s[56:57]
	v_cndmask_b32_e64 v39, v39, 0, s[58:59]
	v_cndmask_b32_e64 v40, v40, 0, s[62:63]
	v_cvt_pk_bf16_f32 v37, v37, v63
	v_cndmask_b32_e64 v43, v43, 0, s[60:61]
	v_cndmask_b32_e64 v41, v41, 0, s[66:67]
	v_cndmask_b32_e64 v45, v38, 0, s[68:69]
	v_cvt_pk_bf16_f32 v38, v46, v39
	v_cvt_pk_bf16_f32 v39, v40, v41
	v_cvt_pk_bf16_f32 v40, v42, v43
	v_add_u32_e32 v42, s77, v166
	v_cndmask_b32_e64 v44, v44, v44, s[56:57]
	v_ashrrev_i32_e32 v43, 31, v42
	v_cndmask_b32_e64 v44, v44, 0, s[64:65]
	v_lshlrev_b64 v[42:43], 2, v[42:43]
	v_cvt_pk_bf16_f32 v41, v44, v45
	v_lshl_add_u64 v[44:45], vcc, 0, v[42:43]
	v_readlane_b32 vcc_lo, v255, 44
	v_readlane_b32 vcc_hi, v255, 45
	global_load_dword v46, v[44:45], off
	v_mov_b32_e32 v63, v122
	v_lshl_add_u64 v[42:43], vcc, 0, v[42:43]
	global_load_dword v47, v[42:43], off
	global_load_dword v48, v[44:45], off offset:256
	global_load_dword v49, v[42:43], off offset:256
	v_mov_b32_e32 v42, 0xc0000
	v_mad_i64_i32 v[42:43], s[72:73], s72, v42, v[56:57]
	s_mov_b64 s[72:73], 0
	s_add_u32 s100, s0, 0x1000
	s_addc_u32 s101, s1, 0
	v_mov_b64_e32 v[176:177], s[100:101]
	s_lshl_b32 s100, s86, 6
	s_and_b32 s101, s100, 0xfc0
	s_sub_i32 s101, 29, s101
	v_cmp_lt_i32_e32 vcc, s101, v123
	s_nop 1
	v_cndmask_b32_e32 v160, 0, v124, vcc
	v_add_u32_e32 v160, s100, v160
	v_mad_i64_i32 v[160:161], vcc, v160, s33, v[176:177]
	v_add_co_u32_e32 v160, vcc, v160, v0
	s_nop 1
	v_addc_co_u32_e32 v161, vcc, 0, v161, vcc
	global_load_dwordx4 v[152:155], v[160:161], off offset:512
	global_load_dwordx4 v[156:159], v[160:161], off offset:1024
	v_cmp_lt_i32_e32 vcc, s101, v126
	s_nop 1
	v_cndmask_b32_e32 v160, 0, v127, vcc
	v_add_u32_e32 v160, s100, v160
	v_mad_i64_i32 v[160:161], vcc, v160, s33, v[176:177]
	v_add_co_u32_e32 v160, vcc, v160, v62
	s_nop 1
	v_addc_co_u32_e32 v161, vcc, 0, v161, vcc
	global_load_dwordx4 v[168:171], v[160:161], off offset:512
	global_load_dwordx4 v[172:175], v[160:161], off offset:1024
	v_cmp_lt_i32_e32 vcc, s101, v129
	s_nop 1
	v_cndmask_b32_e32 v160, 0, v130, vcc
	v_add_u32_e32 v160, s100, v160
	v_mad_i64_i32 v[160:161], vcc, v160, s33, v[176:177]
	v_add_co_u32_e32 v160, vcc, v160, v64
	s_nop 1
	v_addc_co_u32_e32 v161, vcc, 0, v161, vcc
	global_load_dwordx4 v[182:185], v[160:161], off offset:512
	global_load_dwordx4 v[186:189], v[160:161], off offset:1024
.LBB0_249:
	s_nop 0
	v_lshl_add_u64 v[44:45], v[42:43], 0, s[72:73]
	s_mov_b32 s82, 0x8400000
	v_lshl_add_u64 v[198:199], v[44:45], 0, s[82:83]
	s_mov_b32 s82, 0x8402000
	v_lshl_add_u64 v[200:201], v[44:45], 0, s[82:83]
	s_mov_b32 s82, 0x8403000
	v_lshl_add_u64 v[202:203], v[44:45], 0, s[82:83]
	s_mov_b32 s82, 0x8405000
	v_lshl_add_u64 v[204:205], v[44:45], 0, s[82:83]
	s_mov_b32 s82, 0x8406000
	v_lshl_add_u64 v[206:207], v[44:45], 0, s[82:83]
	s_mov_b32 s82, 0x8408000
	v_lshl_add_u64 v[208:209], v[44:45], 0, s[82:83]
	s_mov_b32 s82, 0x8409000
	v_lshl_add_u64 v[210:211], v[44:45], 0, s[82:83]
	s_mov_b32 s82, 0x840b000
	v_lshl_add_u64 v[212:213], v[44:45], 0, s[82:83]
	global_load_ushort v214, v[198:199], off offset:2048
	global_load_ushort v215, v[198:199], off offset:2176
	global_load_ushort v216, v[198:199], off offset:2304
	global_load_ushort v217, v[198:199], off offset:2432
	global_load_ushort v219, v[200:201], off
	global_load_ushort v220, v[200:201], off offset:128
	global_load_ushort v221, v[200:201], off offset:256
	global_load_ushort v222, v[200:201], off offset:384
	global_load_ushort v223, v[202:203], off offset:2048
	global_load_ushort v224, v[202:203], off offset:2176
	global_load_ushort v225, v[202:203], off offset:2304
	global_load_ushort v226, v[202:203], off offset:2432
	global_load_ushort v227, v[204:205], off
	global_load_ushort v228, v[204:205], off offset:256
	global_load_ushort v229, v[204:205], off offset:128
	global_load_ushort v230, v[204:205], off offset:384
	global_load_ushort v231, v[206:207], off offset:2048
	global_load_ushort v232, v[206:207], off offset:2176
	global_load_ushort v233, v[206:207], off offset:2304
	global_load_ushort v234, v[206:207], off offset:2432
	global_load_ushort v235, v[208:209], off
	global_load_ushort v236, v[208:209], off offset:128
	global_load_ushort v237, v[208:209], off offset:256
	global_load_ushort v238, v[208:209], off offset:384
	global_load_ushort v239, v[210:211], off offset:2048
	global_load_ushort v243, v[210:211], off offset:2176
	global_load_ushort v244, v[210:211], off offset:2304
	global_load_ushort v245, v[210:211], off offset:2432
	global_load_ushort v246, v[212:213], off
	global_load_ushort v248, v[212:213], off offset:128
	global_load_ushort v249, v[212:213], off offset:256
	global_load_ushort v250, v[212:213], off offset:384
	v_add_co_u32_e32 v86, vcc, 0x8400000, v44
	s_add_u32 s72, s72, 0xc000
	s_nop 0
	v_addc_co_u32_e32 v87, vcc, 0, v45, vcc
	s_waitcnt vmcnt(28)
; __device__ __forceinline__ unsigned cvt_pk_bf16(float lo, float hi) { unsigned r; asm volatile("v_cvt_pk_bf16_f32 %0, %1, %2" : "=v"(r) : "v"(lo), "v"(hi)); return r; }
; __device__ __forceinline__ float bf2f(unsigned short h) { return __uint_as_float((unsigned)h << 16); }
; __device__ __forceinline__ void mixer_bd(const bf16_t* __restrict__ Z, bf16_t* __restrict__ Y, const float* __restrict__ lng, const float* __restrict__ lnb, const float* __restrict__ wsp, const float* __restrict__ bsp, ...
;     ...
;         for (int k = 0; k < 16; ++k) {
;             const int s = wave * 16 + k; const bf16_t* zr = Z + (row0 + s) * NZ + 4 * 256;
;             const float v0 = bf2f(zr[lane]), v1 = bf2f(zr[lane + 64]), v2 = bf2f(zr[lane + 128]), v3 = bf2f(zr[lane + 192]);
;             const float mean = wave_sum((v0 + v1) + (v2 + v3)) * (1.f / 256.f);
;             const float d0 = v0 - mean, d1 = v1 - mean, d2 = v2 - mean, d3 = v3 - mean;
;             const float var = wave_sum((d0 * d0 + d1 * d1) + (d2 * d2 + d3 * d3)) * (1.f / 256.f);
;             const float rstd = __builtin_amdgcn_rsqf(var + 1e-5f);
;             const int ca = hf * 128 + lane, cb = ca + 64;
;             const float a = (hf ? d2 : d0) * rstd * lng[ca] + lnb[ca], b = (hf ? d3 : d1) * rstd * lng[cb] + lnb[cb];
;             const unsigned pk = cvt_pk_bf16(a, b);
;             vt[lane * VP + s] = (bf16_t)(pk & 0xffffu); vt[(lane + 64) * VP + s] = (bf16_t)(pk >> 16);
;         }
	v_mov_b32_e32 v65, v214
	v_mov_b32_e32 v67, v215
	v_mov_b32_e32 v88, v216
	s_addc_u32 s73, s73, 0
	v_mov_b32_e32 v86, v217
	s_cmp_eq_u32 s72, 0x18000
	v_lshlrev_b32_e32 v65, 16, v65
	v_lshlrev_b32_e32 v67, 16, v67
	v_lshlrev_b32_e32 v88, 16, v88
	v_add_f32_e32 v87, v65, v67
	v_lshlrev_b32_e32 v86, 16, v86
	v_add_f32_e32 v140, v88, v86
	v_add_f32_e32 v87, v87, v140
	v_mov_b32_e32 v140, 0
	s_nop 0
	v_add_f32_dpp v87, v87, v87 row_shr:1 row_mask:0xf bank_mask:0xf bound_ctrl:1
	s_nop 1
	v_add_f32_dpp v87, v87, v87 row_shr:2 row_mask:0xf bank_mask:0xf bound_ctrl:1
	s_nop 1
	v_add_f32_dpp v87, v87, v87 row_shr:4 row_mask:0xf bank_mask:0xf bound_ctrl:1
	s_nop 1
	v_add_f32_dpp v87, v87, v87 row_shr:8 row_mask:0xf bank_mask:0xf bound_ctrl:1
	s_nop 1
	v_mov_b32_dpp v140, v87 row_bcast:15 row_mask:0xa bank_mask:0xf
	v_add_f32_e32 v87, v87, v140
	v_mov_b32_e32 v140, 0
	s_nop 1
	v_mov_b32_dpp v140, v87 row_bcast:31 row_mask:0xc bank_mask:0xf
	v_add_f32_e32 v87, v87, v140
	s_nop 0
	v_readlane_b32 s82, v87, 63
	s_nop 1
	v_fmac_f32_e32 v67, s82, v241
	v_fmac_f32_e32 v86, s82, v241
	v_fmac_f32_e32 v65, s82, v241
	v_fmac_f32_e32 v88, s82, v241
	v_mul_f32_e32 v87, v67, v67
	v_mul_f32_e32 v140, v86, v86
	v_fmac_f32_e32 v87, v65, v65
	v_fmac_f32_e32 v140, v88, v88
	v_add_f32_e32 v87, v87, v140
	v_mov_b32_e32 v140, 0
	v_cndmask_b32_e64 v65, v88, v65, s[70:71]
	v_add_f32_dpp v87, v87, v87 row_shr:1 row_mask:0xf bank_mask:0xf bound_ctrl:1
	v_cndmask_b32_e64 v67, v86, v67, s[70:71]
	s_nop 0
	v_add_f32_dpp v87, v87, v87 row_shr:2 row_mask:0xf bank_mask:0xf bound_ctrl:1
	s_nop 1
	v_add_f32_dpp v87, v87, v87 row_shr:4 row_mask:0xf bank_mask:0xf bound_ctrl:1
	s_nop 1
	v_add_f32_dpp v87, v87, v87 row_shr:8 row_mask:0xf bank_mask:0xf bound_ctrl:1
	s_nop 1
	v_mov_b32_dpp v140, v87 row_bcast:15 row_mask:0xa bank_mask:0xf
	v_add_f32_e32 v87, v87, v140
	v_mov_b32_e32 v140, 0
	s_nop 1
	v_mov_b32_dpp v140, v87 row_bcast:31 row_mask:0xc bank_mask:0xf
	v_add_f32_e32 v87, v87, v140
	s_nop 0
	v_readlane_b32 s82, v87, 63
	s_nop 1
	v_fma_f32 v87, s82, v242, v197
	v_rsq_f32_e32 v87, v87
	s_mov_b32 s82, 0x8402000
	v_add_co_u32_e32 v86, vcc, s82, v44
	v_mul_f32_e32 v65, v65, v87
	v_fma_f32 v65, v46, v65, v47
	v_mul_f32_e32 v67, v67, v87
	v_fma_f32 v67, v48, v67, v49
	v_cvt_pk_bf16_f32 v65, v65, v67
	ds_write_b16 v63, v65
	ds_write_b16_d16_hi v63, v65 offset:16896
	v_addc_co_u32_e32 v87, vcc, 0, v45, vcc
	s_waitcnt vmcnt(24)
	v_mov_b32_e32 v65, v219
	v_mov_b32_e32 v67, v220
	v_mov_b32_e32 v88, v221
	v_lshlrev_b32_e32 v65, 16, v65
	v_mov_b32_e32 v86, v222
	v_lshlrev_b32_e32 v67, 16, v67
	v_lshlrev_b32_e32 v88, 16, v88
	v_add_f32_e32 v87, v65, v67
	v_lshlrev_b32_e32 v86, 16, v86
	v_add_f32_e32 v140, v88, v86
	v_add_f32_e32 v87, v87, v140
	v_mov_b32_e32 v140, 0
	s_nop 0
	v_add_f32_dpp v87, v87, v87 row_shr:1 row_mask:0xf bank_mask:0xf bound_ctrl:1
	s_nop 1
	v_add_f32_dpp v87, v87, v87 row_shr:2 row_mask:0xf bank_mask:0xf bound_ctrl:1
	s_nop 1
	v_add_f32_dpp v87, v87, v87 row_shr:4 row_mask:0xf bank_mask:0xf bound_ctrl:1
	s_nop 1
	v_add_f32_dpp v87, v87, v87 row_shr:8 row_mask:0xf bank_mask:0xf bound_ctrl:1
	s_nop 1
	v_mov_b32_dpp v140, v87 row_bcast:15 row_mask:0xa bank_mask:0xf
	v_add_f32_e32 v87, v87, v140
	v_mov_b32_e32 v140, 0
	s_nop 1
	v_mov_b32_dpp v140, v87 row_bcast:31 row_mask:0xc bank_mask:0xf
	v_add_f32_e32 v87, v87, v140
	s_nop 0
	v_readlane_b32 s82, v87, 63
	s_nop 1
	v_fmac_f32_e32 v67, s82, v241
	v_fmac_f32_e32 v86, s82, v241
	v_fmac_f32_e32 v65, s82, v241
	v_fmac_f32_e32 v88, s82, v241
	v_mul_f32_e32 v87, v67, v67
	v_mul_f32_e32 v140, v86, v86
	v_fmac_f32_e32 v87, v65, v65
	v_fmac_f32_e32 v140, v88, v88
	v_add_f32_e32 v87, v87, v140
	v_mov_b32_e32 v140, 0
	v_cndmask_b32_e64 v65, v88, v65, s[70:71]
	v_add_f32_dpp v87, v87, v87 row_shr:1 row_mask:0xf bank_mask:0xf bound_ctrl:1
	v_cndmask_b32_e64 v67, v86, v67, s[70:71]
	s_nop 0
	v_add_f32_dpp v87, v87, v87 row_shr:2 row_mask:0xf bank_mask:0xf bound_ctrl:1
	s_nop 1
	v_add_f32_dpp v87, v87, v87 row_shr:4 row_mask:0xf bank_mask:0xf bound_ctrl:1
	s_nop 1
	v_add_f32_dpp v87, v87, v87 row_shr:8 row_mask:0xf bank_mask:0xf bound_ctrl:1
	s_nop 1
	v_mov_b32_dpp v140, v87 row_bcast:15 row_mask:0xa bank_mask:0xf
	v_add_f32_e32 v87, v87, v140
	v_mov_b32_e32 v140, 0
	s_nop 1
	v_mov_b32_dpp v140, v87 row_bcast:31 row_mask:0xc bank_mask:0xf
	v_add_f32_e32 v87, v87, v140
	s_nop 0
	v_readlane_b32 s82, v87, 63
	s_nop 1
	v_fma_f32 v87, s82, v242, v197
	v_rsq_f32_e32 v87, v87
	s_mov_b32 s82, 0x8403000
	v_add_co_u32_e32 v86, vcc, s82, v44
	v_mul_f32_e32 v65, v65, v87
	v_fma_f32 v65, v46, v65, v47
	v_mul_f32_e32 v67, v67, v87
	v_fma_f32 v67, v48, v67, v49
	v_cvt_pk_bf16_f32 v65, v65, v67
	ds_write_b16 v63, v65 offset:2
	ds_write_b16_d16_hi v63, v65 offset:16898
	v_addc_co_u32_e32 v87, vcc, 0, v45, vcc
	s_waitcnt vmcnt(20)
; __device__ __forceinline__ unsigned cvt_pk_bf16(float lo, float hi) { unsigned r; asm volatile("v_cvt_pk_bf16_f32 %0, %1, %2" : "=v"(r) : "v"(lo), "v"(hi)); return r; }
; __device__ __forceinline__ float bf2f(unsigned short h) { return __uint_as_float((unsigned)h << 16); }
; __device__ __forceinline__ void mixer_bd(const bf16_t* __restrict__ Z, bf16_t* __restrict__ Y, const float* __restrict__ lng, const float* __restrict__ lnb, const float* __restrict__ wsp, const float* __restrict__ bsp, ...
;     ...
;         for (int k = 0; k < 16; ++k) {
;             const int s = wave * 16 + k; const bf16_t* zr = Z + (row0 + s) * NZ + 4 * 256;
;             const float v0 = bf2f(zr[lane]), v1 = bf2f(zr[lane + 64]), v2 = bf2f(zr[lane + 128]), v3 = bf2f(zr[lane + 192]);
;             const float mean = wave_sum((v0 + v1) + (v2 + v3)) * (1.f / 256.f);
;             const float d0 = v0 - mean, d1 = v1 - mean, d2 = v2 - mean, d3 = v3 - mean;
;             const float var = wave_sum((d0 * d0 + d1 * d1) + (d2 * d2 + d3 * d3)) * (1.f / 256.f);
;             const float rstd = __builtin_amdgcn_rsqf(var + 1e-5f);
;             const int ca = hf * 128 + lane, cb = ca + 64;
;             const float a = (hf ? d2 : d0) * rstd * lng[ca] + lnb[ca], b = (hf ? d3 : d1) * rstd * lng[cb] + lnb[cb];
;             const unsigned pk = cvt_pk_bf16(a, b);
;             vt[lane * VP + s] = (bf16_t)(pk & 0xffffu); vt[(lane + 64) * VP + s] = (bf16_t)(pk >> 16);
;         }
	v_mov_b32_e32 v65, v223
	v_mov_b32_e32 v67, v224
	v_mov_b32_e32 v88, v225
	v_lshlrev_b32_e32 v65, 16, v65
	v_mov_b32_e32 v86, v226
	v_lshlrev_b32_e32 v67, 16, v67
	v_lshlrev_b32_e32 v88, 16, v88
	v_add_f32_e32 v87, v65, v67
	v_lshlrev_b32_e32 v86, 16, v86
	v_add_f32_e32 v140, v88, v86
	v_add_f32_e32 v87, v87, v140
	v_mov_b32_e32 v140, 0
	s_nop 0
	v_add_f32_dpp v87, v87, v87 row_shr:1 row_mask:0xf bank_mask:0xf bound_ctrl:1
	s_nop 1
	v_add_f32_dpp v87, v87, v87 row_shr:2 row_mask:0xf bank_mask:0xf bound_ctrl:1
	s_nop 1
	v_add_f32_dpp v87, v87, v87 row_shr:4 row_mask:0xf bank_mask:0xf bound_ctrl:1
	s_nop 1
	v_add_f32_dpp v87, v87, v87 row_shr:8 row_mask:0xf bank_mask:0xf bound_ctrl:1
	s_nop 1
	v_mov_b32_dpp v140, v87 row_bcast:15 row_mask:0xa bank_mask:0xf
	v_add_f32_e32 v87, v87, v140
	v_mov_b32_e32 v140, 0
	s_nop 1
	v_mov_b32_dpp v140, v87 row_bcast:31 row_mask:0xc bank_mask:0xf
	v_add_f32_e32 v87, v87, v140
	s_nop 0
	v_readlane_b32 s82, v87, 63
	s_nop 1
	v_fmac_f32_e32 v67, s82, v241
	v_fmac_f32_e32 v86, s82, v241
	v_fmac_f32_e32 v65, s82, v241
	v_fmac_f32_e32 v88, s82, v241
	v_mul_f32_e32 v87, v67, v67
	v_mul_f32_e32 v140, v86, v86
	v_fmac_f32_e32 v87, v65, v65
	v_fmac_f32_e32 v140, v88, v88
	v_add_f32_e32 v87, v87, v140
	v_mov_b32_e32 v140, 0
	v_cndmask_b32_e64 v65, v88, v65, s[70:71]
	v_add_f32_dpp v87, v87, v87 row_shr:1 row_mask:0xf bank_mask:0xf bound_ctrl:1
	v_cndmask_b32_e64 v67, v86, v67, s[70:71]
	s_nop 0
	v_add_f32_dpp v87, v87, v87 row_shr:2 row_mask:0xf bank_mask:0xf bound_ctrl:1
	s_nop 1
	v_add_f32_dpp v87, v87, v87 row_shr:4 row_mask:0xf bank_mask:0xf bound_ctrl:1
	s_nop 1
	v_add_f32_dpp v87, v87, v87 row_shr:8 row_mask:0xf bank_mask:0xf bound_ctrl:1
	s_nop 1
	v_mov_b32_dpp v140, v87 row_bcast:15 row_mask:0xa bank_mask:0xf
	v_add_f32_e32 v87, v87, v140
	v_mov_b32_e32 v140, 0
	s_nop 1
	v_mov_b32_dpp v140, v87 row_bcast:31 row_mask:0xc bank_mask:0xf
	v_add_f32_e32 v87, v87, v140
	s_nop 0
	v_readlane_b32 s82, v87, 63
	s_nop 1
	v_fma_f32 v87, s82, v242, v197
	v_rsq_f32_e32 v87, v87
	s_mov_b32 s82, 0x8405000
	v_add_co_u32_e32 v140, vcc, s82, v44
	v_mul_f32_e32 v65, v65, v87
	v_fma_f32 v65, v46, v65, v47
	v_mul_f32_e32 v67, v67, v87
	v_fma_f32 v67, v48, v67, v49
	v_cvt_pk_bf16_f32 v65, v65, v67
	ds_write_b16 v63, v65 offset:4
	ds_write_b16_d16_hi v63, v65 offset:16900
	v_addc_co_u32_e32 v141, vcc, 0, v45, vcc
	s_waitcnt vmcnt(16)
	v_mov_b32_e32 v65, v227
	v_mov_b32_e32 v86, v228
	v_lshlrev_b32_e32 v67, 16, v65
	v_mov_b32_e32 v65, v229
	v_lshlrev_b32_e32 v87, 16, v86
	v_mov_b32_e32 v86, v230
	v_lshlrev_b32_e32 v65, 16, v65
	v_add_f32_e32 v88, v67, v65
	v_lshlrev_b32_e32 v86, 16, v86
	v_add_f32_e32 v140, v87, v86
	v_add_f32_e32 v88, v88, v140
	v_mov_b32_e32 v140, 0
	s_nop 0
	v_add_f32_dpp v88, v88, v88 row_shr:1 row_mask:0xf bank_mask:0xf bound_ctrl:1
	s_nop 1
	v_add_f32_dpp v88, v88, v88 row_shr:2 row_mask:0xf bank_mask:0xf bound_ctrl:1
	s_nop 1
	v_add_f32_dpp v88, v88, v88 row_shr:4 row_mask:0xf bank_mask:0xf bound_ctrl:1
	s_nop 1
	v_add_f32_dpp v88, v88, v88 row_shr:8 row_mask:0xf bank_mask:0xf bound_ctrl:1
	s_nop 1
	v_mov_b32_dpp v140, v88 row_bcast:15 row_mask:0xa bank_mask:0xf
	v_add_f32_e32 v88, v88, v140
	v_mov_b32_e32 v140, 0
	s_nop 1
	v_mov_b32_dpp v140, v88 row_bcast:31 row_mask:0xc bank_mask:0xf
	v_add_f32_e32 v88, v88, v140
	s_nop 0
	v_readlane_b32 s82, v88, 63
	s_nop 1
	v_fmac_f32_e32 v65, s82, v241
	v_fmac_f32_e32 v86, s82, v241
	v_fmac_f32_e32 v67, s82, v241
	v_fmac_f32_e32 v87, s82, v241
	v_mul_f32_e32 v88, v65, v65
	v_mul_f32_e32 v140, v86, v86
	v_fmac_f32_e32 v88, v67, v67
	v_fmac_f32_e32 v140, v87, v87
	v_add_f32_e32 v88, v88, v140
	v_mov_b32_e32 v140, 0
	v_cndmask_b32_e64 v65, v86, v65, s[70:71]
	v_add_f32_dpp v88, v88, v88 row_shr:1 row_mask:0xf bank_mask:0xf bound_ctrl:1
	v_cndmask_b32_e64 v67, v87, v67, s[70:71]
	s_nop 0
	v_add_f32_dpp v88, v88, v88 row_shr:2 row_mask:0xf bank_mask:0xf bound_ctrl:1
	s_nop 1
	v_add_f32_dpp v88, v88, v88 row_shr:4 row_mask:0xf bank_mask:0xf bound_ctrl:1
	s_nop 1
	v_add_f32_dpp v88, v88, v88 row_shr:8 row_mask:0xf bank_mask:0xf bound_ctrl:1
	s_nop 1
	v_mov_b32_dpp v140, v88 row_bcast:15 row_mask:0xa bank_mask:0xf
	v_add_f32_e32 v88, v88, v140
	v_mov_b32_e32 v140, 0
	s_nop 1
	v_mov_b32_dpp v140, v88 row_bcast:31 row_mask:0xc bank_mask:0xf
	v_add_f32_e32 v88, v88, v140
	s_nop 0
	v_readlane_b32 s82, v88, 63
	s_nop 1
	v_fma_f32 v88, s82, v242, v197
	v_rsq_f32_e32 v88, v88
	s_mov_b32 s82, 0x8406000
	v_add_co_u32_e32 v86, vcc, s82, v44
	v_mul_f32_e32 v65, v65, v88
	v_mul_f32_e32 v67, v67, v88
	v_fma_f32 v65, v48, v65, v49
	v_fma_f32 v67, v46, v67, v47
	v_cvt_pk_bf16_f32 v65, v67, v65
	ds_write_b16 v63, v65 offset:6
	ds_write_b16_d16_hi v63, v65 offset:16902
	v_addc_co_u32_e32 v87, vcc, 0, v45, vcc
	s_waitcnt vmcnt(12)
; __device__ __forceinline__ unsigned cvt_pk_bf16(float lo, float hi) { unsigned r; asm volatile("v_cvt_pk_bf16_f32 %0, %1, %2" : "=v"(r) : "v"(lo), "v"(hi)); return r; }
; __device__ __forceinline__ float bf2f(unsigned short h) { return __uint_as_float((unsigned)h << 16); }
; __device__ __forceinline__ void mixer_bd(const bf16_t* __restrict__ Z, bf16_t* __restrict__ Y, const float* __restrict__ lng, const float* __restrict__ lnb, const float* __restrict__ wsp, const float* __restrict__ bsp, ...
;     ...
;         for (int k = 0; k < 16; ++k) {
;             const int s = wave * 16 + k; const bf16_t* zr = Z + (row0 + s) * NZ + 4 * 256;
;             const float v0 = bf2f(zr[lane]), v1 = bf2f(zr[lane + 64]), v2 = bf2f(zr[lane + 128]), v3 = bf2f(zr[lane + 192]);
;             const float mean = wave_sum((v0 + v1) + (v2 + v3)) * (1.f / 256.f);
;             const float d0 = v0 - mean, d1 = v1 - mean, d2 = v2 - mean, d3 = v3 - mean;
;             const float var = wave_sum((d0 * d0 + d1 * d1) + (d2 * d2 + d3 * d3)) * (1.f / 256.f);
;             const float rstd = __builtin_amdgcn_rsqf(var + 1e-5f);
;             const int ca = hf * 128 + lane, cb = ca + 64;
;             const float a = (hf ? d2 : d0) * rstd * lng[ca] + lnb[ca], b = (hf ? d3 : d1) * rstd * lng[cb] + lnb[cb];
;             const unsigned pk = cvt_pk_bf16(a, b);
;             vt[lane * VP + s] = (bf16_t)(pk & 0xffffu); vt[(lane + 64) * VP + s] = (bf16_t)(pk >> 16);
;         }
	v_mov_b32_e32 v65, v231
	v_mov_b32_e32 v67, v232
	v_mov_b32_e32 v88, v233
	v_lshlrev_b32_e32 v65, 16, v65
	v_mov_b32_e32 v86, v234
	v_lshlrev_b32_e32 v67, 16, v67
	v_lshlrev_b32_e32 v88, 16, v88
	v_add_f32_e32 v87, v65, v67
	v_lshlrev_b32_e32 v86, 16, v86
	v_add_f32_e32 v140, v88, v86
	v_add_f32_e32 v87, v87, v140
	v_mov_b32_e32 v140, 0
	s_nop 0
	v_add_f32_dpp v87, v87, v87 row_shr:1 row_mask:0xf bank_mask:0xf bound_ctrl:1
	s_nop 1
	v_add_f32_dpp v87, v87, v87 row_shr:2 row_mask:0xf bank_mask:0xf bound_ctrl:1
	s_nop 1
	v_add_f32_dpp v87, v87, v87 row_shr:4 row_mask:0xf bank_mask:0xf bound_ctrl:1
	s_nop 1
	v_add_f32_dpp v87, v87, v87 row_shr:8 row_mask:0xf bank_mask:0xf bound_ctrl:1
	s_nop 1
	v_mov_b32_dpp v140, v87 row_bcast:15 row_mask:0xa bank_mask:0xf
	v_add_f32_e32 v87, v87, v140
	v_mov_b32_e32 v140, 0
	s_nop 1
	v_mov_b32_dpp v140, v87 row_bcast:31 row_mask:0xc bank_mask:0xf
	v_add_f32_e32 v87, v87, v140
	s_nop 0
	v_readlane_b32 s82, v87, 63
	s_nop 1
	v_fmac_f32_e32 v67, s82, v241
	v_fmac_f32_e32 v86, s82, v241
	v_fmac_f32_e32 v65, s82, v241
	v_fmac_f32_e32 v88, s82, v241
	v_mul_f32_e32 v87, v67, v67
	v_mul_f32_e32 v140, v86, v86
	v_fmac_f32_e32 v87, v65, v65
	v_fmac_f32_e32 v140, v88, v88
	v_add_f32_e32 v87, v87, v140
	v_mov_b32_e32 v140, 0
	v_cndmask_b32_e64 v65, v88, v65, s[70:71]
	v_add_f32_dpp v87, v87, v87 row_shr:1 row_mask:0xf bank_mask:0xf bound_ctrl:1
	v_cndmask_b32_e64 v67, v86, v67, s[70:71]
	s_nop 0
	v_add_f32_dpp v87, v87, v87 row_shr:2 row_mask:0xf bank_mask:0xf bound_ctrl:1
	s_nop 1
	v_add_f32_dpp v87, v87, v87 row_shr:4 row_mask:0xf bank_mask:0xf bound_ctrl:1
	s_nop 1
	v_add_f32_dpp v87, v87, v87 row_shr:8 row_mask:0xf bank_mask:0xf bound_ctrl:1
	s_nop 1
	v_mov_b32_dpp v140, v87 row_bcast:15 row_mask:0xa bank_mask:0xf
	v_add_f32_e32 v87, v87, v140
	v_mov_b32_e32 v140, 0
	s_nop 1
	v_mov_b32_dpp v140, v87 row_bcast:31 row_mask:0xc bank_mask:0xf
	v_add_f32_e32 v87, v87, v140
	s_nop 0
	v_readlane_b32 s82, v87, 63
	s_nop 1
	v_fma_f32 v87, s82, v242, v197
	v_rsq_f32_e32 v87, v87
	s_mov_b32 s82, 0x8408000
	v_add_co_u32_e32 v86, vcc, s82, v44
	v_mul_f32_e32 v65, v65, v87
	v_fma_f32 v65, v46, v65, v47
	v_mul_f32_e32 v67, v67, v87
	v_fma_f32 v67, v48, v67, v49
	v_cvt_pk_bf16_f32 v65, v65, v67
	ds_write_b16 v63, v65 offset:8
	ds_write_b16_d16_hi v63, v65 offset:16904
	v_addc_co_u32_e32 v87, vcc, 0, v45, vcc
	s_waitcnt vmcnt(8)
	v_mov_b32_e32 v65, v235
	v_mov_b32_e32 v67, v236
	v_mov_b32_e32 v88, v237
	v_lshlrev_b32_e32 v65, 16, v65
	v_mov_b32_e32 v86, v238
	v_lshlrev_b32_e32 v67, 16, v67
	v_lshlrev_b32_e32 v88, 16, v88
	v_add_f32_e32 v87, v65, v67
	v_lshlrev_b32_e32 v86, 16, v86
	v_add_f32_e32 v140, v88, v86
	v_add_f32_e32 v87, v87, v140
	v_mov_b32_e32 v140, 0
	s_nop 0
	v_add_f32_dpp v87, v87, v87 row_shr:1 row_mask:0xf bank_mask:0xf bound_ctrl:1
	s_nop 1
	v_add_f32_dpp v87, v87, v87 row_shr:2 row_mask:0xf bank_mask:0xf bound_ctrl:1
	s_nop 1
	v_add_f32_dpp v87, v87, v87 row_shr:4 row_mask:0xf bank_mask:0xf bound_ctrl:1
	s_nop 1
	v_add_f32_dpp v87, v87, v87 row_shr:8 row_mask:0xf bank_mask:0xf bound_ctrl:1
	s_nop 1
	v_mov_b32_dpp v140, v87 row_bcast:15 row_mask:0xa bank_mask:0xf
	v_add_f32_e32 v87, v87, v140
	v_mov_b32_e32 v140, 0
	s_nop 1
	v_mov_b32_dpp v140, v87 row_bcast:31 row_mask:0xc bank_mask:0xf
	v_add_f32_e32 v87, v87, v140
	s_nop 0
	v_readlane_b32 s82, v87, 63
	s_nop 1
	v_fmac_f32_e32 v67, s82, v241
	v_fmac_f32_e32 v86, s82, v241
	v_fmac_f32_e32 v65, s82, v241
	v_fmac_f32_e32 v88, s82, v241
	v_mul_f32_e32 v87, v67, v67
	v_mul_f32_e32 v140, v86, v86
	v_fmac_f32_e32 v87, v65, v65
	v_fmac_f32_e32 v140, v88, v88
	v_add_f32_e32 v87, v87, v140
	v_mov_b32_e32 v140, 0
	v_cndmask_b32_e64 v65, v88, v65, s[70:71]
	v_add_f32_dpp v87, v87, v87 row_shr:1 row_mask:0xf bank_mask:0xf bound_ctrl:1
	v_cndmask_b32_e64 v67, v86, v67, s[70:71]
	s_nop 0
	v_add_f32_dpp v87, v87, v87 row_shr:2 row_mask:0xf bank_mask:0xf bound_ctrl:1
	s_nop 1
	v_add_f32_dpp v87, v87, v87 row_shr:4 row_mask:0xf bank_mask:0xf bound_ctrl:1
	s_nop 1
	v_add_f32_dpp v87, v87, v87 row_shr:8 row_mask:0xf bank_mask:0xf bound_ctrl:1
	s_nop 1
	v_mov_b32_dpp v140, v87 row_bcast:15 row_mask:0xa bank_mask:0xf
	v_add_f32_e32 v87, v87, v140
	v_mov_b32_e32 v140, 0
	s_nop 1
	v_mov_b32_dpp v140, v87 row_bcast:31 row_mask:0xc bank_mask:0xf
	v_add_f32_e32 v87, v87, v140
	s_nop 0
	v_readlane_b32 s82, v87, 63
	s_nop 1
	v_fma_f32 v87, s82, v242, v197
	v_rsq_f32_e32 v87, v87
	s_mov_b32 s82, 0x8409000
	v_add_co_u32_e32 v86, vcc, s82, v44
	v_mul_f32_e32 v65, v65, v87
	v_fma_f32 v65, v46, v65, v47
	v_mul_f32_e32 v67, v67, v87
	v_fma_f32 v67, v48, v67, v49
	v_cvt_pk_bf16_f32 v65, v65, v67
	ds_write_b16 v63, v65 offset:10
	ds_write_b16_d16_hi v63, v65 offset:16906
	v_addc_co_u32_e32 v87, vcc, 0, v45, vcc
	s_waitcnt vmcnt(4)
; __device__ __forceinline__ unsigned cvt_pk_bf16(float lo, float hi) { unsigned r; asm volatile("v_cvt_pk_bf16_f32 %0, %1, %2" : "=v"(r) : "v"(lo), "v"(hi)); return r; }
; __device__ __forceinline__ float bf2f(unsigned short h) { return __uint_as_float((unsigned)h << 16); }
; __device__ __forceinline__ void mixer_bd(const bf16_t* __restrict__ Z, bf16_t* __restrict__ Y, const float* __restrict__ lng, const float* __restrict__ lnb, const float* __restrict__ wsp, const float* __restrict__ bsp, ...
;     ...
;         for (int k = 0; k < 16; ++k) {
;             const int s = wave * 16 + k; const bf16_t* zr = Z + (row0 + s) * NZ + 4 * 256;
;             const float v0 = bf2f(zr[lane]), v1 = bf2f(zr[lane + 64]), v2 = bf2f(zr[lane + 128]), v3 = bf2f(zr[lane + 192]);
;             const float mean = wave_sum((v0 + v1) + (v2 + v3)) * (1.f / 256.f);
;             const float d0 = v0 - mean, d1 = v1 - mean, d2 = v2 - mean, d3 = v3 - mean;
;             const float var = wave_sum((d0 * d0 + d1 * d1) + (d2 * d2 + d3 * d3)) * (1.f / 256.f);
;             const float rstd = __builtin_amdgcn_rsqf(var + 1e-5f);
;             const int ca = hf * 128 + lane, cb = ca + 64;
;             const float a = (hf ? d2 : d0) * rstd * lng[ca] + lnb[ca], b = (hf ? d3 : d1) * rstd * lng[cb] + lnb[cb];
;             const unsigned pk = cvt_pk_bf16(a, b);
;             vt[lane * VP + s] = (bf16_t)(pk & 0xffffu); vt[(lane + 64) * VP + s] = (bf16_t)(pk >> 16);
;         }
	v_mov_b32_e32 v65, v239
	v_mov_b32_e32 v67, v243
	v_mov_b32_e32 v88, v244
	v_lshlrev_b32_e32 v65, 16, v65
	v_mov_b32_e32 v86, v245
	v_lshlrev_b32_e32 v67, 16, v67
	v_lshlrev_b32_e32 v88, 16, v88
	v_add_f32_e32 v87, v65, v67
	v_lshlrev_b32_e32 v86, 16, v86
	v_add_f32_e32 v140, v88, v86
	v_add_f32_e32 v87, v87, v140
	v_mov_b32_e32 v140, 0
	s_nop 0
	v_add_f32_dpp v87, v87, v87 row_shr:1 row_mask:0xf bank_mask:0xf bound_ctrl:1
	s_nop 1
	v_add_f32_dpp v87, v87, v87 row_shr:2 row_mask:0xf bank_mask:0xf bound_ctrl:1
	s_nop 1
	v_add_f32_dpp v87, v87, v87 row_shr:4 row_mask:0xf bank_mask:0xf bound_ctrl:1
	s_nop 1
	v_add_f32_dpp v87, v87, v87 row_shr:8 row_mask:0xf bank_mask:0xf bound_ctrl:1
	s_nop 1
	v_mov_b32_dpp v140, v87 row_bcast:15 row_mask:0xa bank_mask:0xf
	v_add_f32_e32 v87, v87, v140
	v_mov_b32_e32 v140, 0
	s_nop 1
	v_mov_b32_dpp v140, v87 row_bcast:31 row_mask:0xc bank_mask:0xf
	v_add_f32_e32 v87, v87, v140
	s_nop 0
	v_readlane_b32 s82, v87, 63
	s_nop 1
	v_fmac_f32_e32 v67, s82, v241
	v_fmac_f32_e32 v86, s82, v241
	v_fmac_f32_e32 v65, s82, v241
	v_fmac_f32_e32 v88, s82, v241
	v_mul_f32_e32 v87, v67, v67
	v_mul_f32_e32 v140, v86, v86
	v_fmac_f32_e32 v87, v65, v65
	v_fmac_f32_e32 v140, v88, v88
	v_add_f32_e32 v87, v87, v140
	v_mov_b32_e32 v140, 0
	v_cndmask_b32_e64 v65, v88, v65, s[70:71]
	v_add_f32_dpp v87, v87, v87 row_shr:1 row_mask:0xf bank_mask:0xf bound_ctrl:1
	v_cndmask_b32_e64 v67, v86, v67, s[70:71]
	s_nop 0
	v_add_f32_dpp v87, v87, v87 row_shr:2 row_mask:0xf bank_mask:0xf bound_ctrl:1
	s_nop 1
	v_add_f32_dpp v87, v87, v87 row_shr:4 row_mask:0xf bank_mask:0xf bound_ctrl:1
	s_nop 1
	v_add_f32_dpp v87, v87, v87 row_shr:8 row_mask:0xf bank_mask:0xf bound_ctrl:1
	s_nop 1
	v_mov_b32_dpp v140, v87 row_bcast:15 row_mask:0xa bank_mask:0xf
	v_add_f32_e32 v87, v87, v140
	v_mov_b32_e32 v140, 0
	s_nop 1
	v_mov_b32_dpp v140, v87 row_bcast:31 row_mask:0xc bank_mask:0xf
	v_add_f32_e32 v87, v87, v140
	s_nop 0
	v_readlane_b32 s82, v87, 63
	s_nop 1
	v_fma_f32 v87, s82, v242, v197
	v_rsq_f32_e32 v87, v87
	s_mov_b32 s82, 0x840b000
	v_add_co_u32_e32 v44, vcc, s82, v44
	v_mul_f32_e32 v65, v65, v87
	v_fma_f32 v65, v46, v65, v47
	v_mul_f32_e32 v67, v67, v87
	v_fma_f32 v67, v48, v67, v49
	v_cvt_pk_bf16_f32 v65, v65, v67
	ds_write_b16 v63, v65 offset:12
	ds_write_b16_d16_hi v63, v65 offset:16908
	v_addc_co_u32_e32 v45, vcc, 0, v45, vcc
	s_waitcnt vmcnt(0)
	v_mov_b32_e32 v65, v246
	v_mov_b32_e32 v67, v248
	v_mov_b32_e32 v86, v249
	v_lshlrev_b32_e32 v65, 16, v65
	v_mov_b32_e32 v44, v250
	v_lshlrev_b32_e32 v67, 16, v67
	v_lshlrev_b32_e32 v86, 16, v86
	v_add_f32_e32 v45, v65, v67
	v_lshlrev_b32_e32 v44, 16, v44
	v_add_f32_e32 v87, v86, v44
	v_add_f32_e32 v45, v45, v87
	v_mov_b32_e32 v87, 0
	s_nop 0
	v_add_f32_dpp v45, v45, v45 row_shr:1 row_mask:0xf bank_mask:0xf bound_ctrl:1
	s_nop 1
	v_add_f32_dpp v45, v45, v45 row_shr:2 row_mask:0xf bank_mask:0xf bound_ctrl:1
	s_nop 1
	v_add_f32_dpp v45, v45, v45 row_shr:4 row_mask:0xf bank_mask:0xf bound_ctrl:1
	s_nop 1
	v_add_f32_dpp v45, v45, v45 row_shr:8 row_mask:0xf bank_mask:0xf bound_ctrl:1
	s_nop 1
	v_mov_b32_dpp v87, v45 row_bcast:15 row_mask:0xa bank_mask:0xf
	v_add_f32_e32 v45, v45, v87
	v_mov_b32_e32 v87, 0
	s_nop 1
	v_mov_b32_dpp v87, v45 row_bcast:31 row_mask:0xc bank_mask:0xf
	v_add_f32_e32 v45, v45, v87
	s_nop 0
	v_readlane_b32 s82, v45, 63
	s_nop 1
	v_fmac_f32_e32 v67, s82, v241
	v_fmac_f32_e32 v44, s82, v241
	v_fmac_f32_e32 v65, s82, v241
	v_fmac_f32_e32 v86, s82, v241
	v_mul_f32_e32 v45, v67, v67
	v_mul_f32_e32 v87, v44, v44
	v_fmac_f32_e32 v45, v65, v65
	v_fmac_f32_e32 v87, v86, v86
	v_add_f32_e32 v45, v45, v87
	v_mov_b32_e32 v87, 0
	v_cndmask_b32_e64 v44, v44, v67, s[70:71]
	v_add_f32_dpp v45, v45, v45 row_shr:1 row_mask:0xf bank_mask:0xf bound_ctrl:1
	v_cndmask_b32_e64 v65, v86, v65, s[70:71]
	s_nop 0
	v_add_f32_dpp v45, v45, v45 row_shr:2 row_mask:0xf bank_mask:0xf bound_ctrl:1
	s_nop 1
	v_add_f32_dpp v45, v45, v45 row_shr:4 row_mask:0xf bank_mask:0xf bound_ctrl:1
	s_nop 1
	v_add_f32_dpp v45, v45, v45 row_shr:8 row_mask:0xf bank_mask:0xf bound_ctrl:1
	s_nop 1
	v_mov_b32_dpp v87, v45 row_bcast:15 row_mask:0xa bank_mask:0xf
	v_add_f32_e32 v45, v45, v87
	v_mov_b32_e32 v87, 0
	s_nop 1
	v_mov_b32_dpp v87, v45 row_bcast:31 row_mask:0xc bank_mask:0xf
	v_add_f32_e32 v45, v45, v87
	s_nop 0
	v_readlane_b32 s82, v45, 63
	s_nop 1
	v_fma_f32 v45, s82, v242, v197
	v_rsq_f32_e32 v45, v45
	s_nop 0
	v_mul_f32_e32 v44, v44, v45
	v_mul_f32_e32 v65, v65, v45
	v_fma_f32 v44, v48, v44, v49
	v_fma_f32 v65, v46, v65, v47
	v_cvt_pk_bf16_f32 v44, v65, v44
	ds_write_b16 v63, v44 offset:14
	ds_write_b16_d16_hi v63, v44 offset:16910
	v_add_u32_e32 v63, 16, v63
	s_cbranch_scc0 .LBB0_249
	s_lshl_b32 s70, s86, 6
	s_and_b32 s71, s70, 0xfc0
	s_sub_i32 s71, 29, s71
	v_cmp_lt_i32_e32 vcc, s71, v123
	v_mov_b64_e32 v[86:87], s[0:1]
	s_movk_i32 s82, 0x1000
	v_cndmask_b32_e32 v42, 0, v124, vcc
	v_add_u32_e32 v42, s70, v42
	v_mad_i64_i32 v[42:43], s[72:73], v42, s33, v[86:87]
	v_lshl_add_u64 v[42:43], v[42:43], 0, v[0:1]
	v_cndmask_b32_e64 v88, 0, 1.0, vcc
	v_add_co_u32_e32 v46, vcc, s82, v42
	v_mov_b32_e32 v67, v1
	s_nop 0
	v_addc_co_u32_e32 v47, vcc, 0, v43, vcc
	s_waitcnt vmcnt(0)
	v_mov_b32_e32 v42, v152
	v_mov_b32_e32 v43, v153
	v_mov_b32_e32 v44, v154
	v_mov_b32_e32 v45, v155
	v_mov_b32_e32 v46, v156
	v_mov_b32_e32 v47, v157
	v_mov_b32_e32 v48, v158
	v_mov_b32_e32 v49, v159
	v_cmp_lt_i32_e32 vcc, s71, v132
	s_nop 1
	v_cndmask_b32_e32 v160, 0, v133, vcc
	v_add_u32_e32 v160, s70, v160
	v_mad_i64_i32 v[160:161], vcc, v160, s33, v[176:177]
	v_add_co_u32_e32 v160, vcc, v160, v66
	s_nop 1
	v_addc_co_u32_e32 v161, vcc, 0, v161, vcc
	global_load_dwordx4 v[152:155], v[160:161], off offset:512
	global_load_dwordx4 v[156:159], v[160:161], off offset:1024
	v_cmp_lt_i32_e32 vcc, s71, v126
	v_add_u32_e32 v148, s77, v54
	v_ashrrev_i32_e32 v149, 31, v148
	s_add_i32 s86, s86, s97
	v_lshlrev_b32_e32 v142, 16, v42
	v_lshlrev_b32_e32 v63, 16, v46
	v_and_b32_e32 v46, 0xffff0000, v46
	v_and_b32_e32 v143, 0xffff0000, v42
	v_lshlrev_b32_e32 v42, 16, v47
	v_mul_f32_e32 v63, 0xbfb8aa3b, v63
	v_mul_f32_e32 v46, 0xbfb8aa3b, v46
	v_mul_f32_e32 v42, 0xbfb8aa3b, v42
	v_exp_f32_e32 v63, v63
	v_exp_f32_e32 v46, v46
	v_exp_f32_e32 v42, v42
	v_add_f32_e32 v63, 1.0, v63
	v_add_f32_e32 v46, 1.0, v46
	v_add_f32_e32 v42, 1.0, v42
	v_rcp_f32_e32 v140, v63
	v_rcp_f32_e32 v141, v46
	v_rcp_f32_e32 v46, v42
	v_and_b32_e32 v42, 0xffff0000, v47
	v_mul_f32_e32 v42, 0xbfb8aa3b, v42
	v_exp_f32_e32 v42, v42
	v_pk_mul_f32 v[140:141], v[140:141], v[142:143]
	v_lshlrev_b32_e32 v142, 16, v44
	v_and_b32_e32 v143, 0xffff0000, v44
	v_lshlrev_b32_e32 v44, 16, v49
	v_mul_f32_e32 v44, 0xbfb8aa3b, v44
	v_add_f32_e32 v42, 1.0, v42
	v_exp_f32_e32 v44, v44
	v_rcp_f32_e32 v47, v42
	v_lshlrev_b32_e32 v42, 16, v43
	v_and_b32_e32 v43, 0xffff0000, v43
	v_add_f32_e32 v44, 1.0, v44
	v_pk_mul_f32 v[42:43], v[46:47], v[42:43]
	v_lshlrev_b32_e32 v46, 16, v48
	v_and_b32_e32 v47, 0xffff0000, v48
	v_rcp_f32_e32 v48, v44
	v_and_b32_e32 v44, 0xffff0000, v49
	v_mul_f32_e32 v46, 0xbfb8aa3b, v46
	v_mul_f32_e32 v47, 0xbfb8aa3b, v47
	v_mul_f32_e32 v44, 0xbfb8aa3b, v44
	v_exp_f32_e32 v46, v46
	v_exp_f32_e32 v47, v47
	v_exp_f32_e32 v44, v44
	v_mov_b32_e32 v63, v1
	v_add_f32_e32 v46, 1.0, v46
	v_add_f32_e32 v47, 1.0, v47
	v_add_f32_e32 v44, 1.0, v44
	v_rcp_f32_e32 v46, v46
	v_rcp_f32_e32 v47, v47
	v_rcp_f32_e32 v49, v44
	v_lshlrev_b32_e32 v44, 16, v45
	v_and_b32_e32 v45, 0xffff0000, v45
	v_pk_mul_f32 v[46:47], v[46:47], v[142:143]
	v_pk_mul_f32 v[48:49], v[48:49], v[44:45]
	v_pk_mul_f32 v[44:45], v[88:89], v[42:43] op_sel_hi:[0,1]
	v_pk_mul_f32 v[42:43], v[88:89], v[140:141] op_sel_hi:[0,1]
	ds_write_b128 v125, v[42:45] offset:36864
	v_pk_mul_f32 v[44:45], v[88:89], v[48:49] op_sel_hi:[0,1]
	v_pk_mul_f32 v[42:43], v[88:89], v[46:47] op_sel_hi:[0,1]
	ds_write_b128 v125, v[42:45] offset:36880
	v_cndmask_b32_e32 v42, 0, v127, vcc
	v_add_u32_e32 v42, s70, v42
	v_mad_i64_i32 v[42:43], s[72:73], v42, s33, v[86:87]
	v_lshl_add_u64 v[42:43], v[42:43], 0, v[62:63]
	v_cndmask_b32_e64 v88, 0, 1.0, vcc
	v_add_co_u32_e32 v46, vcc, s82, v42
	s_nop 1
	v_addc_co_u32_e32 v47, vcc, 0, v43, vcc
	v_mov_b32_e32 v42, v168
	v_mov_b32_e32 v43, v169
	v_mov_b32_e32 v44, v170
	v_mov_b32_e32 v45, v171
	v_mov_b32_e32 v46, v172
	v_mov_b32_e32 v47, v173
	v_mov_b32_e32 v48, v174
	v_mov_b32_e32 v49, v175
	v_cmp_lt_i32_e32 vcc, s71, v129
	v_lshlrev_b32_e32 v142, 16, v42
	v_lshlrev_b32_e32 v65, 16, v46
	v_and_b32_e32 v46, 0xffff0000, v46
	v_and_b32_e32 v143, 0xffff0000, v42
	v_lshlrev_b32_e32 v42, 16, v47
	v_mul_f32_e32 v65, 0xbfb8aa3b, v65
	v_mul_f32_e32 v46, 0xbfb8aa3b, v46
	v_mul_f32_e32 v42, 0xbfb8aa3b, v42
	v_exp_f32_e32 v65, v65
	v_exp_f32_e32 v46, v46
	v_exp_f32_e32 v42, v42
	v_add_f32_e32 v65, 1.0, v65
	v_add_f32_e32 v46, 1.0, v46
	v_add_f32_e32 v42, 1.0, v42
	v_rcp_f32_e32 v140, v65
	v_rcp_f32_e32 v141, v46
	v_rcp_f32_e32 v46, v42
	v_and_b32_e32 v42, 0xffff0000, v47
	v_mul_f32_e32 v42, 0xbfb8aa3b, v42
	v_exp_f32_e32 v42, v42
	v_pk_mul_f32 v[140:141], v[140:141], v[142:143]
	v_lshlrev_b32_e32 v142, 16, v44
	v_and_b32_e32 v143, 0xffff0000, v44
	v_lshlrev_b32_e32 v44, 16, v49
	v_mul_f32_e32 v44, 0xbfb8aa3b, v44
	v_add_f32_e32 v42, 1.0, v42
	v_exp_f32_e32 v44, v44
	v_rcp_f32_e32 v47, v42
	v_lshlrev_b32_e32 v42, 16, v43
	v_and_b32_e32 v43, 0xffff0000, v43
	v_add_f32_e32 v44, 1.0, v44
	v_pk_mul_f32 v[42:43], v[46:47], v[42:43]
	v_lshlrev_b32_e32 v46, 16, v48
	v_and_b32_e32 v47, 0xffff0000, v48
	v_rcp_f32_e32 v48, v44
	v_and_b32_e32 v44, 0xffff0000, v49
	v_mul_f32_e32 v46, 0xbfb8aa3b, v46
	v_mul_f32_e32 v47, 0xbfb8aa3b, v47
	v_mul_f32_e32 v44, 0xbfb8aa3b, v44
	v_exp_f32_e32 v46, v46
	v_exp_f32_e32 v47, v47
	v_exp_f32_e32 v44, v44
	v_mov_b32_e32 v65, v1
	v_add_f32_e32 v46, 1.0, v46
	v_add_f32_e32 v47, 1.0, v47
	v_add_f32_e32 v44, 1.0, v44
	v_rcp_f32_e32 v46, v46
	v_rcp_f32_e32 v47, v47
	v_rcp_f32_e32 v49, v44
	v_lshlrev_b32_e32 v44, 16, v45
	v_and_b32_e32 v45, 0xffff0000, v45
	v_pk_mul_f32 v[46:47], v[46:47], v[142:143]
	v_pk_mul_f32 v[48:49], v[48:49], v[44:45]
	v_pk_mul_f32 v[44:45], v[88:89], v[42:43] op_sel_hi:[0,1]
	v_pk_mul_f32 v[42:43], v[88:89], v[140:141] op_sel_hi:[0,1]
	ds_write_b128 v128, v[42:45] offset:36864
	v_pk_mul_f32 v[44:45], v[88:89], v[48:49] op_sel_hi:[0,1]
	v_pk_mul_f32 v[42:43], v[88:89], v[46:47] op_sel_hi:[0,1]
	ds_write_b128 v128, v[42:45] offset:36880
	v_cndmask_b32_e32 v43, 0, v130, vcc
	v_add_u32_e32 v43, s70, v43
	v_mad_i64_i32 v[44:45], s[72:73], v43, s33, v[86:87]
	v_lshl_add_u64 v[44:45], v[44:45], 0, v[64:65]
	v_cndmask_b32_e64 v42, 0, 1.0, vcc
	v_add_co_u32_e32 v48, vcc, s82, v44
	s_nop 1
	v_addc_co_u32_e32 v49, vcc, 0, v45, vcc
	v_mov_b32_e32 v44, v182
	v_mov_b32_e32 v45, v183
	v_mov_b32_e32 v46, v184
	v_mov_b32_e32 v47, v185
	v_mov_b32_e32 v140, v186
	v_mov_b32_e32 v141, v187
	v_mov_b32_e32 v142, v188
	v_mov_b32_e32 v143, v189
	v_cmp_lt_i32_e32 vcc, s71, v132
	v_readlane_b32 s71, v255, 46
	v_lshlrev_b32_e32 v144, 16, v44
	v_lshlrev_b32_e32 v43, 16, v140
	v_mul_f32_e32 v43, 0xbfb8aa3b, v43
	v_exp_f32_e32 v43, v43
	v_and_b32_e32 v145, 0xffff0000, v44
	v_lshlrev_b32_e32 v44, 16, v45
	v_and_b32_e32 v45, 0xffff0000, v45
	v_add_f32_e32 v43, 1.0, v43
	v_rcp_f32_e32 v48, v43
	v_and_b32_e32 v43, 0xffff0000, v140
	v_mul_f32_e32 v43, 0xbfb8aa3b, v43
	v_exp_f32_e32 v43, v43
	v_cndmask_b32_e64 v88, 0, 1.0, vcc
	v_add_f32_e32 v43, 1.0, v43
	v_rcp_f32_e32 v49, v43
	v_lshlrev_b32_e32 v43, 16, v141
	v_mul_f32_e32 v43, 0xbfb8aa3b, v43
	v_exp_f32_e32 v43, v43
	v_pk_mul_f32 v[48:49], v[48:49], v[144:145]
	v_lshlrev_b32_e32 v144, 16, v46
	v_and_b32_e32 v145, 0xffff0000, v46
	v_add_f32_e32 v43, 1.0, v43
	v_rcp_f32_e32 v140, v43
	v_and_b32_e32 v43, 0xffff0000, v141
	v_mul_f32_e32 v43, 0xbfb8aa3b, v43
	v_exp_f32_e32 v43, v43
	v_lshlrev_b32_e32 v46, 16, v47
	v_and_b32_e32 v47, 0xffff0000, v47
	v_add_f32_e32 v43, 1.0, v43
	v_rcp_f32_e32 v141, v43
	v_lshlrev_b32_e32 v43, 16, v142
	v_mul_f32_e32 v43, 0xbfb8aa3b, v43
	v_exp_f32_e32 v43, v43
	v_pk_mul_f32 v[44:45], v[140:141], v[44:45]
	v_add_f32_e32 v43, 1.0, v43
	v_rcp_f32_e32 v140, v43
	v_and_b32_e32 v43, 0xffff0000, v142
	v_mul_f32_e32 v43, 0xbfb8aa3b, v43
	v_exp_f32_e32 v43, v43
	s_nop 0
	v_add_f32_e32 v43, 1.0, v43
	v_rcp_f32_e32 v141, v43
	v_lshlrev_b32_e32 v43, 16, v143
	v_mul_f32_e32 v43, 0xbfb8aa3b, v43
	v_exp_f32_e32 v43, v43
	v_pk_mul_f32 v[140:141], v[140:141], v[144:145]
	v_add_f32_e32 v43, 1.0, v43
	v_rcp_f32_e32 v142, v43
	v_and_b32_e32 v43, 0xffff0000, v143
	v_mul_f32_e32 v43, 0xbfb8aa3b, v43
	v_exp_f32_e32 v43, v43
	s_nop 0
	v_add_f32_e32 v43, 1.0, v43
	v_rcp_f32_e32 v143, v43
	s_nop 0
	v_pk_mul_f32 v[142:143], v[142:143], v[46:47]
	v_pk_mul_f32 v[46:47], v[42:43], v[44:45] op_sel_hi:[0,1]
	v_pk_mul_f32 v[44:45], v[42:43], v[48:49] op_sel_hi:[0,1]
	ds_write_b128 v131, v[44:47] offset:36864
	v_pk_mul_f32 v[44:45], v[42:43], v[142:143] op_sel_hi:[0,1]
	v_pk_mul_f32 v[42:43], v[42:43], v[140:141] op_sel_hi:[0,1]
	ds_write_b128 v131, v[42:45] offset:36880
	v_cndmask_b32_e32 v42, 0, v133, vcc
	v_add_u32_e32 v42, s70, v42
	v_mad_i64_i32 v[42:43], s[72:73], v42, s33, v[86:87]
	v_lshl_add_u64 v[42:43], v[42:43], 0, v[66:67]
	v_add_co_u32_e32 v46, vcc, s82, v42
	v_readlane_b32 s72, v255, 30
	s_nop 0
	v_addc_co_u32_e32 v47, vcc, 0, v43, vcc
	s_waitcnt vmcnt(0)
	v_mov_b32_e32 v42, v152
	v_mov_b32_e32 v43, v153
	v_mov_b32_e32 v44, v154
	v_mov_b32_e32 v45, v155
	v_mov_b32_e32 v46, v156
	v_mov_b32_e32 v47, v157
	v_mov_b32_e32 v48, v158
	v_mov_b32_e32 v49, v159
	v_readlane_b32 s73, v255, 31
	v_lshlrev_b32_e32 v142, 16, v42
	v_lshlrev_b32_e32 v140, 16, v46
	v_and_b32_e32 v46, 0xffff0000, v46
	v_and_b32_e32 v143, 0xffff0000, v42
	v_lshlrev_b32_e32 v42, 16, v47
	v_mul_f32_e32 v140, 0xbfb8aa3b, v140
	v_mul_f32_e32 v46, 0xbfb8aa3b, v46
	v_mul_f32_e32 v42, 0xbfb8aa3b, v42
	v_exp_f32_e32 v140, v140
	v_exp_f32_e32 v46, v46
	v_exp_f32_e32 v42, v42
	v_add_f32_e32 v140, 1.0, v140
	v_add_f32_e32 v46, 1.0, v46
	v_add_f32_e32 v42, 1.0, v42
	v_rcp_f32_e32 v140, v140
	v_rcp_f32_e32 v141, v46
	v_rcp_f32_e32 v46, v42
	v_and_b32_e32 v42, 0xffff0000, v47
	v_mul_f32_e32 v42, 0xbfb8aa3b, v42
	v_exp_f32_e32 v42, v42
	v_pk_mul_f32 v[140:141], v[140:141], v[142:143]
	v_lshlrev_b32_e32 v142, 16, v44
	v_and_b32_e32 v143, 0xffff0000, v44
	v_lshlrev_b32_e32 v44, 16, v49
	v_mul_f32_e32 v44, 0xbfb8aa3b, v44
	v_add_f32_e32 v42, 1.0, v42
	v_exp_f32_e32 v44, v44
	v_rcp_f32_e32 v47, v42
	v_lshlrev_b32_e32 v42, 16, v43
	v_and_b32_e32 v43, 0xffff0000, v43
	v_add_f32_e32 v44, 1.0, v44
	v_pk_mul_f32 v[42:43], v[46:47], v[42:43]
	v_lshlrev_b32_e32 v46, 16, v48
	v_and_b32_e32 v47, 0xffff0000, v48
	v_rcp_f32_e32 v48, v44
	v_and_b32_e32 v44, 0xffff0000, v49
	v_mul_f32_e32 v46, 0xbfb8aa3b, v46
	v_mul_f32_e32 v47, 0xbfb8aa3b, v47
	v_mul_f32_e32 v44, 0xbfb8aa3b, v44
	v_exp_f32_e32 v46, v46
	v_exp_f32_e32 v47, v47
	v_exp_f32_e32 v44, v44
	v_add_f32_e32 v46, 1.0, v46
	v_add_f32_e32 v47, 1.0, v47
	v_add_f32_e32 v44, 1.0, v44
	v_rcp_f32_e32 v46, v46
	v_rcp_f32_e32 v47, v47
	v_rcp_f32_e32 v49, v44
	v_lshlrev_b32_e32 v44, 16, v45
	v_and_b32_e32 v45, 0xffff0000, v45
	v_pk_mul_f32 v[46:47], v[46:47], v[142:143]
	v_pk_mul_f32 v[48:49], v[48:49], v[44:45]
	v_pk_mul_f32 v[44:45], v[88:89], v[42:43] op_sel_hi:[0,1]
	v_pk_mul_f32 v[42:43], v[88:89], v[140:141] op_sel_hi:[0,1]
	ds_write_b128 v134, v[42:45] offset:36864
	v_pk_mul_f32 v[44:45], v[88:89], v[48:49] op_sel_hi:[0,1]
	v_pk_mul_f32 v[42:43], v[88:89], v[46:47] op_sel_hi:[0,1]
	v_add_u32_e32 v46, 0x1080, v135
	v_add_u32_e32 v88, 0x2100, v135
	ds_write_b128 v134, v[42:45] offset:36880
	s_waitcnt lgkmcnt(0)
	s_barrier
	v_lshlrev_b64 v[42:43], 11, v[76:77]
	ds_read2_b64 v[46:49], v46 offset1:1
	ds_read2_b64 v[140:143], v88 offset1:1
	v_add_u32_e32 v88, 0x3180, v135
	v_lshl_add_u64 v[76:77], s[72:73], 0, v[42:43]
	ds_read2_b64 v[42:45], v135 offset1:1
	ds_read2_b64 v[144:147], v88 offset1:1
	s_waitcnt lgkmcnt(1)
	v_mfma_f32_16x16x32_bf16 v[42:45], v[42:45], v[10:13], 0
	v_add_u32_e32 v88, 0x10c0, v135
	s_add_i32 s72, s70, s84
	s_ashr_i32 s73, s72, 31
	v_mfma_f32_16x16x32_bf16 v[46:49], v[46:49], v[10:13], 0
	s_lshl_b64 s[72:73], s[72:73], 11
	v_mfma_f32_16x16x32_bf16 v[140:143], v[140:143], v[10:13], 0
	s_waitcnt lgkmcnt(0)
	v_mfma_f32_16x16x32_bf16 v[10:13], v[144:147], v[10:13], 0
	ds_read2_b64 v[144:147], v135 offset0:8 offset1:9
	s_waitcnt lgkmcnt(0)
	v_mfma_f32_16x16x32_bf16 v[42:45], v[144:147], v[14:17], v[42:45]
	ds_read2_b64 v[144:147], v88 offset1:1
	v_add_u32_e32 v88, 0x2140, v135
	s_waitcnt lgkmcnt(0)
	v_mfma_f32_16x16x32_bf16 v[46:49], v[144:147], v[14:17], v[46:49]
	ds_read2_b64 v[144:147], v88 offset1:1
	v_add_u32_e32 v88, 0x31c0, v135
	s_waitcnt lgkmcnt(0)
	v_mfma_f32_16x16x32_bf16 v[140:143], v[144:147], v[14:17], v[140:143]
	ds_read2_b64 v[144:147], v88 offset1:1
	v_add_u32_e32 v88, 0x3200, v135
	s_waitcnt lgkmcnt(0)
	v_mfma_f32_16x16x32_bf16 v[10:13], v[144:147], v[14:17], v[10:13]
	ds_read2_b64 v[14:17], v135 offset0:16 offset1:17
	s_waitcnt lgkmcnt(0)
	v_mfma_f32_16x16x32_bf16 v[14:17], v[14:17], v[18:21], v[42:45]
	s_nop 2
	v_add_u32_e32 v42, 0x1100, v135
	ds_read2_b64 v[42:45], v42 offset1:1
	s_waitcnt lgkmcnt(0)
	v_mfma_f32_16x16x32_bf16 v[42:45], v[42:45], v[18:21], v[46:49]
	s_nop 2
	v_add_u32_e32 v46, 0x2180, v135
	ds_read2_b64 v[46:49], v46 offset1:1
	s_waitcnt lgkmcnt(0)
	v_mfma_f32_16x16x32_bf16 v[46:49], v[46:49], v[18:21], v[140:143]
	s_nop 2
	ds_read2_b64 v[140:143], v88 offset1:1
	s_waitcnt lgkmcnt(0)
	v_mfma_f32_16x16x32_bf16 v[10:13], v[140:143], v[18:21], v[10:13]
	ds_read2_b64 v[18:21], v135 offset0:24 offset1:25
	s_waitcnt lgkmcnt(0)
	v_mfma_f32_16x16x32_bf16 v[14:17], v[18:21], v[26:29], v[14:17]
	v_add_u32_e32 v18, 0x1140, v135
	ds_read2_b64 v[18:21], v18 offset1:1
	s_waitcnt lgkmcnt(0)
	v_mfma_f32_16x16x32_bf16 v[18:21], v[18:21], v[26:29], v[42:45]
	s_nop 2
	v_add_u32_e32 v42, 0x21c0, v135
	ds_read2_b64 v[42:45], v42 offset1:1
	s_waitcnt lgkmcnt(0)
	v_mfma_f32_16x16x32_bf16 v[42:45], v[42:45], v[26:29], v[46:49]
	s_nop 2
	v_add_u32_e32 v46, 0x3240, v135
	ds_read2_b64 v[46:49], v46 offset1:1
	s_waitcnt lgkmcnt(0)
	v_mfma_f32_16x16x32_bf16 v[26:29], v[46:49], v[26:29], v[10:13]
	s_nop 2
	v_add_f32_e32 v10, v138, v14
	v_lshlrev_b32_e32 v11, 16, v74
	v_mul_f32_e32 v10, v10, v11
	v_add_f32_e32 v11, v138, v15
	v_and_b32_e32 v12, 0xffff0000, v74
	v_mul_f32_e32 v11, v11, v12
	v_cvt_pk_bf16_f32 v12, v10, v11
	v_add_f32_e32 v10, v138, v16
	v_lshlrev_b32_e32 v11, 16, v75
	v_mul_f32_e32 v10, v10, v11
	v_add_f32_e32 v11, v138, v17
	v_and_b32_e32 v13, 0xffff0000, v75
	v_mul_f32_e32 v11, v11, v13
	v_cvt_pk_bf16_f32 v13, v10, v11
	v_lshl_add_u64 v[10:11], v[148:149], 1, v[76:77]
	global_store_dwordx2 v[10:11], v[12:13], off offset:512
	v_add_f32_e32 v12, v138, v18
	v_lshlrev_b32_e32 v13, 16, v72
	v_mul_f32_e32 v12, v12, v13
	v_add_f32_e32 v13, v138, v19
	v_and_b32_e32 v14, 0xffff0000, v72
	v_mul_f32_e32 v13, v13, v14
	v_cvt_pk_bf16_f32 v12, v12, v13
	v_add_f32_e32 v13, v138, v20
	v_lshlrev_b32_e32 v14, 16, v73
	v_mul_f32_e32 v13, v13, v14
	v_add_f32_e32 v14, v138, v21
	v_and_b32_e32 v15, 0xffff0000, v73
	v_mul_f32_e32 v14, v14, v15
	v_cvt_pk_bf16_f32 v13, v13, v14
	global_store_dwordx2 v[10:11], v[12:13], off offset:544
	v_add_f32_e32 v12, v138, v42
	v_lshlrev_b32_e32 v13, 16, v70
	v_mul_f32_e32 v12, v12, v13
	v_add_f32_e32 v13, v138, v43
	v_and_b32_e32 v14, 0xffff0000, v70
	v_mul_f32_e32 v13, v13, v14
	v_cvt_pk_bf16_f32 v12, v12, v13
	v_add_f32_e32 v13, v138, v44
	v_lshlrev_b32_e32 v14, 16, v71
	v_mul_f32_e32 v13, v13, v14
	v_add_f32_e32 v14, v138, v45
	v_and_b32_e32 v15, 0xffff0000, v71
	v_mul_f32_e32 v14, v14, v15
	v_cvt_pk_bf16_f32 v13, v13, v14
	global_store_dwordx2 v[10:11], v[12:13], off offset:576
	v_add_f32_e32 v12, v138, v26
	v_lshlrev_b32_e32 v13, 16, v68
	v_mul_f32_e32 v12, v12, v13
	v_add_f32_e32 v13, v138, v27
	v_and_b32_e32 v14, 0xffff0000, v68
	v_mul_f32_e32 v13, v13, v14
	v_cvt_pk_bf16_f32 v12, v12, v13
	v_add_f32_e32 v13, v138, v28
	v_lshlrev_b32_e32 v14, 16, v69
	v_mul_f32_e32 v13, v13, v14
	v_add_f32_e32 v14, v138, v29
	v_and_b32_e32 v15, 0xffff0000, v69
	v_add_u32_e32 v20, 0x6300, v135
	v_mul_f32_e32 v14, v14, v15
	v_cvt_pk_bf16_f32 v13, v13, v14
	global_store_dwordx2 v[10:11], v[12:13], off offset:608
	v_add_u32_e32 v12, 0x4200, v135
	v_add_u32_e32 v16, 0x5280, v135
	ds_read2_b64 v[26:29], v20 offset1:1
	v_add_u32_e32 v20, 0x7380, v135
	ds_read2_b64 v[12:15], v12 offset1:1
	ds_read2_b64 v[16:19], v16 offset1:1
	ds_read2_b64 v[42:45], v20 offset1:1
	s_waitcnt lgkmcnt(2)
	v_mfma_f32_16x16x32_bf16 v[12:15], v[12:15], v[22:25], 0
	s_waitcnt lgkmcnt(1)
	v_mfma_f32_16x16x32_bf16 v[16:19], v[16:19], v[22:25], 0
	v_mfma_f32_16x16x32_bf16 v[26:29], v[26:29], v[22:25], 0
	s_waitcnt lgkmcnt(0)
	v_mfma_f32_16x16x32_bf16 v[20:23], v[42:45], v[22:25], 0
	v_add_u32_e32 v24, 0x4240, v135
	ds_read2_b64 v[42:45], v24 offset1:1
	v_add_u32_e32 v24, 0x52c0, v135
	s_waitcnt lgkmcnt(0)
	v_mfma_f32_16x16x32_bf16 v[12:15], v[42:45], v[30:33], v[12:15]
	ds_read2_b64 v[42:45], v24 offset1:1
	v_add_u32_e32 v24, 0x6340, v135
	s_waitcnt lgkmcnt(0)
	v_mfma_f32_16x16x32_bf16 v[16:19], v[42:45], v[30:33], v[16:19]
	ds_read2_b64 v[42:45], v24 offset1:1
	s_waitcnt lgkmcnt(0)
	v_mfma_f32_16x16x32_bf16 v[24:27], v[42:45], v[30:33], v[26:29]
	s_nop 2
	v_add_u32_e32 v28, 0x73c0, v135
	ds_read2_b64 v[42:45], v28 offset1:1
	v_add_u32_e32 v28, 0x4280, v135
	s_waitcnt lgkmcnt(0)
	v_mfma_f32_16x16x32_bf16 v[20:23], v[42:45], v[30:33], v[20:23]
	ds_read2_b64 v[28:31], v28 offset1:1
	s_waitcnt lgkmcnt(0)
	v_mfma_f32_16x16x32_bf16 v[12:15], v[28:31], v[34:37], v[12:15]
	v_add_u32_e32 v28, 0x5300, v135
	ds_read2_b64 v[28:31], v28 offset1:1
	s_waitcnt lgkmcnt(0)
	v_mfma_f32_16x16x32_bf16 v[16:19], v[28:31], v[34:37], v[16:19]
	v_add_u32_e32 v28, 0x6380, v135
	ds_read2_b64 v[28:31], v28 offset1:1
	s_waitcnt lgkmcnt(0)
	v_mfma_f32_16x16x32_bf16 v[24:27], v[28:31], v[34:37], v[24:27]
	v_add_u32_e32 v28, 0x7400, v135
	ds_read2_b64 v[28:31], v28 offset1:1
	s_waitcnt lgkmcnt(0)
	v_mfma_f32_16x16x32_bf16 v[20:23], v[28:31], v[34:37], v[20:23]
	v_add_u32_e32 v28, 0x42c0, v135
	ds_read2_b64 v[28:31], v28 offset1:1
	s_waitcnt lgkmcnt(0)
	v_mfma_f32_16x16x32_bf16 v[12:15], v[28:31], v[38:41], v[12:15]
	v_add_u32_e32 v28, 0x5340, v135
	ds_read2_b64 v[28:31], v28 offset1:1
	s_nop 5
	v_add_f32_e32 v12, v139, v12
	s_waitcnt lgkmcnt(0)
	v_mfma_f32_16x16x32_bf16 v[16:19], v[28:31], v[38:41], v[16:19]
	v_add_u32_e32 v28, 0x63c0, v135
	ds_read2_b64 v[28:31], v28 offset1:1
	v_add_f32_e32 v13, v139, v13
	s_waitcnt lgkmcnt(0)
	v_mfma_f32_16x16x32_bf16 v[24:27], v[28:31], v[38:41], v[24:27]
	v_add_u32_e32 v28, 0x7440, v135
	ds_read2_b64 v[28:31], v28 offset1:1
	s_waitcnt lgkmcnt(0)
	v_mfma_f32_16x16x32_bf16 v[20:23], v[28:31], v[38:41], v[20:23]
	v_lshlrev_b32_e32 v28, 16, v84
	v_mul_f32_e32 v12, v12, v28
	v_and_b32_e32 v28, 0xffff0000, v84
	v_mul_f32_e32 v13, v13, v28
	v_cvt_pk_bf16_f32 v12, v12, v13
	v_add_f32_e32 v13, v139, v14
	v_lshlrev_b32_e32 v14, 16, v85
	v_mul_f32_e32 v13, v13, v14
	v_add_f32_e32 v14, v139, v15
	v_and_b32_e32 v15, 0xffff0000, v85
	v_mul_f32_e32 v14, v14, v15
	v_cvt_pk_bf16_f32 v13, v13, v14
	global_store_dwordx2 v[10:11], v[12:13], off offset:640
	v_add_f32_e32 v12, v139, v16
	v_lshlrev_b32_e32 v13, 16, v82
	v_mul_f32_e32 v12, v12, v13
	v_add_f32_e32 v13, v139, v17
	v_and_b32_e32 v14, 0xffff0000, v82
	v_mul_f32_e32 v13, v13, v14
	v_cvt_pk_bf16_f32 v12, v12, v13
	v_add_f32_e32 v13, v139, v18
	v_lshlrev_b32_e32 v14, 16, v83
	v_mul_f32_e32 v13, v13, v14
	v_add_f32_e32 v14, v139, v19
	v_and_b32_e32 v15, 0xffff0000, v83
	v_mul_f32_e32 v14, v14, v15
	v_cvt_pk_bf16_f32 v13, v13, v14
	global_store_dwordx2 v[10:11], v[12:13], off offset:672
	v_add_f32_e32 v12, v139, v24
	v_lshlrev_b32_e32 v13, 16, v80
	v_mul_f32_e32 v12, v12, v13
	v_add_f32_e32 v13, v139, v25
	v_and_b32_e32 v14, 0xffff0000, v80
	v_mul_f32_e32 v13, v13, v14
	v_cvt_pk_bf16_f32 v12, v12, v13
	v_add_f32_e32 v13, v139, v26
	v_lshlrev_b32_e32 v14, 16, v81
	v_mul_f32_e32 v13, v13, v14
	v_add_f32_e32 v14, v139, v27
	v_and_b32_e32 v15, 0xffff0000, v81
	v_mul_f32_e32 v14, v14, v15
	v_cvt_pk_bf16_f32 v13, v13, v14
	global_store_dwordx2 v[10:11], v[12:13], off offset:704
	v_add_f32_e32 v12, v139, v20
	v_lshlrev_b32_e32 v13, 16, v78
	v_mul_f32_e32 v12, v12, v13
	v_add_f32_e32 v13, v139, v21
	v_and_b32_e32 v14, 0xffff0000, v78
	v_mul_f32_e32 v13, v13, v14
	v_cvt_pk_bf16_f32 v12, v12, v13
	v_add_f32_e32 v13, v139, v22
	v_lshlrev_b32_e32 v14, 16, v79
	v_mul_f32_e32 v13, v13, v14
	v_add_f32_e32 v14, v139, v23
	v_and_b32_e32 v15, 0xffff0000, v79
	v_mul_f32_e32 v14, v14, v15
	v_cvt_pk_bf16_f32 v13, v13, v14
	global_store_dwordx2 v[10:11], v[12:13], off offset:736
	ds_read2st64_b32 v[10:11], v136 offset0:144 offset1:148
	ds_read2st64_b32 v[12:13], v136 offset0:180 offset1:184
	ds_read2st64_b32 v[14:15], v136 offset0:184 offset1:188
	ds_read2st64_b32 v[16:17], v136 offset0:188 offset1:192
	ds_read2st64_b32 v[18:19], v136 offset0:192 offset1:196
	s_waitcnt lgkmcnt(4)
	v_fma_f32 v46, v116, v10, v120
	v_fmac_f32_e32 v46, v117, v11
	v_fma_f32 v47, v116, v11, v120
	ds_read2st64_b32 v[10:11], v136 offset0:152 offset1:156
	ds_read2st64_b32 v[20:21], v136 offset0:196 offset1:200
	ds_read2st64_b32 v[22:23], v136 offset0:200 offset1:204
	ds_read2st64_b32 v[24:25], v136 offset0:204 offset1:208
	ds_read2st64_b32 v[26:27], v136 offset0:212 offset1:216
	s_waitcnt lgkmcnt(4)
	v_fmac_f32_e32 v46, v118, v10
	v_fmac_f32_e32 v47, v117, v10
	v_fma_f32 v48, v116, v10, v120
	v_fmac_f32_e32 v46, v119, v11
	v_fmac_f32_e32 v47, v118, v11
	v_fmac_f32_e32 v48, v117, v11
	v_fma_f32 v49, v116, v11, v120
	ds_read2st64_b32 v[10:11], v136 offset0:160 offset1:164
	ds_read2st64_b32 v[28:29], v136 offset0:220 offset1:224
	ds_read2st64_b32 v[30:31], v136 offset0:228 offset1:232
	ds_read2st64_b32 v[32:33], v136 offset0:236 offset1:240
	ds_read2st64_b32 v[34:35], v136 offset0:244 offset1:248
	s_waitcnt lgkmcnt(4)
	v_fmac_f32_e32 v46, v89, v10
	v_fmac_f32_e32 v47, v119, v10
	v_fmac_f32_e32 v48, v118, v10
	v_fmac_f32_e32 v49, v117, v10
	v_fma_f32 v68, v116, v10, v120
	v_fmac_f32_e32 v46, v97, v11
	v_fmac_f32_e32 v47, v89, v11
	v_fmac_f32_e32 v48, v119, v11
	v_fmac_f32_e32 v49, v118, v11
	v_fmac_f32_e32 v68, v117, v11
	v_fma_f32 v69, v116, v11, v120
	ds_read2st64_b32 v[10:11], v136 offset0:168 offset1:172
	ds_read2st64_b32 v[36:37], v137 offset0:112 offset1:116
	ds_read2st64_b32 v[38:39], v137 offset0:120 offset1:124
	ds_read2st64_b32 v[40:41], v137 offset0:128 offset1:132
	ds_read2st64_b32 v[42:43], v137 offset0:136 offset1:140
	s_waitcnt lgkmcnt(4)
	v_fmac_f32_e32 v46, v98, v10
	v_fmac_f32_e32 v47, v97, v10
	v_fmac_f32_e32 v48, v89, v10
	v_fmac_f32_e32 v49, v119, v10
	v_fmac_f32_e32 v68, v118, v10
	v_fmac_f32_e32 v69, v117, v10
	v_fma_f32 v70, v116, v10, v120
	v_fmac_f32_e32 v46, v99, v11
	v_fmac_f32_e32 v47, v98, v11
	v_fmac_f32_e32 v48, v97, v11
	v_fmac_f32_e32 v49, v89, v11
	v_fmac_f32_e32 v68, v119, v11
	v_fmac_f32_e32 v69, v118, v11
	v_fmac_f32_e32 v70, v117, v11
	v_fma_f32 v71, v116, v11, v120
	ds_read2st64_b32 v[10:11], v136 offset0:176 offset1:180
	ds_read2st64_b32 v[44:45], v137 offset0:144 offset1:148
	s_waitcnt lgkmcnt(1)
	v_fmac_f32_e32 v71, v117, v10
	v_fmac_f32_e32 v70, v118, v10
	v_fmac_f32_e32 v71, v118, v11
	v_fmac_f32_e32 v69, v119, v10
	v_fmac_f32_e32 v70, v119, v11
	v_fmac_f32_e32 v71, v119, v13
	v_fmac_f32_e32 v68, v89, v10
	v_fmac_f32_e32 v69, v89, v11
	v_fmac_f32_e32 v70, v89, v13
	v_fmac_f32_e32 v71, v89, v15
	v_fmac_f32_e32 v49, v97, v10
	v_fmac_f32_e32 v68, v97, v11
	v_fmac_f32_e32 v69, v97, v13
	v_fmac_f32_e32 v70, v97, v15
	v_fmac_f32_e32 v71, v97, v17
	v_fmac_f32_e32 v46, v90, v10
	v_fmac_f32_e32 v47, v99, v10
	v_fmac_f32_e32 v48, v98, v10
	v_fmac_f32_e32 v49, v98, v11
	v_fmac_f32_e32 v68, v98, v13
	v_fmac_f32_e32 v69, v98, v15
	v_fmac_f32_e32 v70, v98, v17
	v_fmac_f32_e32 v71, v98, v19
	v_fmac_f32_e32 v46, v91, v11
	v_fmac_f32_e32 v47, v90, v11
	v_fmac_f32_e32 v48, v99, v11
	v_fmac_f32_e32 v49, v99, v13
	v_fmac_f32_e32 v68, v99, v15
	v_fmac_f32_e32 v69, v99, v17
	v_fmac_f32_e32 v70, v99, v19
	v_fmac_f32_e32 v71, v99, v21
	v_fma_f32 v10, v116, v10, v120
	v_fma_f32 v11, v116, v12, v120
	v_fmac_f32_e32 v47, v91, v13
	v_fmac_f32_e32 v48, v90, v13
	v_fmac_f32_e32 v49, v90, v15
	v_fmac_f32_e32 v68, v90, v17
	v_fmac_f32_e32 v69, v90, v19
	v_fmac_f32_e32 v70, v90, v21
	v_fmac_f32_e32 v71, v90, v23
	v_fmac_f32_e32 v10, v117, v12
	v_fmac_f32_e32 v11, v117, v14
	v_fma_f32 v12, v116, v14, v120
	v_fmac_f32_e32 v46, v92, v13
	v_fmac_f32_e32 v47, v92, v15
	v_fmac_f32_e32 v48, v91, v15
	v_fmac_f32_e32 v49, v91, v17
	v_fmac_f32_e32 v68, v91, v19
	v_fmac_f32_e32 v69, v91, v21
	v_fmac_f32_e32 v70, v91, v23
	v_fmac_f32_e32 v71, v91, v25
	v_fmac_f32_e32 v10, v118, v14
	v_fmac_f32_e32 v11, v118, v16
	v_fmac_f32_e32 v12, v117, v16
	v_fma_f32 v13, v116, v16, v120
	v_fmac_f32_e32 v46, v93, v15
	v_fmac_f32_e32 v47, v93, v17
	v_fmac_f32_e32 v48, v92, v17
	v_fmac_f32_e32 v49, v92, v19
	v_fmac_f32_e32 v68, v92, v21
	v_fmac_f32_e32 v69, v92, v23
	v_fmac_f32_e32 v70, v92, v25
	v_fmac_f32_e32 v71, v92, v26
	v_fmac_f32_e32 v10, v119, v16
	v_fmac_f32_e32 v11, v119, v18
	v_fmac_f32_e32 v12, v118, v18
	v_fmac_f32_e32 v13, v117, v18
	v_fma_f32 v14, v116, v18, v120
	v_fmac_f32_e32 v46, v94, v17
	v_fmac_f32_e32 v47, v94, v19
	v_fmac_f32_e32 v48, v93, v19
	v_fmac_f32_e32 v49, v93, v21
	v_fmac_f32_e32 v68, v93, v23
	v_fmac_f32_e32 v69, v93, v25
	v_fmac_f32_e32 v70, v93, v26
	v_fmac_f32_e32 v71, v93, v27
	v_fmac_f32_e32 v10, v89, v18
	v_fmac_f32_e32 v11, v89, v20
	v_fmac_f32_e32 v12, v119, v20
	v_fmac_f32_e32 v13, v118, v20
	v_fmac_f32_e32 v14, v117, v20
	v_fma_f32 v15, v116, v20, v120
	v_fmac_f32_e32 v46, v100, v19
	v_fmac_f32_e32 v47, v100, v21
	v_fmac_f32_e32 v48, v94, v21
	v_fmac_f32_e32 v49, v94, v23
	v_fmac_f32_e32 v68, v94, v25
	v_fmac_f32_e32 v69, v94, v26
	v_fmac_f32_e32 v70, v94, v27
	v_fmac_f32_e32 v71, v94, v28
	v_fmac_f32_e32 v10, v97, v20
	v_fmac_f32_e32 v11, v97, v22
	v_fmac_f32_e32 v12, v89, v22
	v_fmac_f32_e32 v13, v119, v22
	v_fmac_f32_e32 v14, v118, v22
	v_fmac_f32_e32 v15, v117, v22
	v_fma_f32 v16, v116, v22, v120
	v_fmac_f32_e32 v46, v101, v21
	v_fmac_f32_e32 v47, v101, v23
	v_fmac_f32_e32 v48, v100, v23
	v_fmac_f32_e32 v49, v100, v25
	v_fmac_f32_e32 v68, v100, v26
	v_fmac_f32_e32 v69, v100, v27
	v_fmac_f32_e32 v70, v100, v28
	v_fmac_f32_e32 v71, v100, v29
	v_fmac_f32_e32 v10, v98, v22
	v_fmac_f32_e32 v11, v98, v24
	v_fmac_f32_e32 v12, v97, v24
	v_fmac_f32_e32 v13, v89, v24
	v_fmac_f32_e32 v14, v119, v24
	v_fmac_f32_e32 v15, v118, v24
	v_fmac_f32_e32 v16, v117, v24
	v_fma_f32 v18, v116, v24, v120
	v_fmac_f32_e32 v46, v102, v23
	v_fmac_f32_e32 v47, v102, v25
	v_fmac_f32_e32 v48, v101, v25
	v_fmac_f32_e32 v49, v101, v26
	v_fmac_f32_e32 v68, v101, v27
	v_fmac_f32_e32 v69, v101, v28
	v_fmac_f32_e32 v70, v101, v29
	v_fmac_f32_e32 v71, v101, v30
	v_fmac_f32_e32 v10, v99, v24
	v_fmac_f32_e32 v11, v99, v25
	v_fmac_f32_e32 v12, v98, v25
	v_fmac_f32_e32 v13, v97, v25
	v_fmac_f32_e32 v14, v89, v25
	v_fmac_f32_e32 v15, v119, v25
	v_fmac_f32_e32 v16, v118, v25
	v_fmac_f32_e32 v18, v117, v25
	v_fmac_f32_e32 v46, v95, v25
	v_fmac_f32_e32 v47, v95, v26
	v_fmac_f32_e32 v48, v102, v26
	v_fmac_f32_e32 v49, v102, v27
	v_fmac_f32_e32 v68, v102, v28
	v_fmac_f32_e32 v69, v102, v29
	v_fmac_f32_e32 v70, v102, v30
	v_fmac_f32_e32 v71, v102, v31
	ds_read_b32 v17, v136 offset:64512
	v_fmac_f32_e32 v10, v90, v25
	v_fmac_f32_e32 v11, v90, v26
	v_fmac_f32_e32 v12, v99, v26
	v_fmac_f32_e32 v13, v98, v26
	v_fmac_f32_e32 v14, v97, v26
	v_fmac_f32_e32 v15, v89, v26
	v_fmac_f32_e32 v16, v119, v26
	v_fmac_f32_e32 v18, v118, v26
	v_fmac_f32_e32 v46, v96, v26
	v_fmac_f32_e32 v47, v96, v27
	v_fmac_f32_e32 v48, v95, v27
	v_fmac_f32_e32 v49, v95, v28
	v_fmac_f32_e32 v68, v95, v29
	v_fmac_f32_e32 v69, v95, v30
	v_fmac_f32_e32 v70, v95, v31
	v_fmac_f32_e32 v71, v95, v32
	v_fmac_f32_e32 v10, v91, v26
	v_fmac_f32_e32 v11, v91, v27
	v_fmac_f32_e32 v12, v90, v27
	v_fmac_f32_e32 v13, v99, v27
	v_fmac_f32_e32 v14, v98, v27
	v_fmac_f32_e32 v15, v97, v27
	v_fmac_f32_e32 v16, v89, v27
	v_fmac_f32_e32 v18, v119, v27
	v_fmac_f32_e32 v46, v105, v27
	v_fmac_f32_e32 v47, v105, v28
	v_fmac_f32_e32 v48, v96, v28
	v_fmac_f32_e32 v49, v96, v29
	v_fmac_f32_e32 v68, v96, v30
	v_fmac_f32_e32 v69, v96, v31
	v_fmac_f32_e32 v70, v96, v32
	v_fmac_f32_e32 v71, v96, v33
	v_fmac_f32_e32 v10, v92, v27
	v_fmac_f32_e32 v11, v92, v28
	v_fmac_f32_e32 v12, v91, v28
	v_fmac_f32_e32 v13, v90, v28
	v_fmac_f32_e32 v14, v99, v28
	v_fmac_f32_e32 v15, v98, v28
	v_fmac_f32_e32 v16, v97, v28
	v_fmac_f32_e32 v18, v89, v28
	v_fmac_f32_e32 v46, v106, v28
	v_fmac_f32_e32 v47, v106, v29
	v_fmac_f32_e32 v48, v105, v29
	v_fmac_f32_e32 v49, v105, v30
	v_fmac_f32_e32 v68, v105, v31
	v_fmac_f32_e32 v69, v105, v32
	v_fmac_f32_e32 v70, v105, v33
	v_fmac_f32_e32 v71, v105, v34
	v_fmac_f32_e32 v10, v93, v28
	v_fmac_f32_e32 v11, v93, v29
	v_fmac_f32_e32 v12, v92, v29
	v_fmac_f32_e32 v13, v91, v29
	v_fmac_f32_e32 v14, v90, v29
	v_fmac_f32_e32 v15, v99, v29
	v_fmac_f32_e32 v16, v98, v29
	v_fmac_f32_e32 v18, v97, v29
	v_fmac_f32_e32 v46, v107, v29
	v_fmac_f32_e32 v47, v107, v30
	v_fmac_f32_e32 v48, v106, v30
	v_fmac_f32_e32 v49, v106, v31
	v_fmac_f32_e32 v68, v106, v32
	v_fmac_f32_e32 v69, v106, v33
	v_fmac_f32_e32 v70, v106, v34
	v_fmac_f32_e32 v71, v106, v35
	v_fmac_f32_e32 v10, v94, v29
	v_fmac_f32_e32 v11, v94, v30
	v_fmac_f32_e32 v12, v93, v30
	v_fmac_f32_e32 v13, v92, v30
	v_fmac_f32_e32 v14, v91, v30
	v_fmac_f32_e32 v15, v90, v30
	v_fmac_f32_e32 v16, v99, v30
	v_fmac_f32_e32 v18, v98, v30
	v_fmac_f32_e32 v46, v103, v30
	v_fmac_f32_e32 v47, v103, v31
	v_fmac_f32_e32 v48, v107, v31
	v_fmac_f32_e32 v49, v107, v32
	v_fmac_f32_e32 v68, v107, v33
	v_fmac_f32_e32 v69, v107, v34
	v_fmac_f32_e32 v70, v107, v35
	s_waitcnt lgkmcnt(0)
	v_fmac_f32_e32 v71, v107, v17
	v_fmac_f32_e32 v10, v100, v30
	v_fmac_f32_e32 v11, v100, v31
	v_fmac_f32_e32 v12, v94, v31
	v_fmac_f32_e32 v13, v93, v31
	v_fmac_f32_e32 v14, v92, v31
	v_fmac_f32_e32 v15, v91, v31
	v_fmac_f32_e32 v16, v90, v31
	v_fmac_f32_e32 v18, v99, v31
	v_fmac_f32_e32 v46, v104, v31
	v_fmac_f32_e32 v47, v104, v32
	v_fmac_f32_e32 v48, v103, v32
	v_fmac_f32_e32 v49, v103, v33
	v_fmac_f32_e32 v68, v103, v34
	v_fmac_f32_e32 v69, v103, v35
	v_fmac_f32_e32 v70, v103, v17
	v_fmac_f32_e32 v71, v103, v36
	v_fmac_f32_e32 v10, v101, v31
	v_fmac_f32_e32 v11, v101, v32
	v_fmac_f32_e32 v12, v100, v32
	v_fmac_f32_e32 v13, v94, v32
	v_fmac_f32_e32 v14, v93, v32
	v_fmac_f32_e32 v15, v92, v32
	v_fmac_f32_e32 v16, v91, v32
	v_fmac_f32_e32 v18, v90, v32
	v_fmac_f32_e32 v46, v112, v32
	v_fmac_f32_e32 v47, v112, v33
	v_fmac_f32_e32 v48, v104, v33
	v_fmac_f32_e32 v49, v104, v34
	v_fmac_f32_e32 v68, v104, v35
	v_fmac_f32_e32 v69, v104, v17
	v_fmac_f32_e32 v70, v104, v36
	v_fmac_f32_e32 v71, v104, v37
	v_fmac_f32_e32 v10, v102, v32
	v_fmac_f32_e32 v11, v102, v33
	v_fmac_f32_e32 v12, v101, v33
	v_fmac_f32_e32 v13, v100, v33
	v_fmac_f32_e32 v14, v94, v33
	v_fmac_f32_e32 v15, v93, v33
	v_fmac_f32_e32 v16, v92, v33
	v_fmac_f32_e32 v18, v91, v33
	v_fmac_f32_e32 v46, v108, v33
	v_fmac_f32_e32 v47, v108, v34
	v_fmac_f32_e32 v48, v112, v34
	v_fmac_f32_e32 v49, v112, v35
	v_fmac_f32_e32 v68, v112, v17
	v_fmac_f32_e32 v69, v112, v36
	v_fmac_f32_e32 v70, v112, v37
	v_fmac_f32_e32 v71, v112, v38
	v_fmac_f32_e32 v10, v95, v33
	v_fmac_f32_e32 v11, v95, v34
	v_fmac_f32_e32 v12, v102, v34
	v_fmac_f32_e32 v13, v101, v34
	v_fmac_f32_e32 v14, v100, v34
	v_fmac_f32_e32 v15, v94, v34
	v_fmac_f32_e32 v16, v93, v34
	v_fmac_f32_e32 v18, v92, v34
	v_fmac_f32_e32 v46, v109, v34
	v_fmac_f32_e32 v47, v109, v35
	v_fmac_f32_e32 v48, v108, v35
	v_fmac_f32_e32 v49, v108, v17
	v_fmac_f32_e32 v68, v108, v36
	v_fmac_f32_e32 v69, v108, v37
	v_fmac_f32_e32 v70, v108, v38
	v_fmac_f32_e32 v71, v108, v39
	v_fmac_f32_e32 v10, v96, v34
	v_fmac_f32_e32 v11, v96, v35
	v_fmac_f32_e32 v12, v95, v35
	v_fmac_f32_e32 v13, v102, v35
	v_fmac_f32_e32 v14, v101, v35
	v_fmac_f32_e32 v15, v100, v35
	v_fmac_f32_e32 v16, v94, v35
	v_fmac_f32_e32 v18, v93, v35
	v_fmac_f32_e32 v46, v110, v35
	v_fmac_f32_e32 v47, v110, v17
	v_fmac_f32_e32 v48, v109, v17
	v_fmac_f32_e32 v49, v109, v36
	v_fmac_f32_e32 v68, v109, v37
	v_fmac_f32_e32 v69, v109, v38
	v_fmac_f32_e32 v70, v109, v39
	v_fmac_f32_e32 v71, v109, v40
	v_fmac_f32_e32 v10, v105, v35
	v_fmac_f32_e32 v11, v105, v17
	v_fmac_f32_e32 v12, v96, v17
	v_fmac_f32_e32 v13, v95, v17
	v_fmac_f32_e32 v14, v102, v17
	v_fmac_f32_e32 v15, v101, v17
	v_fmac_f32_e32 v16, v100, v17
	v_fmac_f32_e32 v18, v94, v17
	v_fmac_f32_e32 v46, v111, v17
	v_fmac_f32_e32 v47, v111, v36
	v_fmac_f32_e32 v48, v110, v36
	v_fmac_f32_e32 v49, v110, v37
	v_fmac_f32_e32 v68, v110, v38
	v_fmac_f32_e32 v69, v110, v39
	v_fmac_f32_e32 v70, v110, v40
	v_fmac_f32_e32 v71, v110, v41
	v_fmac_f32_e32 v10, v106, v17
	v_fmac_f32_e32 v11, v106, v36
	v_fmac_f32_e32 v12, v105, v36
	v_fmac_f32_e32 v13, v96, v36
	v_fmac_f32_e32 v14, v95, v36
	v_fmac_f32_e32 v15, v102, v36
	v_fmac_f32_e32 v16, v101, v36
	v_fmac_f32_e32 v18, v100, v36
	v_fmac_f32_e32 v46, v113, v36
	v_fmac_f32_e32 v47, v113, v37
	v_fmac_f32_e32 v48, v111, v37
	v_fmac_f32_e32 v49, v111, v38
	v_fmac_f32_e32 v68, v111, v39
	v_fmac_f32_e32 v69, v111, v40
	v_fmac_f32_e32 v70, v111, v41
	v_fmac_f32_e32 v71, v111, v42
	v_fmac_f32_e32 v10, v107, v36
	v_fmac_f32_e32 v11, v107, v37
	v_fmac_f32_e32 v12, v106, v37
	v_fmac_f32_e32 v13, v105, v37
	v_fmac_f32_e32 v14, v96, v37
	v_fmac_f32_e32 v15, v95, v37
	v_fmac_f32_e32 v16, v102, v37
	v_fmac_f32_e32 v18, v101, v37
	v_fmac_f32_e32 v46, v114, v37
	v_fmac_f32_e32 v47, v114, v38
	v_fmac_f32_e32 v48, v113, v38
	v_fmac_f32_e32 v49, v113, v39
	v_fmac_f32_e32 v68, v113, v40
	v_fmac_f32_e32 v69, v113, v41
	v_fmac_f32_e32 v70, v113, v42
	v_fmac_f32_e32 v71, v113, v43
	v_fmac_f32_e32 v10, v103, v37
	v_fmac_f32_e32 v11, v103, v38
	v_fmac_f32_e32 v12, v107, v38
	v_fmac_f32_e32 v13, v106, v38
	v_fmac_f32_e32 v14, v105, v38
	v_fmac_f32_e32 v15, v96, v38
	v_fmac_f32_e32 v16, v95, v38
	v_fmac_f32_e32 v18, v102, v38
	v_fmac_f32_e32 v46, v115, v38
	v_fmac_f32_e32 v47, v115, v39
	v_fmac_f32_e32 v48, v114, v39
	v_fmac_f32_e32 v49, v114, v40
	v_fmac_f32_e32 v68, v114, v41
	v_fmac_f32_e32 v69, v114, v42
	v_fmac_f32_e32 v70, v114, v43
	v_fmac_f32_e32 v71, v114, v44
	v_fmac_f32_e32 v10, v104, v38
	v_fmac_f32_e32 v11, v104, v39
	v_fmac_f32_e32 v12, v103, v39
	v_fmac_f32_e32 v13, v107, v39
	v_fmac_f32_e32 v14, v106, v39
	v_fmac_f32_e32 v15, v105, v39
	v_fmac_f32_e32 v16, v96, v39
	v_fmac_f32_e32 v18, v95, v39
	v_fmac_f32_e32 v48, v115, v40
	v_fmac_f32_e32 v49, v115, v41
	v_fmac_f32_e32 v68, v115, v42
	v_fmac_f32_e32 v69, v115, v43
	v_fmac_f32_e32 v70, v115, v44
	v_fmac_f32_e32 v71, v115, v45
	ds_write2st64_b32 v55, v46, v47 offset1:4
	ds_write2st64_b32 v55, v48, v49 offset0:8 offset1:12
	ds_write2st64_b32 v55, v68, v69 offset0:16 offset1:20
	ds_write2st64_b32 v55, v70, v71 offset0:24 offset1:28
	v_fmac_f32_e32 v10, v112, v39
	v_fmac_f32_e32 v11, v112, v40
	v_fmac_f32_e32 v12, v104, v40
	v_fmac_f32_e32 v13, v103, v40
	v_fmac_f32_e32 v14, v107, v40
	v_fmac_f32_e32 v15, v106, v40
	v_fmac_f32_e32 v16, v105, v40
	v_fmac_f32_e32 v18, v96, v40
	v_fmac_f32_e32 v10, v108, v40
	v_fmac_f32_e32 v11, v108, v41
	v_fmac_f32_e32 v12, v112, v41
	v_fmac_f32_e32 v13, v104, v41
	v_fmac_f32_e32 v14, v103, v41
	v_fmac_f32_e32 v15, v107, v41
	v_fmac_f32_e32 v16, v106, v41
	v_fmac_f32_e32 v18, v105, v41
	ds_read2st64_b32 v[20:21], v137 offset0:152 offset1:156
	v_fmac_f32_e32 v10, v109, v41
	v_fmac_f32_e32 v11, v109, v42
	v_fmac_f32_e32 v12, v108, v42
	v_fmac_f32_e32 v13, v112, v42
	v_fmac_f32_e32 v14, v104, v42
	v_fmac_f32_e32 v15, v103, v42
	v_fmac_f32_e32 v16, v107, v42
	v_fmac_f32_e32 v18, v106, v42
	v_fmac_f32_e32 v10, v110, v42
	v_fmac_f32_e32 v11, v110, v43
	v_fmac_f32_e32 v12, v109, v43
	v_fmac_f32_e32 v13, v108, v43
	v_fmac_f32_e32 v14, v112, v43
	v_fmac_f32_e32 v15, v104, v43
	v_fmac_f32_e32 v16, v103, v43
	v_fmac_f32_e32 v18, v107, v43
	v_fmac_f32_e32 v10, v111, v43
	v_fmac_f32_e32 v11, v111, v44
	v_fmac_f32_e32 v12, v110, v44
	v_fmac_f32_e32 v13, v109, v44
	v_fmac_f32_e32 v14, v108, v44
	v_fmac_f32_e32 v15, v112, v44
	v_fmac_f32_e32 v16, v104, v44
	v_fmac_f32_e32 v18, v103, v44
	v_fmac_f32_e32 v10, v113, v44
	v_fmac_f32_e32 v11, v113, v45
	v_fmac_f32_e32 v12, v111, v45
	v_fmac_f32_e32 v13, v110, v45
	v_fmac_f32_e32 v14, v109, v45
	v_fmac_f32_e32 v15, v108, v45
	v_fmac_f32_e32 v16, v112, v45
	v_fmac_f32_e32 v18, v104, v45
	v_fmac_f32_e32 v10, v114, v45
	s_waitcnt lgkmcnt(0)
	v_fmac_f32_e32 v11, v114, v20
	v_fmac_f32_e32 v12, v113, v20
	v_fmac_f32_e32 v13, v111, v20
	v_fmac_f32_e32 v14, v110, v20
	v_fmac_f32_e32 v15, v109, v20
	v_fmac_f32_e32 v16, v108, v20
	v_fmac_f32_e32 v18, v112, v20
	v_fmac_f32_e32 v10, v115, v20
	v_fmac_f32_e32 v11, v115, v21
	v_fmac_f32_e32 v12, v114, v21
	v_fmac_f32_e32 v13, v113, v21
	v_fmac_f32_e32 v14, v111, v21
	v_fmac_f32_e32 v15, v110, v21
	v_fmac_f32_e32 v16, v109, v21
	v_fmac_f32_e32 v18, v108, v21
	ds_read2st64_b32 v[20:21], v137 offset0:160 offset1:164
	v_add_u32_e32 v46, s71, v121
	v_add_u32_e32 v48, s80, v121
	v_add_u32_e32 v49, s90, v121
	s_waitcnt lgkmcnt(0)
	v_fmac_f32_e32 v13, v114, v20
	v_fmac_f32_e32 v14, v113, v20
	v_fmac_f32_e32 v15, v111, v20
	v_fmac_f32_e32 v16, v110, v20
	v_fmac_f32_e32 v18, v109, v20
	v_fmac_f32_e32 v12, v115, v20
	v_fmac_f32_e32 v13, v115, v21
	v_fmac_f32_e32 v14, v114, v21
	v_fmac_f32_e32 v15, v113, v21
	v_fmac_f32_e32 v16, v111, v21
	v_fmac_f32_e32 v18, v110, v21
	ds_read2st64_b32 v[20:21], v137 offset0:168 offset1:172
	s_waitcnt lgkmcnt(0)
	v_fmac_f32_e32 v15, v114, v20
	v_fmac_f32_e32 v16, v113, v20
	v_fmac_f32_e32 v18, v111, v20
	v_fmac_f32_e32 v14, v115, v20
	v_fmac_f32_e32 v15, v115, v21
	v_fmac_f32_e32 v16, v114, v21
	v_fmac_f32_e32 v18, v113, v21
	ds_read2st64_b32 v[20:21], v137 offset0:176 offset1:180
	s_waitcnt lgkmcnt(0)
	v_fmac_f32_e32 v18, v114, v20
	v_fmac_f32_e32 v16, v115, v20
	v_fmac_f32_e32 v18, v115, v21
	ds_write2st64_b32 v55, v10, v11 offset0:32 offset1:36
	ds_write2st64_b32 v55, v12, v13 offset0:40 offset1:44
	ds_write2st64_b32 v55, v14, v15 offset0:48 offset1:52
	ds_write2st64_b32 v55, v16, v18 offset0:56 offset1:60
	s_waitcnt lgkmcnt(0)
	s_barrier
	ds_read_b128 v[10:13], v46
	s_or_b32 s100, s70, 32
	s_and_b32 s101, s100, 0xfe0
	s_sub_i32 s101, 29, s101
	v_cmp_lt_i32_e32 vcc, s101, v123
	s_nop 1
	v_cndmask_b32_e32 v160, 0, v124, vcc
	v_add_u32_e32 v160, s100, v160
	v_mad_i64_i32 v[160:161], vcc, v160, s33, v[176:177]
	v_add_co_u32_e32 v160, vcc, v160, v0
	s_nop 1
	v_addc_co_u32_e32 v161, vcc, 0, v161, vcc
	global_load_dwordx4 v[152:155], v[160:161], off offset:512
	global_load_dwordx4 v[156:159], v[160:161], off offset:1024
	v_cmp_lt_i32_e32 vcc, s101, v126
	s_nop 1
	v_cndmask_b32_e32 v160, 0, v127, vcc
	v_add_u32_e32 v160, s100, v160
	v_mad_i64_i32 v[160:161], vcc, v160, s33, v[176:177]
	v_add_co_u32_e32 v160, vcc, v160, v62
	s_nop 1
	v_addc_co_u32_e32 v161, vcc, 0, v161, vcc
	global_load_dwordx4 v[168:171], v[160:161], off offset:512
	global_load_dwordx4 v[172:175], v[160:161], off offset:1024
	v_cmp_lt_i32_e32 vcc, s101, v129
	s_nop 1
	v_cndmask_b32_e32 v160, 0, v130, vcc
	v_add_u32_e32 v160, s100, v160
	v_mad_i64_i32 v[160:161], vcc, v160, s33, v[176:177]
	v_add_co_u32_e32 v160, vcc, v160, v64
	s_nop 1
	v_addc_co_u32_e32 v161, vcc, 0, v161, vcc
	global_load_dwordx4 v[182:185], v[160:161], off offset:512
	global_load_dwordx4 v[186:189], v[160:161], off offset:1024
	s_waitcnt lgkmcnt(0)
	v_mov_b32_e32 v14, v11
	v_mov_b32_e32 v15, v12
	v_mov_b32_e32 v16, v10
	v_mov_b32_e32 v17, v13
	v_pk_add_f32 v[14:15], v[14:15], v[16:17]
	s_nop 0
	v_add_f32_e32 v14, v14, v15
	v_mov_b32_e32 v15, v1
	s_nop 0
	v_add_f32_dpp v14, v14, v14 row_shr:1 row_mask:0xf bank_mask:0xf bound_ctrl:1
	s_nop 1
	v_add_f32_dpp v14, v14, v14 row_shr:2 row_mask:0xf bank_mask:0xf bound_ctrl:1
	s_nop 1
	v_add_f32_dpp v14, v14, v14 row_shr:4 row_mask:0xf bank_mask:0xf bound_ctrl:1
	s_nop 1
	v_add_f32_dpp v14, v14, v14 row_shr:8 row_mask:0xf bank_mask:0xf bound_ctrl:1
	s_nop 1
	v_mov_b32_dpp v15, v14 row_bcast:15 row_mask:0xa bank_mask:0xf
	v_add_f32_e32 v14, v14, v15
	v_mov_b32_e32 v15, v1
	s_nop 1
	v_mov_b32_dpp v15, v14 row_bcast:31 row_mask:0xc bank_mask:0xf
	v_add_f32_e32 v14, v14, v15
	s_nop 0
	v_readlane_b32 s71, v14, 63
	s_nop 1
	v_fma_f32 v11, s71, v241, v11
	v_fma_f32 v10, s71, v241, v10
	v_fma_f32 v13, s71, v241, v13
	v_fmac_f32_e32 v12, s71, v241
	v_pk_mul_f32 v[14:15], v[12:13], v[12:13]
	v_pk_mul_f32 v[16:17], v[10:11], v[10:11]
	s_nop 0
	v_pk_mov_b32 v[18:19], v[16:17], v[14:15] op_sel:[1,0]
	v_mov_b32_e32 v17, v15
	v_pk_add_f32 v[14:15], v[18:19], v[16:17]
	s_nop 0
	v_add_f32_e32 v14, v14, v15
	v_mov_b32_e32 v15, v1
	s_nop 0
	v_add_f32_dpp v14, v14, v14 row_shr:1 row_mask:0xf bank_mask:0xf bound_ctrl:1
	s_nop 1
	v_add_f32_dpp v14, v14, v14 row_shr:2 row_mask:0xf bank_mask:0xf bound_ctrl:1
	s_nop 1
	v_add_f32_dpp v14, v14, v14 row_shr:4 row_mask:0xf bank_mask:0xf bound_ctrl:1
	s_nop 1
	v_add_f32_dpp v14, v14, v14 row_shr:8 row_mask:0xf bank_mask:0xf bound_ctrl:1
	s_nop 1
	v_mov_b32_dpp v15, v14 row_bcast:15 row_mask:0xa bank_mask:0xf
	v_add_f32_e32 v14, v14, v15
	v_mov_b32_e32 v15, v1
	s_nop 1
	v_mov_b32_dpp v15, v14 row_bcast:31 row_mask:0xc bank_mask:0xf
	v_add_f32_e32 v14, v14, v15
	s_nop 0
	v_readlane_b32 s71, v14, 63
	s_nop 1
	v_fma_f32 v14, s71, v242, v197
	v_rsq_f32_e32 v14, v14
	v_readlane_b32 s71, v255, 47
	v_pk_mul_f32 v[10:11], v[10:11], v[14:15] op_sel_hi:[1,0]
	s_nop 0
	v_pk_fma_f32 v[10:11], v[2:3], v[10:11], v[6:7]
	v_pk_mul_f32 v[12:13], v[12:13], v[14:15] op_sel_hi:[1,0]
	v_mul_f32_e32 v14, 0xbfb8aa3b, v10
	v_exp_f32_e32 v14, v14
	v_pk_fma_f32 v[12:13], v[4:5], v[12:13], v[8:9]
	v_add_u32_e32 v47, s71, v121
	v_add_f32_e32 v14, 1.0, v14
	v_rcp_f32_e32 v14, v14
	s_nop 0
	v_mul_f32_e32 v10, v10, v14
	v_mul_f32_e32 v14, 0xbfb8aa3b, v11
	v_exp_f32_e32 v14, v14
	s_nop 0
	v_add_f32_e32 v14, 1.0, v14
	v_rcp_f32_e32 v14, v14
	s_nop 0
	v_mul_f32_e32 v11, v11, v14
	v_cvt_pk_bf16_f32 v10, v10, v11
	v_mul_f32_e32 v11, 0xbfb8aa3b, v12
	v_exp_f32_e32 v11, v11
	s_nop 0
	v_add_f32_e32 v11, 1.0, v11
	v_rcp_f32_e32 v11, v11
	s_nop 0
	v_mul_f32_e32 v11, v12, v11
	v_mul_f32_e32 v12, 0xbfb8aa3b, v13
	v_exp_f32_e32 v12, v12
	s_nop 0
	v_add_f32_e32 v12, 1.0, v12
	v_rcp_f32_e32 v12, v12
	s_nop 0
	v_mul_f32_e32 v12, v13, v12
	v_cvt_pk_bf16_f32 v11, v11, v12
	v_lshl_add_u64 v[12:13], v[60:61], 0, s[72:73]
	global_store_dwordx2 v[12:13], v[10:11], off offset:1536
	ds_read_b128 v[10:13], v47
	s_add_i32 s72, s70, s88
	s_ashr_i32 s73, s72, 31
	s_lshl_b64 s[72:73], s[72:73], 11
	s_waitcnt lgkmcnt(0)
	v_mov_b32_e32 v14, v11
	v_mov_b32_e32 v15, v12
	v_mov_b32_e32 v16, v10
	v_mov_b32_e32 v17, v13
	v_pk_add_f32 v[14:15], v[14:15], v[16:17]
	s_nop 0
	v_add_f32_e32 v14, v14, v15
	v_mov_b32_e32 v15, v1
	s_nop 0
	v_add_f32_dpp v14, v14, v14 row_shr:1 row_mask:0xf bank_mask:0xf bound_ctrl:1
	s_nop 1
	v_add_f32_dpp v14, v14, v14 row_shr:2 row_mask:0xf bank_mask:0xf bound_ctrl:1
	s_nop 1
	v_add_f32_dpp v14, v14, v14 row_shr:4 row_mask:0xf bank_mask:0xf bound_ctrl:1
	s_nop 1
	v_add_f32_dpp v14, v14, v14 row_shr:8 row_mask:0xf bank_mask:0xf bound_ctrl:1
	s_nop 1
	v_mov_b32_dpp v15, v14 row_bcast:15 row_mask:0xa bank_mask:0xf
	v_add_f32_e32 v14, v14, v15
	v_mov_b32_e32 v15, v1
	s_nop 1
	v_mov_b32_dpp v15, v14 row_bcast:31 row_mask:0xc bank_mask:0xf
	v_add_f32_e32 v14, v14, v15
	s_nop 0
	v_readlane_b32 s71, v14, 63
	s_nop 1
	v_fma_f32 v11, s71, v241, v11
	v_fma_f32 v10, s71, v241, v10
	v_fma_f32 v13, s71, v241, v13
	v_fmac_f32_e32 v12, s71, v241
	v_pk_mul_f32 v[14:15], v[12:13], v[12:13]
	v_pk_mul_f32 v[16:17], v[10:11], v[10:11]
	s_nop 0
	v_pk_mov_b32 v[18:19], v[16:17], v[14:15] op_sel:[1,0]
	v_mov_b32_e32 v17, v15
	v_pk_add_f32 v[14:15], v[18:19], v[16:17]
	s_nop 0
	v_add_f32_e32 v14, v14, v15
	v_mov_b32_e32 v15, v1
	s_nop 0
	v_add_f32_dpp v14, v14, v14 row_shr:1 row_mask:0xf bank_mask:0xf bound_ctrl:1
	s_nop 1
	v_add_f32_dpp v14, v14, v14 row_shr:2 row_mask:0xf bank_mask:0xf bound_ctrl:1
	s_nop 1
	v_add_f32_dpp v14, v14, v14 row_shr:4 row_mask:0xf bank_mask:0xf bound_ctrl:1
	s_nop 1
	v_add_f32_dpp v14, v14, v14 row_shr:8 row_mask:0xf bank_mask:0xf bound_ctrl:1
	s_nop 1
	v_mov_b32_dpp v15, v14 row_bcast:15 row_mask:0xa bank_mask:0xf
	v_add_f32_e32 v14, v14, v15
	v_mov_b32_e32 v15, v1
	s_nop 1
	v_mov_b32_dpp v15, v14 row_bcast:31 row_mask:0xc bank_mask:0xf
	v_add_f32_e32 v14, v14, v15
	s_nop 0
	v_readlane_b32 s71, v14, 63
	s_nop 1
	v_fma_f32 v14, s71, v242, v197
	v_rsq_f32_e32 v14, v14
	s_nop 0
	v_pk_mul_f32 v[10:11], v[10:11], v[14:15] op_sel_hi:[1,0]
	s_nop 0
	v_pk_fma_f32 v[10:11], v[2:3], v[10:11], v[6:7]
	v_pk_mul_f32 v[12:13], v[12:13], v[14:15] op_sel_hi:[1,0]
	v_mul_f32_e32 v14, 0xbfb8aa3b, v10
	v_exp_f32_e32 v14, v14
	v_pk_fma_f32 v[12:13], v[4:5], v[12:13], v[8:9]
	v_add_f32_e32 v14, 1.0, v14
	v_rcp_f32_e32 v14, v14
	s_nop 0
	v_mul_f32_e32 v10, v10, v14
	v_mul_f32_e32 v14, 0xbfb8aa3b, v11
	v_exp_f32_e32 v14, v14
	s_nop 0
	v_add_f32_e32 v14, 1.0, v14
	v_rcp_f32_e32 v14, v14
	s_nop 0
	v_mul_f32_e32 v11, v11, v14
	v_cvt_pk_bf16_f32 v10, v10, v11
	v_mul_f32_e32 v11, 0xbfb8aa3b, v12
	v_exp_f32_e32 v11, v11
	s_nop 0
	v_add_f32_e32 v11, 1.0, v11
	v_rcp_f32_e32 v11, v11
	s_nop 0
	v_mul_f32_e32 v11, v12, v11
	v_mul_f32_e32 v12, 0xbfb8aa3b, v13
	v_exp_f32_e32 v12, v12
	s_nop 0
	v_add_f32_e32 v12, 1.0, v12
	v_rcp_f32_e32 v12, v12
	s_nop 0
	v_mul_f32_e32 v12, v13, v12
	v_cvt_pk_bf16_f32 v11, v11, v12
	v_lshl_add_u64 v[12:13], v[60:61], 0, s[72:73]
	global_store_dwordx2 v[12:13], v[10:11], off offset:1536
	ds_read_b128 v[10:13], v48
	s_add_i32 s72, s70, s91
	s_ashr_i32 s73, s72, 31
	s_lshl_b64 s[72:73], s[72:73], 11
	s_waitcnt lgkmcnt(0)
	v_mov_b32_e32 v14, v11
	v_mov_b32_e32 v15, v12
	v_mov_b32_e32 v16, v10
	v_mov_b32_e32 v17, v13
	v_pk_add_f32 v[14:15], v[14:15], v[16:17]
	s_nop 0
	v_add_f32_e32 v14, v14, v15
	v_mov_b32_e32 v15, v1
	s_nop 0
	v_add_f32_dpp v14, v14, v14 row_shr:1 row_mask:0xf bank_mask:0xf bound_ctrl:1
	s_nop 1
	v_add_f32_dpp v14, v14, v14 row_shr:2 row_mask:0xf bank_mask:0xf bound_ctrl:1
	s_nop 1
	v_add_f32_dpp v14, v14, v14 row_shr:4 row_mask:0xf bank_mask:0xf bound_ctrl:1
	s_nop 1
	v_add_f32_dpp v14, v14, v14 row_shr:8 row_mask:0xf bank_mask:0xf bound_ctrl:1
	s_nop 1
	v_mov_b32_dpp v15, v14 row_bcast:15 row_mask:0xa bank_mask:0xf
	v_add_f32_e32 v14, v14, v15
	v_mov_b32_e32 v15, v1
	s_nop 1
	v_mov_b32_dpp v15, v14 row_bcast:31 row_mask:0xc bank_mask:0xf
	v_add_f32_e32 v14, v14, v15
	s_nop 0
	v_readlane_b32 s71, v14, 63
	s_nop 1
	v_fma_f32 v11, s71, v241, v11
	v_fma_f32 v10, s71, v241, v10
	v_fma_f32 v13, s71, v241, v13
	v_fmac_f32_e32 v12, s71, v241
	v_pk_mul_f32 v[14:15], v[12:13], v[12:13]
	v_pk_mul_f32 v[16:17], v[10:11], v[10:11]
	s_nop 0
	v_pk_mov_b32 v[18:19], v[16:17], v[14:15] op_sel:[1,0]
	v_mov_b32_e32 v17, v15
	v_pk_add_f32 v[14:15], v[18:19], v[16:17]
	s_nop 0
	v_add_f32_e32 v14, v14, v15
	v_mov_b32_e32 v15, v1
	s_nop 0
	v_add_f32_dpp v14, v14, v14 row_shr:1 row_mask:0xf bank_mask:0xf bound_ctrl:1
	s_nop 1
	v_add_f32_dpp v14, v14, v14 row_shr:2 row_mask:0xf bank_mask:0xf bound_ctrl:1
	s_nop 1
	v_add_f32_dpp v14, v14, v14 row_shr:4 row_mask:0xf bank_mask:0xf bound_ctrl:1
	s_nop 1
	v_add_f32_dpp v14, v14, v14 row_shr:8 row_mask:0xf bank_mask:0xf bound_ctrl:1
	s_nop 1
	v_mov_b32_dpp v15, v14 row_bcast:15 row_mask:0xa bank_mask:0xf
	v_add_f32_e32 v14, v14, v15
	v_mov_b32_e32 v15, v1
	s_nop 1
	v_mov_b32_dpp v15, v14 row_bcast:31 row_mask:0xc bank_mask:0xf
	v_add_f32_e32 v14, v14, v15
	s_nop 0
	v_readlane_b32 s71, v14, 63
	s_nop 1
	v_fma_f32 v14, s71, v242, v197
	v_rsq_f32_e32 v14, v14
	s_nop 0
	v_pk_mul_f32 v[10:11], v[10:11], v[14:15] op_sel_hi:[1,0]
	s_nop 0
	v_pk_fma_f32 v[10:11], v[2:3], v[10:11], v[6:7]
	v_pk_mul_f32 v[12:13], v[12:13], v[14:15] op_sel_hi:[1,0]
	v_mul_f32_e32 v14, 0xbfb8aa3b, v10
	v_exp_f32_e32 v14, v14
	v_pk_fma_f32 v[12:13], v[4:5], v[12:13], v[8:9]
	v_add_f32_e32 v14, 1.0, v14
	v_rcp_f32_e32 v14, v14
	s_nop 0
	v_mul_f32_e32 v10, v10, v14
	v_mul_f32_e32 v14, 0xbfb8aa3b, v11
	v_exp_f32_e32 v14, v14
	s_nop 0
	v_add_f32_e32 v14, 1.0, v14
	v_rcp_f32_e32 v14, v14
	s_nop 0
	v_mul_f32_e32 v11, v11, v14
	v_cvt_pk_bf16_f32 v10, v10, v11
	v_mul_f32_e32 v11, 0xbfb8aa3b, v12
	v_exp_f32_e32 v11, v11
	s_nop 0
	v_add_f32_e32 v11, 1.0, v11
	v_rcp_f32_e32 v11, v11
	s_nop 0
	v_mul_f32_e32 v11, v12, v11
	v_mul_f32_e32 v12, 0xbfb8aa3b, v13
	v_exp_f32_e32 v12, v12
	s_nop 0
	v_add_f32_e32 v12, 1.0, v12
	v_rcp_f32_e32 v12, v12
	s_nop 0
	v_mul_f32_e32 v12, v13, v12
	v_cvt_pk_bf16_f32 v11, v11, v12
	v_lshl_add_u64 v[12:13], v[60:61], 0, s[72:73]
	global_store_dwordx2 v[12:13], v[10:11], off offset:1536
	ds_read_b128 v[10:13], v49
	s_add_i32 s72, s70, s87
	s_or_b32 s70, s70, 32
	s_ashr_i32 s73, s72, 31
	s_lshl_b64 s[72:73], s[72:73], 11
	s_waitcnt lgkmcnt(0)
	v_mov_b32_e32 v14, v11
	v_mov_b32_e32 v15, v12
	v_mov_b32_e32 v16, v10
	v_mov_b32_e32 v17, v13
	v_pk_add_f32 v[14:15], v[14:15], v[16:17]
	s_nop 0
	v_add_f32_e32 v14, v14, v15
	v_mov_b32_e32 v15, v1
	s_nop 0
	v_add_f32_dpp v14, v14, v14 row_shr:1 row_mask:0xf bank_mask:0xf bound_ctrl:1
	s_nop 1
	v_add_f32_dpp v14, v14, v14 row_shr:2 row_mask:0xf bank_mask:0xf bound_ctrl:1
	s_nop 1
	v_add_f32_dpp v14, v14, v14 row_shr:4 row_mask:0xf bank_mask:0xf bound_ctrl:1
	s_nop 1
	v_add_f32_dpp v14, v14, v14 row_shr:8 row_mask:0xf bank_mask:0xf bound_ctrl:1
	s_nop 1
	v_mov_b32_dpp v15, v14 row_bcast:15 row_mask:0xa bank_mask:0xf
	v_add_f32_e32 v14, v14, v15
	v_mov_b32_e32 v15, v1
	s_nop 1
	v_mov_b32_dpp v15, v14 row_bcast:31 row_mask:0xc bank_mask:0xf
	v_add_f32_e32 v14, v14, v15
	s_nop 0
	v_readlane_b32 s71, v14, 63
	s_nop 1
	v_fma_f32 v11, s71, v241, v11
	v_fma_f32 v10, s71, v241, v10
	v_fma_f32 v13, s71, v241, v13
	v_fmac_f32_e32 v12, s71, v241
	v_pk_mul_f32 v[14:15], v[12:13], v[12:13]
	v_pk_mul_f32 v[16:17], v[10:11], v[10:11]
	s_nop 0
	v_pk_mov_b32 v[18:19], v[16:17], v[14:15] op_sel:[1,0]
	v_mov_b32_e32 v17, v15
	v_pk_add_f32 v[14:15], v[18:19], v[16:17]
	s_nop 0
	v_add_f32_e32 v14, v14, v15
	v_mov_b32_e32 v15, v1
	s_nop 0
	v_add_f32_dpp v14, v14, v14 row_shr:1 row_mask:0xf bank_mask:0xf bound_ctrl:1
	s_nop 1
	v_add_f32_dpp v14, v14, v14 row_shr:2 row_mask:0xf bank_mask:0xf bound_ctrl:1
	s_nop 1
	v_add_f32_dpp v14, v14, v14 row_shr:4 row_mask:0xf bank_mask:0xf bound_ctrl:1
	s_nop 1
	v_add_f32_dpp v14, v14, v14 row_shr:8 row_mask:0xf bank_mask:0xf bound_ctrl:1
	s_nop 1
	v_mov_b32_dpp v15, v14 row_bcast:15 row_mask:0xa bank_mask:0xf
	v_add_f32_e32 v14, v14, v15
	v_mov_b32_e32 v15, v1
	s_nop 1
	v_mov_b32_dpp v15, v14 row_bcast:31 row_mask:0xc bank_mask:0xf
	v_add_f32_e32 v14, v14, v15
	s_nop 0
	v_readlane_b32 s71, v14, 63
	s_nop 1
	v_fma_f32 v14, s71, v242, v197
	v_rsq_f32_e32 v14, v14
	s_and_b32 s71, s70, 0xfe0
	s_sub_i32 s71, 29, s71
	v_cmp_lt_i32_e32 vcc, s71, v123
	v_pk_mul_f32 v[10:11], v[10:11], v[14:15] op_sel_hi:[1,0]
	v_pk_mul_f32 v[12:13], v[12:13], v[14:15] op_sel_hi:[1,0]
	v_pk_fma_f32 v[10:11], v[2:3], v[10:11], v[6:7]
	v_pk_fma_f32 v[12:13], v[4:5], v[12:13], v[8:9]
	v_mul_f32_e32 v14, 0xbfb8aa3b, v10
	v_exp_f32_e32 v14, v14
	v_cndmask_b32_e64 v18, 0, 1.0, vcc
	v_add_f32_e32 v14, 1.0, v14
	v_rcp_f32_e32 v14, v14
	s_nop 0
	v_mul_f32_e32 v10, v10, v14
	v_mul_f32_e32 v14, 0xbfb8aa3b, v11
	v_exp_f32_e32 v14, v14
	s_nop 0
	v_add_f32_e32 v14, 1.0, v14
	v_rcp_f32_e32 v14, v14
	s_nop 0
	v_mul_f32_e32 v11, v11, v14
	v_cvt_pk_bf16_f32 v10, v10, v11
	v_mul_f32_e32 v11, 0xbfb8aa3b, v12
	v_exp_f32_e32 v11, v11
	s_nop 0
	v_add_f32_e32 v11, 1.0, v11
	v_rcp_f32_e32 v11, v11
	s_nop 0
	v_mul_f32_e32 v11, v12, v11
	v_mul_f32_e32 v12, 0xbfb8aa3b, v13
	v_exp_f32_e32 v12, v12
	s_nop 0
	v_add_f32_e32 v12, 1.0, v12
	v_rcp_f32_e32 v12, v12
	s_nop 0
	v_mul_f32_e32 v12, v13, v12
	v_cvt_pk_bf16_f32 v11, v11, v12
	v_lshl_add_u64 v[12:13], v[60:61], 0, s[72:73]
	global_store_dwordx2 v[12:13], v[10:11], off offset:1536
	v_cndmask_b32_e32 v10, 0, v124, vcc
	v_add_u32_e32 v10, s70, v10
	v_mad_i64_i32 v[10:11], s[72:73], v10, s33, v[86:87]
	v_lshl_add_u64 v[10:11], v[10:11], 0, v[0:1]
	v_add_co_u32_e32 v14, vcc, s82, v10
	s_nop 1
	v_addc_co_u32_e32 v15, vcc, 0, v11, vcc
	s_waitcnt vmcnt(8)
	v_mov_b32_e32 v10, v152
	v_mov_b32_e32 v11, v153
	v_mov_b32_e32 v12, v154
	v_mov_b32_e32 v13, v155
	v_mov_b32_e32 v14, v156
	v_mov_b32_e32 v15, v157
	v_mov_b32_e32 v16, v158
	v_mov_b32_e32 v17, v159
	v_cmp_lt_i32_e32 vcc, s71, v132
	s_nop 1
	v_cndmask_b32_e32 v160, 0, v133, vcc
	v_add_u32_e32 v160, s70, v160
	v_mad_i64_i32 v[160:161], vcc, v160, s33, v[176:177]
	v_add_co_u32_e32 v160, vcc, v160, v66
	s_nop 1
	v_addc_co_u32_e32 v161, vcc, 0, v161, vcc
	global_load_dwordx4 v[152:155], v[160:161], off offset:512
	global_load_dwordx4 v[156:159], v[160:161], off offset:1024
	v_cmp_lt_i32_e32 vcc, s71, v126
	v_lshlrev_b32_e32 v22, 16, v10
	v_lshlrev_b32_e32 v19, 16, v14
	v_and_b32_e32 v14, 0xffff0000, v14
	v_and_b32_e32 v23, 0xffff0000, v10
	v_lshlrev_b32_e32 v10, 16, v15
	v_mul_f32_e32 v19, 0xbfb8aa3b, v19
	v_mul_f32_e32 v14, 0xbfb8aa3b, v14
	v_mul_f32_e32 v10, 0xbfb8aa3b, v10
	v_exp_f32_e32 v19, v19
	v_exp_f32_e32 v14, v14
	v_exp_f32_e32 v10, v10
	v_add_f32_e32 v19, 1.0, v19
	v_add_f32_e32 v14, 1.0, v14
	v_add_f32_e32 v10, 1.0, v10
	v_rcp_f32_e32 v20, v19
	v_rcp_f32_e32 v21, v14
	v_rcp_f32_e32 v14, v10
	v_and_b32_e32 v10, 0xffff0000, v15
	v_mul_f32_e32 v10, 0xbfb8aa3b, v10
	v_exp_f32_e32 v10, v10
	v_pk_mul_f32 v[20:21], v[20:21], v[22:23]
	v_lshlrev_b32_e32 v22, 16, v12
	v_and_b32_e32 v23, 0xffff0000, v12
	v_lshlrev_b32_e32 v12, 16, v17
	v_mul_f32_e32 v12, 0xbfb8aa3b, v12
	v_add_f32_e32 v10, 1.0, v10
	v_exp_f32_e32 v12, v12
	v_rcp_f32_e32 v15, v10
	v_lshlrev_b32_e32 v10, 16, v11
	v_and_b32_e32 v11, 0xffff0000, v11
	v_add_f32_e32 v12, 1.0, v12
	v_pk_mul_f32 v[10:11], v[14:15], v[10:11]
	v_lshlrev_b32_e32 v14, 16, v16
	v_and_b32_e32 v15, 0xffff0000, v16
	v_rcp_f32_e32 v16, v12
	v_and_b32_e32 v12, 0xffff0000, v17
	v_mul_f32_e32 v14, 0xbfb8aa3b, v14
	v_mul_f32_e32 v15, 0xbfb8aa3b, v15
	v_mul_f32_e32 v12, 0xbfb8aa3b, v12
	v_exp_f32_e32 v14, v14
	v_exp_f32_e32 v15, v15
	v_exp_f32_e32 v12, v12
	v_add_f32_e32 v14, 1.0, v14
	v_add_f32_e32 v15, 1.0, v15
	v_add_f32_e32 v12, 1.0, v12
	v_rcp_f32_e32 v14, v14
	v_rcp_f32_e32 v15, v15
	v_rcp_f32_e32 v17, v12
	v_lshlrev_b32_e32 v12, 16, v13
	v_and_b32_e32 v13, 0xffff0000, v13
	v_pk_mul_f32 v[14:15], v[14:15], v[22:23]
	v_pk_mul_f32 v[16:17], v[16:17], v[12:13]
	v_pk_mul_f32 v[12:13], v[18:19], v[10:11] op_sel_hi:[0,1]
	v_pk_mul_f32 v[10:11], v[18:19], v[20:21] op_sel_hi:[0,1]
	ds_write_b128 v125, v[10:13] offset:36864
	v_pk_mul_f32 v[12:13], v[18:19], v[16:17] op_sel_hi:[0,1]
	v_pk_mul_f32 v[10:11], v[18:19], v[14:15] op_sel_hi:[0,1]
	ds_write_b128 v125, v[10:13] offset:36880
	v_cndmask_b32_e32 v10, 0, v127, vcc
	v_add_u32_e32 v10, s70, v10
	v_mad_i64_i32 v[10:11], s[72:73], v10, s33, v[86:87]
	v_lshl_add_u64 v[10:11], v[10:11], 0, v[62:63]
	v_cndmask_b32_e64 v18, 0, 1.0, vcc
	v_add_co_u32_e32 v14, vcc, s82, v10
	s_nop 1
	v_addc_co_u32_e32 v15, vcc, 0, v11, vcc
	s_waitcnt vmcnt(8)
	v_mov_b32_e32 v10, v168
	v_mov_b32_e32 v11, v169
	v_mov_b32_e32 v12, v170
	v_mov_b32_e32 v13, v171
	v_mov_b32_e32 v14, v172
	v_mov_b32_e32 v15, v173
	v_mov_b32_e32 v16, v174
	v_mov_b32_e32 v17, v175
	v_cmp_lt_i32_e32 vcc, s71, v129
	v_lshlrev_b32_e32 v22, 16, v10
	v_lshlrev_b32_e32 v19, 16, v14
	v_and_b32_e32 v14, 0xffff0000, v14
	v_and_b32_e32 v23, 0xffff0000, v10
	v_lshlrev_b32_e32 v10, 16, v15
	v_mul_f32_e32 v19, 0xbfb8aa3b, v19
	v_mul_f32_e32 v14, 0xbfb8aa3b, v14
	v_mul_f32_e32 v10, 0xbfb8aa3b, v10
	v_exp_f32_e32 v19, v19
	v_exp_f32_e32 v14, v14
	v_exp_f32_e32 v10, v10
	v_add_f32_e32 v19, 1.0, v19
	v_add_f32_e32 v14, 1.0, v14
	v_add_f32_e32 v10, 1.0, v10
	v_rcp_f32_e32 v20, v19
	v_rcp_f32_e32 v21, v14
	v_rcp_f32_e32 v14, v10
	v_and_b32_e32 v10, 0xffff0000, v15
	v_mul_f32_e32 v10, 0xbfb8aa3b, v10
	v_exp_f32_e32 v10, v10
	v_pk_mul_f32 v[20:21], v[20:21], v[22:23]
	v_lshlrev_b32_e32 v22, 16, v12
	v_and_b32_e32 v23, 0xffff0000, v12
	v_lshlrev_b32_e32 v12, 16, v17
	v_mul_f32_e32 v12, 0xbfb8aa3b, v12
	v_add_f32_e32 v10, 1.0, v10
	v_exp_f32_e32 v12, v12
	v_rcp_f32_e32 v15, v10
	v_lshlrev_b32_e32 v10, 16, v11
	v_and_b32_e32 v11, 0xffff0000, v11
	v_add_f32_e32 v12, 1.0, v12
	v_pk_mul_f32 v[10:11], v[14:15], v[10:11]
	v_lshlrev_b32_e32 v14, 16, v16
	v_and_b32_e32 v15, 0xffff0000, v16
	v_rcp_f32_e32 v16, v12
	v_and_b32_e32 v12, 0xffff0000, v17
	v_mul_f32_e32 v14, 0xbfb8aa3b, v14
	v_mul_f32_e32 v15, 0xbfb8aa3b, v15
	v_mul_f32_e32 v12, 0xbfb8aa3b, v12
	v_exp_f32_e32 v14, v14
	v_exp_f32_e32 v15, v15
	v_exp_f32_e32 v12, v12
	v_add_f32_e32 v14, 1.0, v14
	v_add_f32_e32 v15, 1.0, v15
	v_add_f32_e32 v12, 1.0, v12
	v_rcp_f32_e32 v14, v14
	v_rcp_f32_e32 v15, v15
	v_rcp_f32_e32 v17, v12
	v_lshlrev_b32_e32 v12, 16, v13
	v_and_b32_e32 v13, 0xffff0000, v13
	v_pk_mul_f32 v[14:15], v[14:15], v[22:23]
	v_pk_mul_f32 v[16:17], v[16:17], v[12:13]
	v_pk_mul_f32 v[12:13], v[18:19], v[10:11] op_sel_hi:[0,1]
	v_pk_mul_f32 v[10:11], v[18:19], v[20:21] op_sel_hi:[0,1]
	ds_write_b128 v128, v[10:13] offset:36864
	v_pk_mul_f32 v[12:13], v[18:19], v[16:17] op_sel_hi:[0,1]
	v_pk_mul_f32 v[10:11], v[18:19], v[14:15] op_sel_hi:[0,1]
	ds_write_b128 v128, v[10:13] offset:36880
	v_cndmask_b32_e32 v10, 0, v130, vcc
	v_add_u32_e32 v10, s70, v10
	v_mad_i64_i32 v[10:11], s[72:73], v10, s33, v[86:87]
	v_lshl_add_u64 v[10:11], v[10:11], 0, v[64:65]
	v_cndmask_b32_e64 v18, 0, 1.0, vcc
	v_add_co_u32_e32 v14, vcc, s82, v10
	s_nop 1
	v_addc_co_u32_e32 v15, vcc, 0, v11, vcc
	s_waitcnt vmcnt(6)
	v_mov_b32_e32 v10, v182
	v_mov_b32_e32 v11, v183
	v_mov_b32_e32 v12, v184
	v_mov_b32_e32 v13, v185
	v_mov_b32_e32 v14, v186
	v_mov_b32_e32 v15, v187
	v_mov_b32_e32 v16, v188
	v_mov_b32_e32 v17, v189
	v_cmp_lt_i32_e32 vcc, s71, v132
	v_lshlrev_b32_e32 v22, 16, v10
	v_lshlrev_b32_e32 v19, 16, v14
	v_and_b32_e32 v14, 0xffff0000, v14
	v_and_b32_e32 v23, 0xffff0000, v10
	v_lshlrev_b32_e32 v10, 16, v15
	v_mul_f32_e32 v19, 0xbfb8aa3b, v19
	v_mul_f32_e32 v14, 0xbfb8aa3b, v14
	v_mul_f32_e32 v10, 0xbfb8aa3b, v10
	v_exp_f32_e32 v19, v19
	v_exp_f32_e32 v14, v14
	v_exp_f32_e32 v10, v10
	v_add_f32_e32 v19, 1.0, v19
	v_add_f32_e32 v14, 1.0, v14
	v_add_f32_e32 v10, 1.0, v10
	v_rcp_f32_e32 v20, v19
	v_rcp_f32_e32 v21, v14
	v_rcp_f32_e32 v14, v10
	v_and_b32_e32 v10, 0xffff0000, v15
	v_mul_f32_e32 v10, 0xbfb8aa3b, v10
	v_exp_f32_e32 v10, v10
	v_pk_mul_f32 v[20:21], v[20:21], v[22:23]
	v_lshlrev_b32_e32 v22, 16, v12
	v_and_b32_e32 v23, 0xffff0000, v12
	v_lshlrev_b32_e32 v12, 16, v17
	v_mul_f32_e32 v12, 0xbfb8aa3b, v12
	v_add_f32_e32 v10, 1.0, v10
	v_exp_f32_e32 v12, v12
	v_rcp_f32_e32 v15, v10
	v_lshlrev_b32_e32 v10, 16, v11
	v_and_b32_e32 v11, 0xffff0000, v11
	v_add_f32_e32 v12, 1.0, v12
	v_pk_mul_f32 v[10:11], v[14:15], v[10:11]
	v_lshlrev_b32_e32 v14, 16, v16
	v_and_b32_e32 v15, 0xffff0000, v16
	v_rcp_f32_e32 v16, v12
	v_and_b32_e32 v12, 0xffff0000, v17
	v_mul_f32_e32 v14, 0xbfb8aa3b, v14
	v_mul_f32_e32 v15, 0xbfb8aa3b, v15
	v_mul_f32_e32 v12, 0xbfb8aa3b, v12
	v_exp_f32_e32 v14, v14
	v_exp_f32_e32 v15, v15
	v_exp_f32_e32 v12, v12
	v_add_f32_e32 v14, 1.0, v14
	v_add_f32_e32 v15, 1.0, v15
	v_add_f32_e32 v12, 1.0, v12
	v_rcp_f32_e32 v14, v14
	v_rcp_f32_e32 v15, v15
	v_rcp_f32_e32 v17, v12
	v_lshlrev_b32_e32 v12, 16, v13
	v_and_b32_e32 v13, 0xffff0000, v13
	v_pk_mul_f32 v[14:15], v[14:15], v[22:23]
	v_pk_mul_f32 v[16:17], v[16:17], v[12:13]
	v_pk_mul_f32 v[12:13], v[18:19], v[10:11] op_sel_hi:[0,1]
	v_pk_mul_f32 v[10:11], v[18:19], v[20:21] op_sel_hi:[0,1]
	ds_write_b128 v131, v[10:13] offset:36864
	v_pk_mul_f32 v[12:13], v[18:19], v[16:17] op_sel_hi:[0,1]
	v_pk_mul_f32 v[10:11], v[18:19], v[14:15] op_sel_hi:[0,1]
	ds_write_b128 v131, v[10:13] offset:36880
	v_cndmask_b32_e32 v10, 0, v133, vcc
	v_add_u32_e32 v10, s70, v10
	v_mad_i64_i32 v[10:11], s[72:73], v10, s33, v[86:87]
	v_lshl_add_u64 v[10:11], v[10:11], 0, v[66:67]
	v_cndmask_b32_e64 v18, 0, 1.0, vcc
	v_add_co_u32_e32 v14, vcc, s82, v10
	s_add_i32 s72, s70, s84
	s_nop 0
	v_addc_co_u32_e32 v15, vcc, 0, v11, vcc
	s_waitcnt vmcnt(0)
	v_mov_b32_e32 v10, v152
	v_mov_b32_e32 v11, v153
	v_mov_b32_e32 v12, v154
	v_mov_b32_e32 v13, v155
	v_mov_b32_e32 v14, v156
	v_mov_b32_e32 v15, v157
	v_mov_b32_e32 v16, v158
	v_mov_b32_e32 v17, v159
	s_ashr_i32 s73, s72, 31
	s_lshl_b64 s[72:73], s[72:73], 11
	v_lshlrev_b32_e32 v22, 16, v10
	v_lshlrev_b32_e32 v19, 16, v14
	v_and_b32_e32 v14, 0xffff0000, v14
	v_and_b32_e32 v23, 0xffff0000, v10
	v_lshlrev_b32_e32 v10, 16, v15
	v_mul_f32_e32 v19, 0xbfb8aa3b, v19
	v_mul_f32_e32 v14, 0xbfb8aa3b, v14
	v_mul_f32_e32 v10, 0xbfb8aa3b, v10
	v_exp_f32_e32 v19, v19
	v_exp_f32_e32 v14, v14
	v_exp_f32_e32 v10, v10
	v_add_f32_e32 v19, 1.0, v19
	v_add_f32_e32 v14, 1.0, v14
	v_add_f32_e32 v10, 1.0, v10
	v_rcp_f32_e32 v20, v19
	v_rcp_f32_e32 v21, v14
	v_rcp_f32_e32 v14, v10
	v_and_b32_e32 v10, 0xffff0000, v15
	v_mul_f32_e32 v10, 0xbfb8aa3b, v10
	v_exp_f32_e32 v10, v10
	v_pk_mul_f32 v[20:21], v[20:21], v[22:23]
	v_lshlrev_b32_e32 v22, 16, v12
	v_and_b32_e32 v23, 0xffff0000, v12
	v_lshlrev_b32_e32 v12, 16, v17
	v_mul_f32_e32 v12, 0xbfb8aa3b, v12
	v_add_f32_e32 v10, 1.0, v10
	v_exp_f32_e32 v12, v12
	v_rcp_f32_e32 v15, v10
	v_lshlrev_b32_e32 v10, 16, v11
	v_and_b32_e32 v11, 0xffff0000, v11
	v_add_f32_e32 v12, 1.0, v12
	v_pk_mul_f32 v[10:11], v[14:15], v[10:11]
	v_lshlrev_b32_e32 v14, 16, v16
	v_and_b32_e32 v15, 0xffff0000, v16
	v_rcp_f32_e32 v16, v12
	v_and_b32_e32 v12, 0xffff0000, v17
	v_mul_f32_e32 v14, 0xbfb8aa3b, v14
	v_mul_f32_e32 v15, 0xbfb8aa3b, v15
	v_mul_f32_e32 v12, 0xbfb8aa3b, v12
	v_exp_f32_e32 v14, v14
	v_exp_f32_e32 v15, v15
	v_exp_f32_e32 v12, v12
	v_add_f32_e32 v14, 1.0, v14
	v_add_f32_e32 v15, 1.0, v15
	v_add_f32_e32 v12, 1.0, v12
	v_rcp_f32_e32 v14, v14
	v_rcp_f32_e32 v15, v15
	v_rcp_f32_e32 v17, v12
	v_lshlrev_b32_e32 v12, 16, v13
	v_and_b32_e32 v13, 0xffff0000, v13
	v_pk_mul_f32 v[14:15], v[14:15], v[22:23]
	v_pk_mul_f32 v[16:17], v[16:17], v[12:13]
	v_pk_mul_f32 v[12:13], v[18:19], v[10:11] op_sel_hi:[0,1]
	v_pk_mul_f32 v[10:11], v[18:19], v[20:21] op_sel_hi:[0,1]
	ds_write_b128 v134, v[10:13] offset:36864
	v_pk_mul_f32 v[12:13], v[18:19], v[16:17] op_sel_hi:[0,1]
	v_pk_mul_f32 v[10:11], v[18:19], v[14:15] op_sel_hi:[0,1]
	ds_write_b128 v134, v[10:13] offset:36880
	s_waitcnt lgkmcnt(0)
	s_barrier
	ds_read2st64_b32 v[10:11], v136 offset0:144 offset1:148
	ds_read2st64_b32 v[12:13], v136 offset0:180 offset1:184
	ds_read2st64_b32 v[14:15], v136 offset0:184 offset1:188
	ds_read2st64_b32 v[16:17], v136 offset0:188 offset1:192
	ds_read2st64_b32 v[18:19], v136 offset0:192 offset1:196
	s_waitcnt lgkmcnt(4)
	v_fma_f32 v63, v116, v10, v120
	v_fmac_f32_e32 v63, v117, v11
	v_fma_f32 v65, v116, v11, v120
	ds_read2st64_b32 v[10:11], v136 offset0:152 offset1:156
	ds_read2st64_b32 v[20:21], v136 offset0:196 offset1:200
	ds_read2st64_b32 v[22:23], v136 offset0:200 offset1:204
	ds_read2st64_b32 v[24:25], v136 offset0:204 offset1:208
	ds_read2st64_b32 v[26:27], v136 offset0:212 offset1:216
	s_waitcnt lgkmcnt(4)
	v_fmac_f32_e32 v63, v118, v10
	v_fmac_f32_e32 v65, v117, v10
	v_fma_f32 v67, v116, v10, v120
	v_fmac_f32_e32 v63, v119, v11
	v_fmac_f32_e32 v65, v118, v11
	v_fmac_f32_e32 v67, v117, v11
	v_fma_f32 v68, v116, v11, v120
	ds_read2st64_b32 v[10:11], v136 offset0:160 offset1:164
	ds_read2st64_b32 v[28:29], v136 offset0:220 offset1:224
	ds_read2st64_b32 v[30:31], v136 offset0:228 offset1:232
	ds_read2st64_b32 v[32:33], v136 offset0:236 offset1:240
	ds_read2st64_b32 v[34:35], v136 offset0:244 offset1:248
	s_waitcnt lgkmcnt(4)
	v_fmac_f32_e32 v63, v89, v10
	v_fmac_f32_e32 v65, v119, v10
	v_fmac_f32_e32 v67, v118, v10
	v_fmac_f32_e32 v68, v117, v10
	v_fma_f32 v69, v116, v10, v120
	v_fmac_f32_e32 v63, v97, v11
	v_fmac_f32_e32 v65, v89, v11
	v_fmac_f32_e32 v67, v119, v11
	v_fmac_f32_e32 v68, v118, v11
	v_fmac_f32_e32 v69, v117, v11
	v_fma_f32 v70, v116, v11, v120
	ds_read2st64_b32 v[10:11], v136 offset0:168 offset1:172
	ds_read2st64_b32 v[36:37], v137 offset0:112 offset1:116
	ds_read2st64_b32 v[38:39], v137 offset0:120 offset1:124
	ds_read2st64_b32 v[40:41], v137 offset0:128 offset1:132
	ds_read2st64_b32 v[42:43], v137 offset0:136 offset1:140
	s_waitcnt lgkmcnt(4)
	v_fmac_f32_e32 v63, v98, v10
	v_fmac_f32_e32 v65, v97, v10
	v_fmac_f32_e32 v67, v89, v10
	v_fmac_f32_e32 v68, v119, v10
	v_fmac_f32_e32 v69, v118, v10
	v_fmac_f32_e32 v70, v117, v10
	v_fma_f32 v71, v116, v10, v120
	v_fmac_f32_e32 v63, v99, v11
	v_fmac_f32_e32 v65, v98, v11
	v_fmac_f32_e32 v67, v97, v11
	v_fmac_f32_e32 v68, v89, v11
	v_fmac_f32_e32 v69, v119, v11
	v_fmac_f32_e32 v70, v118, v11
	v_fmac_f32_e32 v71, v117, v11
	v_fma_f32 v72, v116, v11, v120
	ds_read2st64_b32 v[10:11], v136 offset0:176 offset1:180
	ds_read2st64_b32 v[44:45], v137 offset0:144 offset1:148
	s_waitcnt lgkmcnt(1)
	v_fmac_f32_e32 v72, v117, v10
	v_fmac_f32_e32 v71, v118, v10
	v_fmac_f32_e32 v72, v118, v11
	v_fmac_f32_e32 v70, v119, v10
	v_fmac_f32_e32 v71, v119, v11
	v_fmac_f32_e32 v72, v119, v13
	v_fmac_f32_e32 v69, v89, v10
	v_fmac_f32_e32 v70, v89, v11
	v_fmac_f32_e32 v71, v89, v13
	v_fmac_f32_e32 v72, v89, v15
	v_fmac_f32_e32 v68, v97, v10
	v_fmac_f32_e32 v69, v97, v11
	v_fmac_f32_e32 v70, v97, v13
	v_fmac_f32_e32 v71, v97, v15
	v_fmac_f32_e32 v72, v97, v17
	v_fmac_f32_e32 v63, v90, v10
	v_fmac_f32_e32 v65, v99, v10
	v_fmac_f32_e32 v67, v98, v10
	v_fmac_f32_e32 v68, v98, v11
	v_fmac_f32_e32 v69, v98, v13
	v_fmac_f32_e32 v70, v98, v15
	v_fmac_f32_e32 v71, v98, v17
	v_fmac_f32_e32 v72, v98, v19
	v_fmac_f32_e32 v63, v91, v11
	v_fmac_f32_e32 v65, v90, v11
	v_fmac_f32_e32 v67, v99, v11
	v_fmac_f32_e32 v68, v99, v13
	v_fmac_f32_e32 v69, v99, v15
	v_fmac_f32_e32 v70, v99, v17
	v_fmac_f32_e32 v71, v99, v19
	v_fmac_f32_e32 v72, v99, v21
	v_fma_f32 v10, v116, v10, v120
	v_fma_f32 v11, v116, v12, v120
	v_fmac_f32_e32 v65, v91, v13
	v_fmac_f32_e32 v67, v90, v13
	v_fmac_f32_e32 v68, v90, v15
	v_fmac_f32_e32 v69, v90, v17
	v_fmac_f32_e32 v70, v90, v19
	v_fmac_f32_e32 v71, v90, v21
	v_fmac_f32_e32 v72, v90, v23
	v_fmac_f32_e32 v10, v117, v12
	v_fmac_f32_e32 v11, v117, v14
	v_fma_f32 v12, v116, v14, v120
	v_fmac_f32_e32 v63, v92, v13
	v_fmac_f32_e32 v65, v92, v15
	v_fmac_f32_e32 v67, v91, v15
	v_fmac_f32_e32 v68, v91, v17
	v_fmac_f32_e32 v69, v91, v19
	v_fmac_f32_e32 v70, v91, v21
	v_fmac_f32_e32 v71, v91, v23
	v_fmac_f32_e32 v72, v91, v25
	v_fmac_f32_e32 v10, v118, v14
	v_fmac_f32_e32 v11, v118, v16
	v_fmac_f32_e32 v12, v117, v16
	v_fma_f32 v13, v116, v16, v120
	v_fmac_f32_e32 v63, v93, v15
	v_fmac_f32_e32 v65, v93, v17
	v_fmac_f32_e32 v67, v92, v17
	v_fmac_f32_e32 v68, v92, v19
	v_fmac_f32_e32 v69, v92, v21
	v_fmac_f32_e32 v70, v92, v23
	v_fmac_f32_e32 v71, v92, v25
	v_fmac_f32_e32 v72, v92, v26
	v_fmac_f32_e32 v10, v119, v16
	v_fmac_f32_e32 v11, v119, v18
	v_fmac_f32_e32 v12, v118, v18
	v_fmac_f32_e32 v13, v117, v18
	v_fma_f32 v14, v116, v18, v120
	v_fmac_f32_e32 v63, v94, v17
	v_fmac_f32_e32 v65, v94, v19
	v_fmac_f32_e32 v67, v93, v19
	v_fmac_f32_e32 v68, v93, v21
	v_fmac_f32_e32 v69, v93, v23
	v_fmac_f32_e32 v70, v93, v25
	v_fmac_f32_e32 v71, v93, v26
	v_fmac_f32_e32 v72, v93, v27
	v_fmac_f32_e32 v10, v89, v18
	v_fmac_f32_e32 v11, v89, v20
	v_fmac_f32_e32 v12, v119, v20
	v_fmac_f32_e32 v13, v118, v20
	v_fmac_f32_e32 v14, v117, v20
	v_fma_f32 v15, v116, v20, v120
	v_fmac_f32_e32 v63, v100, v19
	v_fmac_f32_e32 v65, v100, v21
	v_fmac_f32_e32 v67, v94, v21
	v_fmac_f32_e32 v68, v94, v23
	v_fmac_f32_e32 v69, v94, v25
	v_fmac_f32_e32 v70, v94, v26
	v_fmac_f32_e32 v71, v94, v27
	v_fmac_f32_e32 v72, v94, v28
	v_fmac_f32_e32 v10, v97, v20
	v_fmac_f32_e32 v11, v97, v22
	v_fmac_f32_e32 v12, v89, v22
	v_fmac_f32_e32 v13, v119, v22
	v_fmac_f32_e32 v14, v118, v22
	v_fmac_f32_e32 v15, v117, v22
	v_fma_f32 v16, v116, v22, v120
	v_fmac_f32_e32 v63, v101, v21
	v_fmac_f32_e32 v65, v101, v23
	v_fmac_f32_e32 v67, v100, v23
	v_fmac_f32_e32 v68, v100, v25
	v_fmac_f32_e32 v69, v100, v26
	v_fmac_f32_e32 v70, v100, v27
	v_fmac_f32_e32 v71, v100, v28
	v_fmac_f32_e32 v72, v100, v29
	v_fmac_f32_e32 v10, v98, v22
	v_fmac_f32_e32 v11, v98, v24
	v_fmac_f32_e32 v12, v97, v24
	v_fmac_f32_e32 v13, v89, v24
	v_fmac_f32_e32 v14, v119, v24
	v_fmac_f32_e32 v15, v118, v24
	v_fmac_f32_e32 v16, v117, v24
	v_fma_f32 v18, v116, v24, v120
	v_fmac_f32_e32 v63, v102, v23
	v_fmac_f32_e32 v65, v102, v25
	v_fmac_f32_e32 v67, v101, v25
	v_fmac_f32_e32 v68, v101, v26
	v_fmac_f32_e32 v69, v101, v27
	v_fmac_f32_e32 v70, v101, v28
	v_fmac_f32_e32 v71, v101, v29
	v_fmac_f32_e32 v72, v101, v30
	v_fmac_f32_e32 v10, v99, v24
	v_fmac_f32_e32 v11, v99, v25
	v_fmac_f32_e32 v12, v98, v25
	v_fmac_f32_e32 v13, v97, v25
	v_fmac_f32_e32 v14, v89, v25
	v_fmac_f32_e32 v15, v119, v25
	v_fmac_f32_e32 v16, v118, v25
	v_fmac_f32_e32 v18, v117, v25
	v_fmac_f32_e32 v63, v95, v25
	v_fmac_f32_e32 v65, v95, v26
	v_fmac_f32_e32 v67, v102, v26
	v_fmac_f32_e32 v68, v102, v27
	v_fmac_f32_e32 v69, v102, v28
	v_fmac_f32_e32 v70, v102, v29
	v_fmac_f32_e32 v71, v102, v30
	v_fmac_f32_e32 v72, v102, v31
	ds_read_b32 v17, v136 offset:64512
	v_fmac_f32_e32 v10, v90, v25
	v_fmac_f32_e32 v11, v90, v26
	v_fmac_f32_e32 v12, v99, v26
	v_fmac_f32_e32 v13, v98, v26
	v_fmac_f32_e32 v14, v97, v26
	v_fmac_f32_e32 v15, v89, v26
	v_fmac_f32_e32 v16, v119, v26
	v_fmac_f32_e32 v18, v118, v26
	v_fmac_f32_e32 v63, v96, v26
	v_fmac_f32_e32 v65, v96, v27
	v_fmac_f32_e32 v67, v95, v27
	v_fmac_f32_e32 v68, v95, v28
	v_fmac_f32_e32 v69, v95, v29
	v_fmac_f32_e32 v70, v95, v30
	v_fmac_f32_e32 v71, v95, v31
	v_fmac_f32_e32 v72, v95, v32
	v_fmac_f32_e32 v10, v91, v26
	v_fmac_f32_e32 v11, v91, v27
	v_fmac_f32_e32 v12, v90, v27
	v_fmac_f32_e32 v13, v99, v27
	v_fmac_f32_e32 v14, v98, v27
	v_fmac_f32_e32 v15, v97, v27
	v_fmac_f32_e32 v16, v89, v27
	v_fmac_f32_e32 v18, v119, v27
	v_fmac_f32_e32 v63, v105, v27
	v_fmac_f32_e32 v65, v105, v28
	v_fmac_f32_e32 v67, v96, v28
	v_fmac_f32_e32 v68, v96, v29
	v_fmac_f32_e32 v69, v96, v30
	v_fmac_f32_e32 v70, v96, v31
	v_fmac_f32_e32 v71, v96, v32
	v_fmac_f32_e32 v72, v96, v33
	v_fmac_f32_e32 v10, v92, v27
	v_fmac_f32_e32 v11, v92, v28
	v_fmac_f32_e32 v12, v91, v28
	v_fmac_f32_e32 v13, v90, v28
	v_fmac_f32_e32 v14, v99, v28
	v_fmac_f32_e32 v15, v98, v28
	v_fmac_f32_e32 v16, v97, v28
	v_fmac_f32_e32 v18, v89, v28
	v_fmac_f32_e32 v63, v106, v28
	v_fmac_f32_e32 v65, v106, v29
	v_fmac_f32_e32 v67, v105, v29
	v_fmac_f32_e32 v68, v105, v30
	v_fmac_f32_e32 v69, v105, v31
	v_fmac_f32_e32 v70, v105, v32
	v_fmac_f32_e32 v71, v105, v33
	v_fmac_f32_e32 v72, v105, v34
	v_fmac_f32_e32 v10, v93, v28
	v_fmac_f32_e32 v11, v93, v29
	v_fmac_f32_e32 v12, v92, v29
	v_fmac_f32_e32 v13, v91, v29
	v_fmac_f32_e32 v14, v90, v29
	v_fmac_f32_e32 v15, v99, v29
	v_fmac_f32_e32 v16, v98, v29
	v_fmac_f32_e32 v18, v97, v29
	v_fmac_f32_e32 v63, v107, v29
	v_fmac_f32_e32 v65, v107, v30
	v_fmac_f32_e32 v67, v106, v30
	v_fmac_f32_e32 v68, v106, v31
	v_fmac_f32_e32 v69, v106, v32
	v_fmac_f32_e32 v70, v106, v33
	v_fmac_f32_e32 v71, v106, v34
	v_fmac_f32_e32 v72, v106, v35
	v_fmac_f32_e32 v10, v94, v29
	v_fmac_f32_e32 v11, v94, v30
	v_fmac_f32_e32 v12, v93, v30
	v_fmac_f32_e32 v13, v92, v30
	v_fmac_f32_e32 v14, v91, v30
	v_fmac_f32_e32 v15, v90, v30
	v_fmac_f32_e32 v16, v99, v30
	v_fmac_f32_e32 v18, v98, v30
	v_fmac_f32_e32 v63, v103, v30
	v_fmac_f32_e32 v65, v103, v31
	v_fmac_f32_e32 v67, v107, v31
	v_fmac_f32_e32 v68, v107, v32
	v_fmac_f32_e32 v69, v107, v33
	v_fmac_f32_e32 v70, v107, v34
	v_fmac_f32_e32 v71, v107, v35
	s_waitcnt lgkmcnt(0)
	v_fmac_f32_e32 v72, v107, v17
	v_fmac_f32_e32 v10, v100, v30
	v_fmac_f32_e32 v11, v100, v31
	v_fmac_f32_e32 v12, v94, v31
	v_fmac_f32_e32 v13, v93, v31
	v_fmac_f32_e32 v14, v92, v31
	v_fmac_f32_e32 v15, v91, v31
	v_fmac_f32_e32 v16, v90, v31
	v_fmac_f32_e32 v18, v99, v31
	v_fmac_f32_e32 v63, v104, v31
	v_fmac_f32_e32 v65, v104, v32
	v_fmac_f32_e32 v67, v103, v32
	v_fmac_f32_e32 v68, v103, v33
	v_fmac_f32_e32 v69, v103, v34
	v_fmac_f32_e32 v70, v103, v35
	v_fmac_f32_e32 v71, v103, v17
	v_fmac_f32_e32 v72, v103, v36
	v_fmac_f32_e32 v10, v101, v31
	v_fmac_f32_e32 v11, v101, v32
	v_fmac_f32_e32 v12, v100, v32
	v_fmac_f32_e32 v13, v94, v32
	v_fmac_f32_e32 v14, v93, v32
	v_fmac_f32_e32 v15, v92, v32
	v_fmac_f32_e32 v16, v91, v32
	v_fmac_f32_e32 v18, v90, v32
	v_fmac_f32_e32 v63, v112, v32
	v_fmac_f32_e32 v65, v112, v33
	v_fmac_f32_e32 v67, v104, v33
	v_fmac_f32_e32 v68, v104, v34
	v_fmac_f32_e32 v69, v104, v35
	v_fmac_f32_e32 v70, v104, v17
	v_fmac_f32_e32 v71, v104, v36
	v_fmac_f32_e32 v72, v104, v37
	v_fmac_f32_e32 v10, v102, v32
	v_fmac_f32_e32 v11, v102, v33
	v_fmac_f32_e32 v12, v101, v33
	v_fmac_f32_e32 v13, v100, v33
	v_fmac_f32_e32 v14, v94, v33
	v_fmac_f32_e32 v15, v93, v33
	v_fmac_f32_e32 v16, v92, v33
	v_fmac_f32_e32 v18, v91, v33
	v_fmac_f32_e32 v63, v108, v33
	v_fmac_f32_e32 v65, v108, v34
	v_fmac_f32_e32 v67, v112, v34
	v_fmac_f32_e32 v68, v112, v35
	v_fmac_f32_e32 v69, v112, v17
	v_fmac_f32_e32 v70, v112, v36
	v_fmac_f32_e32 v71, v112, v37
	v_fmac_f32_e32 v72, v112, v38
	v_fmac_f32_e32 v10, v95, v33
	v_fmac_f32_e32 v11, v95, v34
	v_fmac_f32_e32 v12, v102, v34
	v_fmac_f32_e32 v13, v101, v34
	v_fmac_f32_e32 v14, v100, v34
	v_fmac_f32_e32 v15, v94, v34
	v_fmac_f32_e32 v16, v93, v34
	v_fmac_f32_e32 v18, v92, v34
	v_fmac_f32_e32 v63, v109, v34
	v_fmac_f32_e32 v65, v109, v35
	v_fmac_f32_e32 v67, v108, v35
	v_fmac_f32_e32 v68, v108, v17
	v_fmac_f32_e32 v69, v108, v36
	v_fmac_f32_e32 v70, v108, v37
	v_fmac_f32_e32 v71, v108, v38
	v_fmac_f32_e32 v72, v108, v39
	v_fmac_f32_e32 v10, v96, v34
	v_fmac_f32_e32 v11, v96, v35
	v_fmac_f32_e32 v12, v95, v35
	v_fmac_f32_e32 v13, v102, v35
	v_fmac_f32_e32 v14, v101, v35
	v_fmac_f32_e32 v15, v100, v35
	v_fmac_f32_e32 v16, v94, v35
	v_fmac_f32_e32 v18, v93, v35
	v_fmac_f32_e32 v63, v110, v35
	v_fmac_f32_e32 v65, v110, v17
	v_fmac_f32_e32 v67, v109, v17
	v_fmac_f32_e32 v68, v109, v36
	v_fmac_f32_e32 v69, v109, v37
	v_fmac_f32_e32 v70, v109, v38
	v_fmac_f32_e32 v71, v109, v39
	v_fmac_f32_e32 v72, v109, v40
	v_fmac_f32_e32 v10, v105, v35
	v_fmac_f32_e32 v11, v105, v17
	v_fmac_f32_e32 v12, v96, v17
	v_fmac_f32_e32 v13, v95, v17
	v_fmac_f32_e32 v14, v102, v17
	v_fmac_f32_e32 v15, v101, v17
	v_fmac_f32_e32 v16, v100, v17
	v_fmac_f32_e32 v18, v94, v17
	v_fmac_f32_e32 v63, v111, v17
	v_fmac_f32_e32 v65, v111, v36
	v_fmac_f32_e32 v67, v110, v36
	v_fmac_f32_e32 v68, v110, v37
	v_fmac_f32_e32 v69, v110, v38
	v_fmac_f32_e32 v70, v110, v39
	v_fmac_f32_e32 v71, v110, v40
	v_fmac_f32_e32 v72, v110, v41
	v_fmac_f32_e32 v10, v106, v17
	v_fmac_f32_e32 v11, v106, v36
	v_fmac_f32_e32 v12, v105, v36
	v_fmac_f32_e32 v13, v96, v36
	v_fmac_f32_e32 v14, v95, v36
	v_fmac_f32_e32 v15, v102, v36
	v_fmac_f32_e32 v16, v101, v36
	v_fmac_f32_e32 v18, v100, v36
	v_fmac_f32_e32 v63, v113, v36
	v_fmac_f32_e32 v65, v113, v37
	v_fmac_f32_e32 v67, v111, v37
	v_fmac_f32_e32 v68, v111, v38
	v_fmac_f32_e32 v69, v111, v39
	v_fmac_f32_e32 v70, v111, v40
	v_fmac_f32_e32 v71, v111, v41
	v_fmac_f32_e32 v72, v111, v42
	v_fmac_f32_e32 v10, v107, v36
	v_fmac_f32_e32 v11, v107, v37
	v_fmac_f32_e32 v12, v106, v37
	v_fmac_f32_e32 v13, v105, v37
	v_fmac_f32_e32 v14, v96, v37
	v_fmac_f32_e32 v15, v95, v37
	v_fmac_f32_e32 v16, v102, v37
	v_fmac_f32_e32 v18, v101, v37
	v_fmac_f32_e32 v63, v114, v37
	v_fmac_f32_e32 v65, v114, v38
	v_fmac_f32_e32 v67, v113, v38
	v_fmac_f32_e32 v68, v113, v39
	v_fmac_f32_e32 v69, v113, v40
	v_fmac_f32_e32 v70, v113, v41
	v_fmac_f32_e32 v71, v113, v42
	v_fmac_f32_e32 v72, v113, v43
	v_fmac_f32_e32 v10, v103, v37
	v_fmac_f32_e32 v11, v103, v38
	v_fmac_f32_e32 v12, v107, v38
	v_fmac_f32_e32 v13, v106, v38
	v_fmac_f32_e32 v14, v105, v38
	v_fmac_f32_e32 v15, v96, v38
	v_fmac_f32_e32 v16, v95, v38
	v_fmac_f32_e32 v18, v102, v38
	v_fmac_f32_e32 v63, v115, v38
	v_fmac_f32_e32 v65, v115, v39
	v_fmac_f32_e32 v67, v114, v39
	v_fmac_f32_e32 v68, v114, v40
	v_fmac_f32_e32 v69, v114, v41
	v_fmac_f32_e32 v70, v114, v42
	v_fmac_f32_e32 v71, v114, v43
	v_fmac_f32_e32 v72, v114, v44
	v_fmac_f32_e32 v10, v104, v38
	v_fmac_f32_e32 v11, v104, v39
	v_fmac_f32_e32 v12, v103, v39
	v_fmac_f32_e32 v13, v107, v39
	v_fmac_f32_e32 v14, v106, v39
	v_fmac_f32_e32 v15, v105, v39
	v_fmac_f32_e32 v16, v96, v39
	v_fmac_f32_e32 v18, v95, v39
	v_fmac_f32_e32 v67, v115, v40
	v_fmac_f32_e32 v68, v115, v41
	v_fmac_f32_e32 v69, v115, v42
	v_fmac_f32_e32 v70, v115, v43
	v_fmac_f32_e32 v71, v115, v44
	v_fmac_f32_e32 v72, v115, v45
	ds_write2st64_b32 v55, v63, v65 offset1:4
	ds_write2st64_b32 v55, v67, v68 offset0:8 offset1:12
	ds_write2st64_b32 v55, v69, v70 offset0:16 offset1:20
	ds_write2st64_b32 v55, v71, v72 offset0:24 offset1:28
	v_fmac_f32_e32 v10, v112, v39
	v_fmac_f32_e32 v11, v112, v40
	v_fmac_f32_e32 v12, v104, v40
	v_fmac_f32_e32 v13, v103, v40
	v_fmac_f32_e32 v14, v107, v40
	v_fmac_f32_e32 v15, v106, v40
	v_fmac_f32_e32 v16, v105, v40
	v_fmac_f32_e32 v18, v96, v40
	v_fmac_f32_e32 v10, v108, v40
	v_fmac_f32_e32 v11, v108, v41
	v_fmac_f32_e32 v12, v112, v41
	v_fmac_f32_e32 v13, v104, v41
	v_fmac_f32_e32 v14, v103, v41
	v_fmac_f32_e32 v15, v107, v41
	v_fmac_f32_e32 v16, v106, v41
	v_fmac_f32_e32 v18, v105, v41
	ds_read2st64_b32 v[20:21], v137 offset0:152 offset1:156
	v_fmac_f32_e32 v10, v109, v41
	v_fmac_f32_e32 v11, v109, v42
	v_fmac_f32_e32 v12, v108, v42
	v_fmac_f32_e32 v13, v112, v42
	v_fmac_f32_e32 v14, v104, v42
	v_fmac_f32_e32 v15, v103, v42
	v_fmac_f32_e32 v16, v107, v42
	v_fmac_f32_e32 v18, v106, v42
	v_fmac_f32_e32 v10, v110, v42
	v_fmac_f32_e32 v11, v110, v43
	v_fmac_f32_e32 v12, v109, v43
	v_fmac_f32_e32 v13, v108, v43
	v_fmac_f32_e32 v14, v112, v43
	v_fmac_f32_e32 v15, v104, v43
	v_fmac_f32_e32 v16, v103, v43
	v_fmac_f32_e32 v18, v107, v43
	v_fmac_f32_e32 v10, v111, v43
	v_fmac_f32_e32 v11, v111, v44
	v_fmac_f32_e32 v12, v110, v44
	v_fmac_f32_e32 v13, v109, v44
	v_fmac_f32_e32 v14, v108, v44
	v_fmac_f32_e32 v15, v112, v44
	v_fmac_f32_e32 v16, v104, v44
	v_fmac_f32_e32 v18, v103, v44
	v_fmac_f32_e32 v10, v113, v44
	v_fmac_f32_e32 v11, v113, v45
	v_fmac_f32_e32 v12, v111, v45
	v_fmac_f32_e32 v13, v110, v45
	v_fmac_f32_e32 v14, v109, v45
	v_fmac_f32_e32 v15, v108, v45
	v_fmac_f32_e32 v16, v112, v45
	v_fmac_f32_e32 v18, v104, v45
	v_fmac_f32_e32 v10, v114, v45
	s_waitcnt lgkmcnt(0)
	v_fmac_f32_e32 v11, v114, v20
	v_fmac_f32_e32 v12, v113, v20
	v_fmac_f32_e32 v13, v111, v20
	v_fmac_f32_e32 v14, v110, v20
	v_fmac_f32_e32 v15, v109, v20
	v_fmac_f32_e32 v16, v108, v20
	v_fmac_f32_e32 v18, v112, v20
	v_fmac_f32_e32 v10, v115, v20
	v_fmac_f32_e32 v11, v115, v21
	v_fmac_f32_e32 v12, v114, v21
	v_fmac_f32_e32 v13, v113, v21
	v_fmac_f32_e32 v14, v111, v21
	v_fmac_f32_e32 v15, v110, v21
	v_fmac_f32_e32 v16, v109, v21
	v_fmac_f32_e32 v18, v108, v21
	ds_read2st64_b32 v[20:21], v137 offset0:160 offset1:164
	s_waitcnt lgkmcnt(0)
	v_fmac_f32_e32 v13, v114, v20
	v_fmac_f32_e32 v14, v113, v20
	v_fmac_f32_e32 v15, v111, v20
	v_fmac_f32_e32 v16, v110, v20
	v_fmac_f32_e32 v18, v109, v20
	v_fmac_f32_e32 v12, v115, v20
	v_fmac_f32_e32 v13, v115, v21
	v_fmac_f32_e32 v14, v114, v21
	v_fmac_f32_e32 v15, v113, v21
	v_fmac_f32_e32 v16, v111, v21
	v_fmac_f32_e32 v18, v110, v21
	ds_read2st64_b32 v[20:21], v137 offset0:168 offset1:172
	s_waitcnt lgkmcnt(0)
	v_fmac_f32_e32 v15, v114, v20
	v_fmac_f32_e32 v16, v113, v20
	v_fmac_f32_e32 v18, v111, v20
	v_fmac_f32_e32 v14, v115, v20
	v_fmac_f32_e32 v15, v115, v21
	v_fmac_f32_e32 v16, v114, v21
	v_fmac_f32_e32 v18, v113, v21
	ds_read2st64_b32 v[20:21], v137 offset0:176 offset1:180
	s_waitcnt lgkmcnt(0)
	v_fmac_f32_e32 v18, v114, v20
	v_fmac_f32_e32 v16, v115, v20
	v_fmac_f32_e32 v18, v115, v21
	ds_write2st64_b32 v55, v10, v11 offset0:32 offset1:36
	ds_write2st64_b32 v55, v12, v13 offset0:40 offset1:44
	ds_write2st64_b32 v55, v14, v15 offset0:48 offset1:52
	ds_write2st64_b32 v55, v16, v18 offset0:56 offset1:60
	s_waitcnt lgkmcnt(0)
	s_barrier
	ds_read_b128 v[10:13], v46
	s_waitcnt lgkmcnt(0)
	v_mov_b32_e32 v14, v11
	v_mov_b32_e32 v15, v12
	v_mov_b32_e32 v16, v10
	v_mov_b32_e32 v17, v13
	v_pk_add_f32 v[14:15], v[14:15], v[16:17]
	s_nop 0
	v_add_f32_e32 v14, v14, v15
	v_mov_b32_e32 v15, v1
	s_nop 0
	v_add_f32_dpp v14, v14, v14 row_shr:1 row_mask:0xf bank_mask:0xf bound_ctrl:1
	s_nop 1
	v_add_f32_dpp v14, v14, v14 row_shr:2 row_mask:0xf bank_mask:0xf bound_ctrl:1
	s_nop 1
	v_add_f32_dpp v14, v14, v14 row_shr:4 row_mask:0xf bank_mask:0xf bound_ctrl:1
	s_nop 1
	v_add_f32_dpp v14, v14, v14 row_shr:8 row_mask:0xf bank_mask:0xf bound_ctrl:1
	s_nop 1
	v_mov_b32_dpp v15, v14 row_bcast:15 row_mask:0xa bank_mask:0xf
	v_add_f32_e32 v14, v14, v15
	v_mov_b32_e32 v15, v1
	s_nop 1
	v_mov_b32_dpp v15, v14 row_bcast:31 row_mask:0xc bank_mask:0xf
	v_add_f32_e32 v14, v14, v15
	s_nop 0
	v_readlane_b32 s71, v14, 63
	s_nop 1
	v_fma_f32 v11, s71, v241, v11
	v_fma_f32 v10, s71, v241, v10
	v_fma_f32 v13, s71, v241, v13
	v_fmac_f32_e32 v12, s71, v241
	v_pk_mul_f32 v[14:15], v[12:13], v[12:13]
	v_pk_mul_f32 v[16:17], v[10:11], v[10:11]
	s_nop 0
	v_pk_mov_b32 v[18:19], v[16:17], v[14:15] op_sel:[1,0]
	v_mov_b32_e32 v17, v15
	v_pk_add_f32 v[14:15], v[18:19], v[16:17]
	s_nop 0
	v_add_f32_e32 v14, v14, v15
	v_mov_b32_e32 v15, v1
	s_nop 0
	v_add_f32_dpp v14, v14, v14 row_shr:1 row_mask:0xf bank_mask:0xf bound_ctrl:1
	s_nop 1
	v_add_f32_dpp v14, v14, v14 row_shr:2 row_mask:0xf bank_mask:0xf bound_ctrl:1
	s_nop 1
	v_add_f32_dpp v14, v14, v14 row_shr:4 row_mask:0xf bank_mask:0xf bound_ctrl:1
	s_nop 1
	v_add_f32_dpp v14, v14, v14 row_shr:8 row_mask:0xf bank_mask:0xf bound_ctrl:1
	s_nop 1
	v_mov_b32_dpp v15, v14 row_bcast:15 row_mask:0xa bank_mask:0xf
	v_add_f32_e32 v14, v14, v15
	v_mov_b32_e32 v15, v1
	s_nop 1
	v_mov_b32_dpp v15, v14 row_bcast:31 row_mask:0xc bank_mask:0xf
	v_add_f32_e32 v14, v14, v15
	s_nop 0
	v_readlane_b32 s71, v14, 63
	s_nop 1
	v_fma_f32 v14, s71, v242, v197
	v_rsq_f32_e32 v14, v14
	s_nop 0
	v_pk_mul_f32 v[10:11], v[10:11], v[14:15] op_sel_hi:[1,0]
	s_nop 0
	v_pk_fma_f32 v[10:11], v[2:3], v[10:11], v[6:7]
	v_pk_mul_f32 v[12:13], v[12:13], v[14:15] op_sel_hi:[1,0]
	v_mul_f32_e32 v14, 0xbfb8aa3b, v10
	v_exp_f32_e32 v14, v14
	v_pk_fma_f32 v[12:13], v[4:5], v[12:13], v[8:9]
	v_add_f32_e32 v14, 1.0, v14
	v_rcp_f32_e32 v14, v14
	s_nop 0
	v_mul_f32_e32 v10, v10, v14
	v_mul_f32_e32 v14, 0xbfb8aa3b, v11
	v_exp_f32_e32 v14, v14
	s_nop 0
	v_add_f32_e32 v14, 1.0, v14
	v_rcp_f32_e32 v14, v14
	s_nop 0
	v_mul_f32_e32 v11, v11, v14
	v_cvt_pk_bf16_f32 v10, v10, v11
	v_mul_f32_e32 v11, 0xbfb8aa3b, v12
	v_exp_f32_e32 v11, v11
	s_nop 0
	v_add_f32_e32 v11, 1.0, v11
	v_rcp_f32_e32 v11, v11
	s_nop 0
	v_mul_f32_e32 v11, v12, v11
	v_mul_f32_e32 v12, 0xbfb8aa3b, v13
	v_exp_f32_e32 v12, v12
	s_nop 0
	v_add_f32_e32 v12, 1.0, v12
	v_rcp_f32_e32 v12, v12
	s_nop 0
	v_mul_f32_e32 v12, v13, v12
	v_cvt_pk_bf16_f32 v11, v11, v12
	v_lshl_add_u64 v[12:13], v[60:61], 0, s[72:73]
	global_store_dwordx2 v[12:13], v[10:11], off offset:1536
	ds_read_b128 v[10:13], v47
	s_add_i32 s72, s70, s88
	s_ashr_i32 s73, s72, 31
	s_lshl_b64 s[72:73], s[72:73], 11
	s_waitcnt lgkmcnt(0)
	v_mov_b32_e32 v14, v11
	v_mov_b32_e32 v15, v12
	v_mov_b32_e32 v16, v10
	v_mov_b32_e32 v17, v13
	v_pk_add_f32 v[14:15], v[14:15], v[16:17]
	s_nop 0
	v_add_f32_e32 v14, v14, v15
	v_mov_b32_e32 v15, v1
	s_nop 0
	v_add_f32_dpp v14, v14, v14 row_shr:1 row_mask:0xf bank_mask:0xf bound_ctrl:1
	s_nop 1
	v_add_f32_dpp v14, v14, v14 row_shr:2 row_mask:0xf bank_mask:0xf bound_ctrl:1
	s_nop 1
	v_add_f32_dpp v14, v14, v14 row_shr:4 row_mask:0xf bank_mask:0xf bound_ctrl:1
	s_nop 1
	v_add_f32_dpp v14, v14, v14 row_shr:8 row_mask:0xf bank_mask:0xf bound_ctrl:1
	s_nop 1
	v_mov_b32_dpp v15, v14 row_bcast:15 row_mask:0xa bank_mask:0xf
	v_add_f32_e32 v14, v14, v15
	v_mov_b32_e32 v15, v1
	s_nop 1
	v_mov_b32_dpp v15, v14 row_bcast:31 row_mask:0xc bank_mask:0xf
	v_add_f32_e32 v14, v14, v15
	s_nop 0
	v_readlane_b32 s71, v14, 63
	s_nop 1
	v_fma_f32 v11, s71, v241, v11
	v_fma_f32 v10, s71, v241, v10
	v_fma_f32 v13, s71, v241, v13
	v_fmac_f32_e32 v12, s71, v241
	v_pk_mul_f32 v[14:15], v[12:13], v[12:13]
	v_pk_mul_f32 v[16:17], v[10:11], v[10:11]
	s_nop 0
	v_pk_mov_b32 v[18:19], v[16:17], v[14:15] op_sel:[1,0]
	v_mov_b32_e32 v17, v15
	v_pk_add_f32 v[14:15], v[18:19], v[16:17]
	s_nop 0
	v_add_f32_e32 v14, v14, v15
	v_mov_b32_e32 v15, v1
	s_nop 0
	v_add_f32_dpp v14, v14, v14 row_shr:1 row_mask:0xf bank_mask:0xf bound_ctrl:1
	s_nop 1
	v_add_f32_dpp v14, v14, v14 row_shr:2 row_mask:0xf bank_mask:0xf bound_ctrl:1
	s_nop 1
	v_add_f32_dpp v14, v14, v14 row_shr:4 row_mask:0xf bank_mask:0xf bound_ctrl:1
	s_nop 1
	v_add_f32_dpp v14, v14, v14 row_shr:8 row_mask:0xf bank_mask:0xf bound_ctrl:1
	s_nop 1
	v_mov_b32_dpp v15, v14 row_bcast:15 row_mask:0xa bank_mask:0xf
	v_add_f32_e32 v14, v14, v15
	v_mov_b32_e32 v15, v1
	s_nop 1
	v_mov_b32_dpp v15, v14 row_bcast:31 row_mask:0xc bank_mask:0xf
	v_add_f32_e32 v14, v14, v15
	s_nop 0
	v_readlane_b32 s71, v14, 63
	s_nop 1
	v_fma_f32 v14, s71, v242, v197
	v_rsq_f32_e32 v14, v14
	s_nop 0
	v_pk_mul_f32 v[10:11], v[10:11], v[14:15] op_sel_hi:[1,0]
	s_nop 0
	v_pk_fma_f32 v[10:11], v[2:3], v[10:11], v[6:7]
	v_pk_mul_f32 v[12:13], v[12:13], v[14:15] op_sel_hi:[1,0]
	v_mul_f32_e32 v14, 0xbfb8aa3b, v10
	v_exp_f32_e32 v14, v14
	v_pk_fma_f32 v[12:13], v[4:5], v[12:13], v[8:9]
	v_add_f32_e32 v14, 1.0, v14
	v_rcp_f32_e32 v14, v14
	s_nop 0
	v_mul_f32_e32 v10, v10, v14
	v_mul_f32_e32 v14, 0xbfb8aa3b, v11
	v_exp_f32_e32 v14, v14
	s_nop 0
	v_add_f32_e32 v14, 1.0, v14
	v_rcp_f32_e32 v14, v14
	s_nop 0
	v_mul_f32_e32 v11, v11, v14
	v_cvt_pk_bf16_f32 v10, v10, v11
	v_mul_f32_e32 v11, 0xbfb8aa3b, v12
	v_exp_f32_e32 v11, v11
	s_nop 0
	v_add_f32_e32 v11, 1.0, v11
	v_rcp_f32_e32 v11, v11
	s_nop 0
	v_mul_f32_e32 v11, v12, v11
	v_mul_f32_e32 v12, 0xbfb8aa3b, v13
	v_exp_f32_e32 v12, v12
	s_nop 0
	v_add_f32_e32 v12, 1.0, v12
	v_rcp_f32_e32 v12, v12
	s_nop 0
	v_mul_f32_e32 v12, v13, v12
	v_cvt_pk_bf16_f32 v11, v11, v12
	v_lshl_add_u64 v[12:13], v[60:61], 0, s[72:73]
	global_store_dwordx2 v[12:13], v[10:11], off offset:1536
	ds_read_b128 v[10:13], v48
	s_add_i32 s72, s70, s91
	s_ashr_i32 s73, s72, 31
	s_lshl_b64 s[72:73], s[72:73], 11
	s_add_i32 s70, s70, s87
	s_waitcnt lgkmcnt(0)
	v_mov_b32_e32 v14, v11
	v_mov_b32_e32 v15, v12
	v_mov_b32_e32 v16, v10
	v_mov_b32_e32 v17, v13
	v_pk_add_f32 v[14:15], v[14:15], v[16:17]
	s_nop 0
	v_add_f32_e32 v14, v14, v15
	v_mov_b32_e32 v15, v1
	s_nop 0
	v_add_f32_dpp v14, v14, v14 row_shr:1 row_mask:0xf bank_mask:0xf bound_ctrl:1
	s_nop 1
	v_add_f32_dpp v14, v14, v14 row_shr:2 row_mask:0xf bank_mask:0xf bound_ctrl:1
	s_nop 1
	v_add_f32_dpp v14, v14, v14 row_shr:4 row_mask:0xf bank_mask:0xf bound_ctrl:1
	s_nop 1
	v_add_f32_dpp v14, v14, v14 row_shr:8 row_mask:0xf bank_mask:0xf bound_ctrl:1
	s_nop 1
	v_mov_b32_dpp v15, v14 row_bcast:15 row_mask:0xa bank_mask:0xf
	v_add_f32_e32 v14, v14, v15
	v_mov_b32_e32 v15, v1
	s_nop 1
	v_mov_b32_dpp v15, v14 row_bcast:31 row_mask:0xc bank_mask:0xf
	v_add_f32_e32 v14, v14, v15
	s_nop 0
	v_readlane_b32 s71, v14, 63
	s_nop 1
	v_fma_f32 v11, s71, v241, v11
	v_fma_f32 v10, s71, v241, v10
	v_fma_f32 v13, s71, v241, v13
	v_fmac_f32_e32 v12, s71, v241
	v_pk_mul_f32 v[14:15], v[12:13], v[12:13]
	v_pk_mul_f32 v[16:17], v[10:11], v[10:11]
	s_nop 0
	v_pk_mov_b32 v[18:19], v[16:17], v[14:15] op_sel:[1,0]
	v_mov_b32_e32 v17, v15
	v_pk_add_f32 v[14:15], v[18:19], v[16:17]
	s_nop 0
	v_add_f32_e32 v14, v14, v15
	v_mov_b32_e32 v15, v1
	s_nop 0
	v_add_f32_dpp v14, v14, v14 row_shr:1 row_mask:0xf bank_mask:0xf bound_ctrl:1
	s_nop 1
	v_add_f32_dpp v14, v14, v14 row_shr:2 row_mask:0xf bank_mask:0xf bound_ctrl:1
	s_nop 1
	v_add_f32_dpp v14, v14, v14 row_shr:4 row_mask:0xf bank_mask:0xf bound_ctrl:1
	s_nop 1
	v_add_f32_dpp v14, v14, v14 row_shr:8 row_mask:0xf bank_mask:0xf bound_ctrl:1
	s_nop 1
	v_mov_b32_dpp v15, v14 row_bcast:15 row_mask:0xa bank_mask:0xf
	v_add_f32_e32 v14, v14, v15
	v_mov_b32_e32 v15, v1
	s_nop 1
	v_mov_b32_dpp v15, v14 row_bcast:31 row_mask:0xc bank_mask:0xf
	v_add_f32_e32 v14, v14, v15
	s_nop 0
	v_readlane_b32 s71, v14, 63
	s_nop 1
	v_fma_f32 v14, s71, v242, v197
	v_rsq_f32_e32 v14, v14
	s_nop 0
	v_pk_mul_f32 v[10:11], v[10:11], v[14:15] op_sel_hi:[1,0]
	s_nop 0
	v_pk_fma_f32 v[10:11], v[2:3], v[10:11], v[6:7]
	v_pk_mul_f32 v[12:13], v[12:13], v[14:15] op_sel_hi:[1,0]
	v_mul_f32_e32 v14, 0xbfb8aa3b, v10
	v_exp_f32_e32 v14, v14
	v_pk_fma_f32 v[12:13], v[4:5], v[12:13], v[8:9]
	v_add_f32_e32 v14, 1.0, v14
	v_rcp_f32_e32 v14, v14
	s_nop 0
	v_mul_f32_e32 v10, v10, v14
	v_mul_f32_e32 v14, 0xbfb8aa3b, v11
	v_exp_f32_e32 v14, v14
	s_nop 0
	v_add_f32_e32 v14, 1.0, v14
	v_rcp_f32_e32 v14, v14
	s_nop 0
	v_mul_f32_e32 v11, v11, v14
	v_cvt_pk_bf16_f32 v10, v10, v11
	v_mul_f32_e32 v11, 0xbfb8aa3b, v12
	v_exp_f32_e32 v11, v11
	s_nop 0
	v_add_f32_e32 v11, 1.0, v11
	v_rcp_f32_e32 v11, v11
	s_nop 0
	v_mul_f32_e32 v11, v12, v11
	v_mul_f32_e32 v12, 0xbfb8aa3b, v13
	v_exp_f32_e32 v12, v12
	s_nop 0
	v_add_f32_e32 v12, 1.0, v12
	v_rcp_f32_e32 v12, v12
	s_nop 0
	v_mul_f32_e32 v12, v13, v12
	v_cvt_pk_bf16_f32 v11, v11, v12
	v_lshl_add_u64 v[12:13], v[60:61], 0, s[72:73]
	global_store_dwordx2 v[12:13], v[10:11], off offset:1536
	ds_read_b128 v[10:13], v49
	s_waitcnt lgkmcnt(0)
	v_mov_b32_e32 v14, v11
	v_mov_b32_e32 v15, v12
	v_mov_b32_e32 v16, v10
	v_mov_b32_e32 v17, v13
	v_pk_add_f32 v[14:15], v[14:15], v[16:17]
	s_nop 0
	v_add_f32_e32 v14, v14, v15
	v_mov_b32_e32 v15, v1
	s_nop 0
	v_add_f32_dpp v14, v14, v14 row_shr:1 row_mask:0xf bank_mask:0xf bound_ctrl:1
	s_nop 1
	v_add_f32_dpp v14, v14, v14 row_shr:2 row_mask:0xf bank_mask:0xf bound_ctrl:1
	s_nop 1
	v_add_f32_dpp v14, v14, v14 row_shr:4 row_mask:0xf bank_mask:0xf bound_ctrl:1
	s_nop 1
	v_add_f32_dpp v14, v14, v14 row_shr:8 row_mask:0xf bank_mask:0xf bound_ctrl:1
	s_nop 1
	v_mov_b32_dpp v15, v14 row_bcast:15 row_mask:0xa bank_mask:0xf
	v_add_f32_e32 v14, v14, v15
	v_mov_b32_e32 v15, v1
	s_nop 1
	v_mov_b32_dpp v15, v14 row_bcast:31 row_mask:0xc bank_mask:0xf
	v_add_f32_e32 v14, v14, v15
	s_nop 0
	v_readlane_b32 s71, v14, 63
	s_nop 1
	v_fma_f32 v11, s71, v241, v11
	v_fma_f32 v10, s71, v241, v10
	v_fma_f32 v13, s71, v241, v13
	v_fmac_f32_e32 v12, s71, v241
	v_pk_mul_f32 v[14:15], v[12:13], v[12:13]
	v_pk_mul_f32 v[16:17], v[10:11], v[10:11]
	s_nop 0
	v_pk_mov_b32 v[18:19], v[16:17], v[14:15] op_sel:[1,0]
	v_mov_b32_e32 v17, v15
	v_pk_add_f32 v[14:15], v[18:19], v[16:17]
	s_nop 0
	v_add_f32_e32 v14, v14, v15
	v_mov_b32_e32 v15, v1
	s_nop 0
	v_add_f32_dpp v14, v14, v14 row_shr:1 row_mask:0xf bank_mask:0xf bound_ctrl:1
	s_nop 1
	v_add_f32_dpp v14, v14, v14 row_shr:2 row_mask:0xf bank_mask:0xf bound_ctrl:1
	s_nop 1
	v_add_f32_dpp v14, v14, v14 row_shr:4 row_mask:0xf bank_mask:0xf bound_ctrl:1
	s_nop 1
	v_add_f32_dpp v14, v14, v14 row_shr:8 row_mask:0xf bank_mask:0xf bound_ctrl:1
	s_nop 1
	v_mov_b32_dpp v15, v14 row_bcast:15 row_mask:0xa bank_mask:0xf
	v_add_f32_e32 v14, v14, v15
	v_mov_b32_e32 v15, v1
	s_nop 1
	v_mov_b32_dpp v15, v14 row_bcast:31 row_mask:0xc bank_mask:0xf
	v_add_f32_e32 v14, v14, v15
	s_nop 0
	v_readlane_b32 s71, v14, 63
	s_nop 1
	v_fma_f32 v14, s71, v242, v197
	v_rsq_f32_e32 v14, v14
	s_ashr_i32 s71, s70, 31
	s_lshl_b64 s[70:71], s[70:71], 11
	s_cmpk_gt_i32 s86, 0xff
	v_pk_mul_f32 v[10:11], v[10:11], v[14:15] op_sel_hi:[1,0]
	v_pk_mul_f32 v[12:13], v[12:13], v[14:15] op_sel_hi:[1,0]
	v_pk_fma_f32 v[10:11], v[2:3], v[10:11], v[6:7]
	v_pk_fma_f32 v[12:13], v[4:5], v[12:13], v[8:9]
	v_mul_f32_e32 v14, 0xbfb8aa3b, v10
	v_exp_f32_e32 v14, v14
	s_nop 0
	v_add_f32_e32 v14, 1.0, v14
	v_rcp_f32_e32 v14, v14
	s_nop 0
	v_mul_f32_e32 v10, v10, v14
	v_mul_f32_e32 v14, 0xbfb8aa3b, v11
	v_exp_f32_e32 v14, v14
	s_nop 0
	v_add_f32_e32 v14, 1.0, v14
	v_rcp_f32_e32 v14, v14
	s_nop 0
	v_mul_f32_e32 v11, v11, v14
	v_cvt_pk_bf16_f32 v10, v10, v11
	v_mul_f32_e32 v11, 0xbfb8aa3b, v12
	v_exp_f32_e32 v11, v11
	s_nop 0
	v_add_f32_e32 v11, 1.0, v11
	v_rcp_f32_e32 v11, v11
	s_nop 0
	v_mul_f32_e32 v11, v12, v11
	v_mul_f32_e32 v12, 0xbfb8aa3b, v13
	v_exp_f32_e32 v12, v12
	s_nop 0
	v_add_f32_e32 v12, 1.0, v12
	v_rcp_f32_e32 v12, v12
	s_nop 0
	v_mul_f32_e32 v12, v13, v12
	v_cvt_pk_bf16_f32 v11, v11, v12
	v_lshl_add_u64 v[12:13], v[60:61], 0, s[70:71]
	global_store_dwordx2 v[12:13], v[10:11], off offset:1536
	s_barrier
	s_cbranch_scc0 .LBB0_248
